# code placement: every 8-byte instruction of the four hand-written GEMM K-loop regions padded onto an 8-byte boundary
# speedup vs baseline: 1.0048x; 1.0048x over previous
.LBB0_111:
	v_mov_b64_e32 v[0:1], v[132:133]
	v_mov_b64_e32 v[2:3], v[132:133]
	v_mov_b32_e32 v6, v154
	s_lshl_b32 s46, s13, 8
	s_mov_b64 s[4:5], 0x11a00000
	v_ashrrev_i32_e32 v9, 3, v6
	v_add_u32_e32 v4, s46, v9
	v_lshl_add_u64 v[0:1], v[0:1], 0, s[4:5]
	v_lshrrev_b32_e32 v8, 4, v6
	v_ashrrev_i32_e32 v5, 31, v4
	v_xor_b32_e32 v10, v8, v6
	v_lshlrev_b64 v[4:5], 11, v[4:5]
	v_lshl_add_u64 v[0:1], v[0:1], 0, v[4:5]
	v_lshlrev_b32_e32 v4, 4, v10
	s_lshl_b32 s6, s39, 8
	v_and_b32_e32 v134, 0x70, v4
	v_lshl_add_u64 v[128:129], v[0:1], 0, v[134:135]
	v_add_u32_e32 v0, s6, v9
	v_ashrrev_i32_e32 v1, 31, v0
	v_lshlrev_b64 v[0:1], 11, v[0:1]
	v_ashrrev_i32_e32 v7, 6, v6
	v_lshl_add_u64 v[0:1], v[2:3], 0, v[0:1]
	v_lshl_add_u64 v[130:131], v[0:1], 0, v[134:135]
	v_ashrrev_i32_e32 v0, 1, v6
	v_and_b32_e32 v134, 0xffffffc0, v0
	v_lshlrev_b32_e32 v0, 7, v7
	v_and_b32_e32 v144, 0x80, v0
	v_lshlrev_b32_e32 v0, 10, v7
	v_add_u32_e32 v145, 0, v0
	v_add_u32_e32 v146, s79, v0
	v_readfirstlane_b32 s4, v145
	s_mov_b32 m0, s4
	v_readfirstlane_b32 s4, v146
	v_add_u32_e32 v147, 0x2000, v145
	global_load_lds_dwordx4 v[128:129], off
	s_mov_b32 m0, s4
	s_mov_b64 s[16:17], 0x20000
	v_readfirstlane_b32 s4, v147
	v_add_u32_e32 v148, 0x2000, v146
	global_load_lds_dwordx4 v[130:131], off
	v_lshl_add_u64 v[0:1], v[128:129], 0, s[16:17]
	s_mov_b32 m0, s4
	v_readfirstlane_b32 s4, v148
	v_add_u32_e32 v149, 0x4000, v145
	global_load_lds_dwordx4 v[0:1], off
	v_lshl_add_u64 v[0:1], v[130:131], 0, s[16:17]
	s_mov_b32 m0, s4
	s_mov_b64 s[16:17], 0x40000
	v_readfirstlane_b32 s4, v149
	v_add_u32_e32 v150, 0x4000, v146
	global_load_lds_dwordx4 v[0:1], off
	v_lshl_add_u64 v[0:1], v[128:129], 0, s[16:17]
	s_mov_b32 m0, s4
	v_readfirstlane_b32 s4, v150
	v_add_u32_e32 v151, 0x6000, v145
	global_load_lds_dwordx4 v[0:1], off
	v_lshl_add_u64 v[0:1], v[130:131], 0, s[16:17]
	s_mov_b32 m0, s4
	s_mov_b64 s[16:17], 0x60000
	v_readfirstlane_b32 s4, v151
	v_add_u32_e32 v152, 0x6000, v146
	global_load_lds_dwordx4 v[0:1], off
	v_lshl_add_u64 v[0:1], v[128:129], 0, s[16:17]
	s_mov_b32 m0, s4
	v_readfirstlane_b32 s4, v152
	global_load_lds_dwordx4 v[0:1], off
	v_lshl_add_u64 v[0:1], v[130:131], 0, s[16:17]
	s_mov_b32 m0, s4
	v_and_b32_e32 v143, 15, v6
	global_load_lds_dwordx4 v[0:1], off
	s_mov_b64 s[100:101], 0x80
	v_lshl_add_u64 v[240:241], v[128:129], 0, s[100:101]
	s_mov_b64 s[100:101], 0x20080
	v_lshl_add_u64 v[242:243], v[128:129], 0, s[100:101]
	s_mov_b64 s[100:101], 0x40080
	v_lshl_add_u64 v[244:245], v[128:129], 0, s[100:101]
	s_mov_b64 s[100:101], 0x60080
	v_lshl_add_u64 v[246:247], v[128:129], 0, s[100:101]
	s_mov_b64 s[100:101], 0x80
	v_lshl_add_u64 v[138:139], v[130:131], 0, s[100:101]
	s_mov_b64 s[100:101], 0x20080
	v_lshl_add_u64 v[140:141], v[130:131], 0, s[100:101]
	s_mov_b64 s[100:101], 0x40080
	v_lshl_add_u64 v[250:251], v[130:131], 0, s[100:101]
	s_mov_b64 s[100:101], 0x60080
	v_lshl_add_u64 v[252:253], v[130:131], 0, s[100:101]
	v_readfirstlane_b32 s100, v145
	v_readfirstlane_b32 s101, v146
	s_nop 3
	s_add_u32 m0, s100, 0x8000
	s_nop 0
	global_load_lds_dwordx4 v[240:241], off
	v_lshl_add_u64 v[240:241], v[240:241], 0, s[34:35]
	s_add_u32 m0, s100, 0xa000
	s_nop 0
	global_load_lds_dwordx4 v[242:243], off
	v_lshl_add_u64 v[242:243], v[242:243], 0, s[34:35]
	s_add_u32 m0, s100, 0xc000
	s_nop 0
	global_load_lds_dwordx4 v[244:245], off
	v_lshl_add_u64 v[244:245], v[244:245], 0, s[34:35]
	s_add_u32 m0, s100, 0xe000
	s_nop 0
	global_load_lds_dwordx4 v[246:247], off
	v_lshl_add_u64 v[246:247], v[246:247], 0, s[34:35]
	s_add_u32 m0, s101, 0x8000
	s_nop 0
	global_load_lds_dwordx4 v[138:139], off
	v_lshl_add_u64 v[138:139], v[138:139], 0, s[34:35]
	s_add_u32 m0, s101, 0xa000
	s_nop 0
	global_load_lds_dwordx4 v[140:141], off
	v_lshl_add_u64 v[140:141], v[140:141], 0, s[34:35]
	s_add_u32 m0, s101, 0xc000
	s_nop 0
	global_load_lds_dwordx4 v[250:251], off
	v_lshl_add_u64 v[250:251], v[250:251], 0, s[34:35]
	s_add_u32 m0, s101, 0xe000
	s_nop 0
	global_load_lds_dwordx4 v[252:253], off
	v_lshl_add_u64 v[252:253], v[252:253], 0, s[34:35]
	s_add_u32 m0, s100, 0x20000
	s_nop 0
	global_load_lds_dwordx4 v[240:241], off
	v_lshl_add_u64 v[240:241], v[240:241], 0, s[34:35]
	s_add_u32 m0, s100, 0x22000
	s_nop 0
	global_load_lds_dwordx4 v[242:243], off
	v_lshl_add_u64 v[242:243], v[242:243], 0, s[34:35]
	s_add_u32 m0, s100, 0x24000
	s_nop 0
	global_load_lds_dwordx4 v[244:245], off
	v_lshl_add_u64 v[244:245], v[244:245], 0, s[34:35]
	s_add_u32 m0, s100, 0x26000
	s_nop 0
	global_load_lds_dwordx4 v[246:247], off
	v_lshl_add_u64 v[246:247], v[246:247], 0, s[34:35]
	v_bfe_u32 v142, v6, 4, 2
	v_bfe_u32 v0, v6, 1, 3
	v_or_b32_e32 v2, v134, v143
	v_or_b32_e32 v3, v144, v143
	v_bitop3_b32 v1, v8, v0, 3 bitop3:0x6c
	v_bitop3_b32 v0, v142, v0, 4 bitop3:0x36
	v_lshl_add_u32 v153, v2, 7, 0
	v_lshl_add_u32 v169, v3, 7, s79
	v_lshlrev_b32_e32 v170, 4, v1
	v_lshlrev_b32_e32 v171, 4, v0
	s_mov_b64 s[4:5], 0
	s_waitcnt vmcnt(12) lgkmcnt(0)
	s_barrier
	s_branch .LBB0_113
	s_nop 0
.LBB0_113:
	v_add_u32_e32 v172, v153, v170
	v_add_u32_e32 v173, v153, v171
	v_add_u32_e32 v174, v169, v170
	v_add_u32_e32 v175, v169, v171
	v_add_u32_e32 v254, 0x20000, v172
	v_add_u32_e32 v255, 0x20000, v173
	s_nop 1
	s_nop 0
	ds_read_b128 v[176:179], v172 offset:0
	ds_read_b128 v[180:183], v172 offset:2048
	ds_read_b128 v[184:187], v172 offset:4096
	ds_read_b128 v[188:191], v172 offset:6144
	ds_read_b128 v[208:211], v174 offset:0
	ds_read_b128 v[212:215], v174 offset:2048
	ds_read_b128 v[216:219], v174 offset:4096
	ds_read_b128 v[220:223], v174 offset:6144
	s_waitcnt lgkmcnt(0)
	s_nop 0
	v_mfma_f32_16x16x32_bf16 v[120:123], v[208:211], v[176:179], 0
	ds_read_b128 v[224:227], v174 offset:8192
	v_mfma_f32_16x16x32_bf16 v[112:115], v[212:215], v[176:179], 0
	ds_read_b128 v[228:231], v174 offset:10240
	v_mfma_f32_16x16x32_bf16 v[124:127], v[216:219], v[176:179], 0
	ds_read_b128 v[232:235], v174 offset:12288
	v_mfma_f32_16x16x32_bf16 v[116:119], v[220:223], v[176:179], 0
	ds_read_b128 v[236:239], v174 offset:14336
	v_mfma_f32_16x16x32_bf16 v[88:91], v[208:211], v[180:183], 0
	v_mfma_f32_16x16x32_bf16 v[80:83], v[212:215], v[180:183], 0
	v_mfma_f32_16x16x32_bf16 v[92:95], v[216:219], v[180:183], 0
	v_mfma_f32_16x16x32_bf16 v[84:87], v[220:223], v[180:183], 0
	v_mfma_f32_16x16x32_bf16 v[56:59], v[208:211], v[184:187], 0
	v_mfma_f32_16x16x32_bf16 v[48:51], v[212:215], v[184:187], 0
	v_mfma_f32_16x16x32_bf16 v[60:63], v[216:219], v[184:187], 0
	v_mfma_f32_16x16x32_bf16 v[52:55], v[220:223], v[184:187], 0
	v_mfma_f32_16x16x32_bf16 v[24:27], v[208:211], v[188:191], 0
	v_mfma_f32_16x16x32_bf16 v[16:19], v[212:215], v[188:191], 0
	v_mfma_f32_16x16x32_bf16 v[28:31], v[216:219], v[188:191], 0
	v_mfma_f32_16x16x32_bf16 v[20:23], v[220:223], v[188:191], 0
	s_waitcnt lgkmcnt(0)
	s_nop 0
	v_mfma_f32_16x16x32_bf16 v[104:107], v[224:227], v[176:179], 0
	ds_read_b128 v[192:195], v173 offset:0
	v_mfma_f32_16x16x32_bf16 v[96:99], v[228:231], v[176:179], 0
	ds_read_b128 v[196:199], v173 offset:2048
	v_mfma_f32_16x16x32_bf16 v[108:111], v[232:235], v[176:179], 0
	ds_read_b128 v[200:203], v173 offset:4096
	v_mfma_f32_16x16x32_bf16 v[100:103], v[236:239], v[176:179], 0
	ds_read_b128 v[204:207], v173 offset:6144
	v_mfma_f32_16x16x32_bf16 v[72:75], v[224:227], v[180:183], 0
	ds_read_b128 v[208:211], v175 offset:0
	v_mfma_f32_16x16x32_bf16 v[64:67], v[228:231], v[180:183], 0
	ds_read_b128 v[212:215], v175 offset:2048
	v_mfma_f32_16x16x32_bf16 v[76:79], v[232:235], v[180:183], 0
	ds_read_b128 v[216:219], v175 offset:4096
	v_mfma_f32_16x16x32_bf16 v[68:71], v[236:239], v[180:183], 0
	ds_read_b128 v[220:223], v175 offset:6144
	v_mfma_f32_16x16x32_bf16 v[40:43], v[224:227], v[184:187], 0
	v_mfma_f32_16x16x32_bf16 v[32:35], v[228:231], v[184:187], 0
	v_mfma_f32_16x16x32_bf16 v[44:47], v[232:235], v[184:187], 0
	v_mfma_f32_16x16x32_bf16 v[36:39], v[236:239], v[184:187], 0
	v_mfma_f32_16x16x32_bf16 v[8:11], v[224:227], v[188:191], 0
	v_mfma_f32_16x16x32_bf16 v[0:3], v[228:231], v[188:191], 0
	v_mfma_f32_16x16x32_bf16 v[12:15], v[232:235], v[188:191], 0
	v_mfma_f32_16x16x32_bf16 v[4:7], v[236:239], v[188:191], 0
	s_waitcnt lgkmcnt(0)
	s_nop 0
	v_mfma_f32_16x16x32_bf16 v[120:123], v[208:211], v[192:195], v[120:123]
	ds_read_b128 v[224:227], v175 offset:8192
	v_mfma_f32_16x16x32_bf16 v[112:115], v[212:215], v[192:195], v[112:115]
	ds_read_b128 v[228:231], v175 offset:10240
	v_mfma_f32_16x16x32_bf16 v[124:127], v[216:219], v[192:195], v[124:127]
	ds_read_b128 v[232:235], v175 offset:12288
	v_mfma_f32_16x16x32_bf16 v[116:119], v[220:223], v[192:195], v[116:119]
	ds_read_b128 v[236:239], v175 offset:14336
	v_mfma_f32_16x16x32_bf16 v[88:91], v[208:211], v[196:199], v[88:91]
	v_mfma_f32_16x16x32_bf16 v[80:83], v[212:215], v[196:199], v[80:83]
	v_mfma_f32_16x16x32_bf16 v[92:95], v[216:219], v[196:199], v[92:95]
	v_mfma_f32_16x16x32_bf16 v[84:87], v[220:223], v[196:199], v[84:87]
	v_mfma_f32_16x16x32_bf16 v[56:59], v[208:211], v[200:203], v[56:59]
	v_mfma_f32_16x16x32_bf16 v[48:51], v[212:215], v[200:203], v[48:51]
	v_mfma_f32_16x16x32_bf16 v[60:63], v[216:219], v[200:203], v[60:63]
	v_mfma_f32_16x16x32_bf16 v[52:55], v[220:223], v[200:203], v[52:55]
	v_mfma_f32_16x16x32_bf16 v[24:27], v[208:211], v[204:207], v[24:27]
	v_mfma_f32_16x16x32_bf16 v[16:19], v[212:215], v[204:207], v[16:19]
	v_mfma_f32_16x16x32_bf16 v[28:31], v[216:219], v[204:207], v[28:31]
	v_mfma_f32_16x16x32_bf16 v[20:23], v[220:223], v[204:207], v[20:23]
	s_waitcnt lgkmcnt(0)
	s_waitcnt vmcnt(4)
	s_barrier
	s_mov_b32 s7, 2
.Lgemm_p2_loop:
	v_mfma_f32_16x16x32_bf16 v[104:107], v[224:227], v[192:195], v[104:107]
	ds_read_b128 v[176:179], v172 offset:32768
	s_mov_b32 m0, s101
	s_nop 0
	v_mfma_f32_16x16x32_bf16 v[96:99], v[228:231], v[192:195], v[96:99]
	ds_read_b128 v[180:183], v172 offset:34816
	global_load_lds_dwordx4 v[138:139], off
	v_lshl_add_u64 v[138:139], v[138:139], 0, s[34:35]
	v_mfma_f32_16x16x32_bf16 v[108:111], v[232:235], v[192:195], v[108:111]
	ds_read_b128 v[184:187], v172 offset:36864
	s_add_u32 m0, s101, 0x2000
	v_mfma_f32_16x16x32_bf16 v[100:103], v[236:239], v[192:195], v[100:103]
	ds_read_b128 v[188:191], v172 offset:38912
	global_load_lds_dwordx4 v[140:141], off
	v_lshl_add_u64 v[140:141], v[140:141], 0, s[34:35]
	v_mfma_f32_16x16x32_bf16 v[72:75], v[224:227], v[196:199], v[72:75]
	ds_read_b128 v[208:211], v174 offset:32768
	s_add_u32 m0, s101, 0x4000
	v_mfma_f32_16x16x32_bf16 v[64:67], v[228:231], v[196:199], v[64:67]
	ds_read_b128 v[212:215], v174 offset:34816
	global_load_lds_dwordx4 v[250:251], off
	v_lshl_add_u64 v[250:251], v[250:251], 0, s[34:35]
	v_mfma_f32_16x16x32_bf16 v[76:79], v[232:235], v[196:199], v[76:79]
	ds_read_b128 v[216:219], v174 offset:36864
	s_add_u32 m0, s101, 0x6000
	v_mfma_f32_16x16x32_bf16 v[68:71], v[236:239], v[196:199], v[68:71]
	ds_read_b128 v[220:223], v174 offset:38912
	global_load_lds_dwordx4 v[252:253], off
	v_lshl_add_u64 v[252:253], v[252:253], 0, s[34:35]
	v_mfma_f32_16x16x32_bf16 v[40:43], v[224:227], v[200:203], v[40:43]
	v_mfma_f32_16x16x32_bf16 v[32:35], v[228:231], v[200:203], v[32:35]
	v_mfma_f32_16x16x32_bf16 v[44:47], v[232:235], v[200:203], v[44:47]
	v_mfma_f32_16x16x32_bf16 v[36:39], v[236:239], v[200:203], v[36:39]
	v_mfma_f32_16x16x32_bf16 v[8:11], v[224:227], v[204:207], v[8:11]
	v_mfma_f32_16x16x32_bf16 v[0:3], v[228:231], v[204:207], v[0:3]
	v_mfma_f32_16x16x32_bf16 v[12:15], v[232:235], v[204:207], v[12:15]
	v_mfma_f32_16x16x32_bf16 v[4:7], v[236:239], v[204:207], v[4:7]
	s_waitcnt lgkmcnt(0)
	s_nop 0
	v_mfma_f32_16x16x32_bf16 v[120:123], v[208:211], v[176:179], v[120:123]
	ds_read_b128 v[224:227], v174 offset:40960
	v_mfma_f32_16x16x32_bf16 v[112:115], v[212:215], v[176:179], v[112:115]
	ds_read_b128 v[228:231], v174 offset:43008
	v_mfma_f32_16x16x32_bf16 v[124:127], v[216:219], v[176:179], v[124:127]
	ds_read_b128 v[232:235], v174 offset:45056
	v_mfma_f32_16x16x32_bf16 v[116:119], v[220:223], v[176:179], v[116:119]
	ds_read_b128 v[236:239], v174 offset:47104
	v_mfma_f32_16x16x32_bf16 v[88:91], v[208:211], v[180:183], v[88:91]
	s_mov_b32 m0, s100
	s_nop 0
	v_mfma_f32_16x16x32_bf16 v[80:83], v[212:215], v[180:183], v[80:83]
	global_load_lds_dwordx4 v[240:241], off
	v_lshl_add_u64 v[240:241], v[240:241], 0, s[34:35]
	v_mfma_f32_16x16x32_bf16 v[92:95], v[216:219], v[180:183], v[92:95]
	s_add_u32 m0, s100, 0x2000
	v_mfma_f32_16x16x32_bf16 v[84:87], v[220:223], v[180:183], v[84:87]
	global_load_lds_dwordx4 v[242:243], off
	v_lshl_add_u64 v[242:243], v[242:243], 0, s[34:35]
	v_mfma_f32_16x16x32_bf16 v[56:59], v[208:211], v[184:187], v[56:59]
	s_add_u32 m0, s100, 0x4000
	v_mfma_f32_16x16x32_bf16 v[48:51], v[212:215], v[184:187], v[48:51]
	global_load_lds_dwordx4 v[244:245], off
	v_lshl_add_u64 v[244:245], v[244:245], 0, s[34:35]
	v_mfma_f32_16x16x32_bf16 v[60:63], v[216:219], v[184:187], v[60:63]
	s_add_u32 m0, s100, 0x6000
	v_mfma_f32_16x16x32_bf16 v[52:55], v[220:223], v[184:187], v[52:55]
	global_load_lds_dwordx4 v[246:247], off
	v_lshl_add_u64 v[246:247], v[246:247], 0, s[34:35]
	v_mfma_f32_16x16x32_bf16 v[24:27], v[208:211], v[188:191], v[24:27]
	v_mfma_f32_16x16x32_bf16 v[16:19], v[212:215], v[188:191], v[16:19]
	v_mfma_f32_16x16x32_bf16 v[28:31], v[216:219], v[188:191], v[28:31]
	v_mfma_f32_16x16x32_bf16 v[20:23], v[220:223], v[188:191], v[20:23]
	s_waitcnt lgkmcnt(0)
	s_nop 0
	v_mfma_f32_16x16x32_bf16 v[104:107], v[224:227], v[176:179], v[104:107]
	ds_read_b128 v[192:195], v173 offset:32768
	v_mfma_f32_16x16x32_bf16 v[96:99], v[228:231], v[176:179], v[96:99]
	ds_read_b128 v[196:199], v173 offset:34816
	v_mfma_f32_16x16x32_bf16 v[108:111], v[232:235], v[176:179], v[108:111]
	ds_read_b128 v[200:203], v173 offset:36864
	v_mfma_f32_16x16x32_bf16 v[100:103], v[236:239], v[176:179], v[100:103]
	ds_read_b128 v[204:207], v173 offset:38912
	v_mfma_f32_16x16x32_bf16 v[72:75], v[224:227], v[180:183], v[72:75]
	ds_read_b128 v[208:211], v175 offset:32768
	v_mfma_f32_16x16x32_bf16 v[64:67], v[228:231], v[180:183], v[64:67]
	ds_read_b128 v[212:215], v175 offset:34816
	v_mfma_f32_16x16x32_bf16 v[76:79], v[232:235], v[180:183], v[76:79]
	ds_read_b128 v[216:219], v175 offset:36864
	v_mfma_f32_16x16x32_bf16 v[68:71], v[236:239], v[180:183], v[68:71]
	ds_read_b128 v[220:223], v175 offset:38912
	v_mfma_f32_16x16x32_bf16 v[40:43], v[224:227], v[184:187], v[40:43]
	v_mfma_f32_16x16x32_bf16 v[32:35], v[228:231], v[184:187], v[32:35]
	v_mfma_f32_16x16x32_bf16 v[44:47], v[232:235], v[184:187], v[44:47]
	v_mfma_f32_16x16x32_bf16 v[36:39], v[236:239], v[184:187], v[36:39]
	v_mfma_f32_16x16x32_bf16 v[8:11], v[224:227], v[188:191], v[8:11]
	v_mfma_f32_16x16x32_bf16 v[0:3], v[228:231], v[188:191], v[0:3]
	v_mfma_f32_16x16x32_bf16 v[12:15], v[232:235], v[188:191], v[12:15]
	v_mfma_f32_16x16x32_bf16 v[4:7], v[236:239], v[188:191], v[4:7]
	s_waitcnt lgkmcnt(0)
	s_nop 0
	v_mfma_f32_16x16x32_bf16 v[120:123], v[208:211], v[192:195], v[120:123]
	ds_read_b128 v[224:227], v175 offset:40960
	v_mfma_f32_16x16x32_bf16 v[112:115], v[212:215], v[192:195], v[112:115]
	ds_read_b128 v[228:231], v175 offset:43008
	v_mfma_f32_16x16x32_bf16 v[124:127], v[216:219], v[192:195], v[124:127]
	ds_read_b128 v[232:235], v175 offset:45056
	v_mfma_f32_16x16x32_bf16 v[116:119], v[220:223], v[192:195], v[116:119]
	ds_read_b128 v[236:239], v175 offset:47104
	v_mfma_f32_16x16x32_bf16 v[88:91], v[208:211], v[196:199], v[88:91]
	v_mfma_f32_16x16x32_bf16 v[80:83], v[212:215], v[196:199], v[80:83]
	v_mfma_f32_16x16x32_bf16 v[92:95], v[216:219], v[196:199], v[92:95]
	v_mfma_f32_16x16x32_bf16 v[84:87], v[220:223], v[196:199], v[84:87]
	v_mfma_f32_16x16x32_bf16 v[56:59], v[208:211], v[200:203], v[56:59]
	v_mfma_f32_16x16x32_bf16 v[48:51], v[212:215], v[200:203], v[48:51]
	v_mfma_f32_16x16x32_bf16 v[60:63], v[216:219], v[200:203], v[60:63]
	v_mfma_f32_16x16x32_bf16 v[52:55], v[220:223], v[200:203], v[52:55]
	v_mfma_f32_16x16x32_bf16 v[24:27], v[208:211], v[204:207], v[24:27]
	v_mfma_f32_16x16x32_bf16 v[16:19], v[212:215], v[204:207], v[16:19]
	v_mfma_f32_16x16x32_bf16 v[28:31], v[216:219], v[204:207], v[28:31]
	v_mfma_f32_16x16x32_bf16 v[20:23], v[220:223], v[204:207], v[20:23]
	s_waitcnt lgkmcnt(0)
	s_waitcnt vmcnt(4)
	s_barrier
	s_nop 0
	v_mfma_f32_16x16x32_bf16 v[104:107], v[224:227], v[192:195], v[104:107]
	ds_read_b128 v[176:179], v254 offset:0
	s_add_u32 m0, s101, 0x8000
	v_mfma_f32_16x16x32_bf16 v[96:99], v[228:231], v[192:195], v[96:99]
	ds_read_b128 v[180:183], v254 offset:2048
	global_load_lds_dwordx4 v[138:139], off
	v_lshl_add_u64 v[138:139], v[138:139], 0, s[34:35]
	v_mfma_f32_16x16x32_bf16 v[108:111], v[232:235], v[192:195], v[108:111]
	ds_read_b128 v[184:187], v254 offset:4096
	s_add_u32 m0, s101, 0xa000
	v_mfma_f32_16x16x32_bf16 v[100:103], v[236:239], v[192:195], v[100:103]
	ds_read_b128 v[188:191], v254 offset:6144
	global_load_lds_dwordx4 v[140:141], off
	v_lshl_add_u64 v[140:141], v[140:141], 0, s[34:35]
	v_mfma_f32_16x16x32_bf16 v[72:75], v[224:227], v[196:199], v[72:75]
	ds_read_b128 v[208:211], v174 offset:0
	s_add_u32 m0, s101, 0xc000
	v_mfma_f32_16x16x32_bf16 v[64:67], v[228:231], v[196:199], v[64:67]
	ds_read_b128 v[212:215], v174 offset:2048
	global_load_lds_dwordx4 v[250:251], off
	v_lshl_add_u64 v[250:251], v[250:251], 0, s[34:35]
	v_mfma_f32_16x16x32_bf16 v[76:79], v[232:235], v[196:199], v[76:79]
	ds_read_b128 v[216:219], v174 offset:4096
	s_add_u32 m0, s101, 0xe000
	v_mfma_f32_16x16x32_bf16 v[68:71], v[236:239], v[196:199], v[68:71]
	ds_read_b128 v[220:223], v174 offset:6144
	global_load_lds_dwordx4 v[252:253], off
	v_lshl_add_u64 v[252:253], v[252:253], 0, s[34:35]
	v_mfma_f32_16x16x32_bf16 v[40:43], v[224:227], v[200:203], v[40:43]
	v_mfma_f32_16x16x32_bf16 v[32:35], v[228:231], v[200:203], v[32:35]
	v_mfma_f32_16x16x32_bf16 v[44:47], v[232:235], v[200:203], v[44:47]
	v_mfma_f32_16x16x32_bf16 v[36:39], v[236:239], v[200:203], v[36:39]
	v_mfma_f32_16x16x32_bf16 v[8:11], v[224:227], v[204:207], v[8:11]
	v_mfma_f32_16x16x32_bf16 v[0:3], v[228:231], v[204:207], v[0:3]
	v_mfma_f32_16x16x32_bf16 v[12:15], v[232:235], v[204:207], v[12:15]
	v_mfma_f32_16x16x32_bf16 v[4:7], v[236:239], v[204:207], v[4:7]
	s_waitcnt lgkmcnt(0)
	s_nop 0
	v_mfma_f32_16x16x32_bf16 v[120:123], v[208:211], v[176:179], v[120:123]
	ds_read_b128 v[224:227], v174 offset:8192
	v_mfma_f32_16x16x32_bf16 v[112:115], v[212:215], v[176:179], v[112:115]
	ds_read_b128 v[228:231], v174 offset:10240
	v_mfma_f32_16x16x32_bf16 v[124:127], v[216:219], v[176:179], v[124:127]
	ds_read_b128 v[232:235], v174 offset:12288
	v_mfma_f32_16x16x32_bf16 v[116:119], v[220:223], v[176:179], v[116:119]
	ds_read_b128 v[236:239], v174 offset:14336
	v_mfma_f32_16x16x32_bf16 v[88:91], v[208:211], v[180:183], v[88:91]
	s_add_u32 m0, s100, 0x8000
	v_mfma_f32_16x16x32_bf16 v[80:83], v[212:215], v[180:183], v[80:83]
	global_load_lds_dwordx4 v[240:241], off
	v_lshl_add_u64 v[240:241], v[240:241], 0, s[34:35]
	v_mfma_f32_16x16x32_bf16 v[92:95], v[216:219], v[180:183], v[92:95]
	s_add_u32 m0, s100, 0xa000
	v_mfma_f32_16x16x32_bf16 v[84:87], v[220:223], v[180:183], v[84:87]
	global_load_lds_dwordx4 v[242:243], off
	v_lshl_add_u64 v[242:243], v[242:243], 0, s[34:35]
	v_mfma_f32_16x16x32_bf16 v[56:59], v[208:211], v[184:187], v[56:59]
	s_add_u32 m0, s100, 0xc000
	v_mfma_f32_16x16x32_bf16 v[48:51], v[212:215], v[184:187], v[48:51]
	global_load_lds_dwordx4 v[244:245], off
	v_lshl_add_u64 v[244:245], v[244:245], 0, s[34:35]
	v_mfma_f32_16x16x32_bf16 v[60:63], v[216:219], v[184:187], v[60:63]
	s_add_u32 m0, s100, 0xe000
	v_mfma_f32_16x16x32_bf16 v[52:55], v[220:223], v[184:187], v[52:55]
	global_load_lds_dwordx4 v[246:247], off
	v_lshl_add_u64 v[246:247], v[246:247], 0, s[34:35]
	v_mfma_f32_16x16x32_bf16 v[24:27], v[208:211], v[188:191], v[24:27]
	v_mfma_f32_16x16x32_bf16 v[16:19], v[212:215], v[188:191], v[16:19]
	v_mfma_f32_16x16x32_bf16 v[28:31], v[216:219], v[188:191], v[28:31]
	v_mfma_f32_16x16x32_bf16 v[20:23], v[220:223], v[188:191], v[20:23]
	s_waitcnt lgkmcnt(0)
	s_nop 0
	v_mfma_f32_16x16x32_bf16 v[104:107], v[224:227], v[176:179], v[104:107]
	ds_read_b128 v[192:195], v255 offset:0
	v_mfma_f32_16x16x32_bf16 v[96:99], v[228:231], v[176:179], v[96:99]
	ds_read_b128 v[196:199], v255 offset:2048
	v_mfma_f32_16x16x32_bf16 v[108:111], v[232:235], v[176:179], v[108:111]
	ds_read_b128 v[200:203], v255 offset:4096
	v_mfma_f32_16x16x32_bf16 v[100:103], v[236:239], v[176:179], v[100:103]
	ds_read_b128 v[204:207], v255 offset:6144
	v_mfma_f32_16x16x32_bf16 v[72:75], v[224:227], v[180:183], v[72:75]
	ds_read_b128 v[208:211], v175 offset:0
	v_mfma_f32_16x16x32_bf16 v[64:67], v[228:231], v[180:183], v[64:67]
	ds_read_b128 v[212:215], v175 offset:2048
	v_mfma_f32_16x16x32_bf16 v[76:79], v[232:235], v[180:183], v[76:79]
	ds_read_b128 v[216:219], v175 offset:4096
	v_mfma_f32_16x16x32_bf16 v[68:71], v[236:239], v[180:183], v[68:71]
	ds_read_b128 v[220:223], v175 offset:6144
	v_mfma_f32_16x16x32_bf16 v[40:43], v[224:227], v[184:187], v[40:43]
	v_mfma_f32_16x16x32_bf16 v[32:35], v[228:231], v[184:187], v[32:35]
	v_mfma_f32_16x16x32_bf16 v[44:47], v[232:235], v[184:187], v[44:47]
	v_mfma_f32_16x16x32_bf16 v[36:39], v[236:239], v[184:187], v[36:39]
	v_mfma_f32_16x16x32_bf16 v[8:11], v[224:227], v[188:191], v[8:11]
	v_mfma_f32_16x16x32_bf16 v[0:3], v[228:231], v[188:191], v[0:3]
	v_mfma_f32_16x16x32_bf16 v[12:15], v[232:235], v[188:191], v[12:15]
	v_mfma_f32_16x16x32_bf16 v[4:7], v[236:239], v[188:191], v[4:7]
	s_waitcnt lgkmcnt(0)
	s_nop 0
	v_mfma_f32_16x16x32_bf16 v[120:123], v[208:211], v[192:195], v[120:123]
	ds_read_b128 v[224:227], v175 offset:8192
	v_mfma_f32_16x16x32_bf16 v[112:115], v[212:215], v[192:195], v[112:115]
	ds_read_b128 v[228:231], v175 offset:10240
	v_mfma_f32_16x16x32_bf16 v[124:127], v[216:219], v[192:195], v[124:127]
	ds_read_b128 v[232:235], v175 offset:12288
	v_mfma_f32_16x16x32_bf16 v[116:119], v[220:223], v[192:195], v[116:119]
	ds_read_b128 v[236:239], v175 offset:14336
	v_mfma_f32_16x16x32_bf16 v[88:91], v[208:211], v[196:199], v[88:91]
	v_mfma_f32_16x16x32_bf16 v[80:83], v[212:215], v[196:199], v[80:83]
	v_mfma_f32_16x16x32_bf16 v[92:95], v[216:219], v[196:199], v[92:95]
	v_mfma_f32_16x16x32_bf16 v[84:87], v[220:223], v[196:199], v[84:87]
	v_mfma_f32_16x16x32_bf16 v[56:59], v[208:211], v[200:203], v[56:59]
	v_mfma_f32_16x16x32_bf16 v[48:51], v[212:215], v[200:203], v[48:51]
	v_mfma_f32_16x16x32_bf16 v[60:63], v[216:219], v[200:203], v[60:63]
	v_mfma_f32_16x16x32_bf16 v[52:55], v[220:223], v[200:203], v[52:55]
	v_mfma_f32_16x16x32_bf16 v[24:27], v[208:211], v[204:207], v[24:27]
	v_mfma_f32_16x16x32_bf16 v[16:19], v[212:215], v[204:207], v[16:19]
	v_mfma_f32_16x16x32_bf16 v[28:31], v[216:219], v[204:207], v[28:31]
	v_mfma_f32_16x16x32_bf16 v[20:23], v[220:223], v[204:207], v[20:23]
	s_waitcnt lgkmcnt(0)
	s_waitcnt vmcnt(4)
	s_barrier
	s_nop 0
	v_mfma_f32_16x16x32_bf16 v[104:107], v[224:227], v[192:195], v[104:107]
	ds_read_b128 v[176:179], v172 offset:0
	s_mov_b32 m0, s101
	s_nop 0
	v_mfma_f32_16x16x32_bf16 v[96:99], v[228:231], v[192:195], v[96:99]
	ds_read_b128 v[180:183], v172 offset:2048
	global_load_lds_dwordx4 v[138:139], off
	v_lshl_add_u64 v[138:139], v[138:139], 0, s[34:35]
	v_mfma_f32_16x16x32_bf16 v[108:111], v[232:235], v[192:195], v[108:111]
	ds_read_b128 v[184:187], v172 offset:4096
	s_add_u32 m0, s101, 0x2000
	v_mfma_f32_16x16x32_bf16 v[100:103], v[236:239], v[192:195], v[100:103]
	ds_read_b128 v[188:191], v172 offset:6144
	global_load_lds_dwordx4 v[140:141], off
	v_lshl_add_u64 v[140:141], v[140:141], 0, s[34:35]
	v_mfma_f32_16x16x32_bf16 v[72:75], v[224:227], v[196:199], v[72:75]
	ds_read_b128 v[208:211], v174 offset:32768
	s_add_u32 m0, s101, 0x4000
	v_mfma_f32_16x16x32_bf16 v[64:67], v[228:231], v[196:199], v[64:67]
	ds_read_b128 v[212:215], v174 offset:34816
	global_load_lds_dwordx4 v[250:251], off
	v_lshl_add_u64 v[250:251], v[250:251], 0, s[34:35]
	v_mfma_f32_16x16x32_bf16 v[76:79], v[232:235], v[196:199], v[76:79]
	ds_read_b128 v[216:219], v174 offset:36864
	s_add_u32 m0, s101, 0x6000
	v_mfma_f32_16x16x32_bf16 v[68:71], v[236:239], v[196:199], v[68:71]
	ds_read_b128 v[220:223], v174 offset:38912
	global_load_lds_dwordx4 v[252:253], off
	v_lshl_add_u64 v[252:253], v[252:253], 0, s[34:35]
	v_mfma_f32_16x16x32_bf16 v[40:43], v[224:227], v[200:203], v[40:43]
	v_mfma_f32_16x16x32_bf16 v[32:35], v[228:231], v[200:203], v[32:35]
	v_mfma_f32_16x16x32_bf16 v[44:47], v[232:235], v[200:203], v[44:47]
	v_mfma_f32_16x16x32_bf16 v[36:39], v[236:239], v[200:203], v[36:39]
	v_mfma_f32_16x16x32_bf16 v[8:11], v[224:227], v[204:207], v[8:11]
	v_mfma_f32_16x16x32_bf16 v[0:3], v[228:231], v[204:207], v[0:3]
	v_mfma_f32_16x16x32_bf16 v[12:15], v[232:235], v[204:207], v[12:15]
	v_mfma_f32_16x16x32_bf16 v[4:7], v[236:239], v[204:207], v[4:7]
	s_waitcnt lgkmcnt(0)
	s_nop 0
	v_mfma_f32_16x16x32_bf16 v[120:123], v[208:211], v[176:179], v[120:123]
	ds_read_b128 v[224:227], v174 offset:40960
	v_mfma_f32_16x16x32_bf16 v[112:115], v[212:215], v[176:179], v[112:115]
	ds_read_b128 v[228:231], v174 offset:43008
	v_mfma_f32_16x16x32_bf16 v[124:127], v[216:219], v[176:179], v[124:127]
	ds_read_b128 v[232:235], v174 offset:45056
	v_mfma_f32_16x16x32_bf16 v[116:119], v[220:223], v[176:179], v[116:119]
	ds_read_b128 v[236:239], v174 offset:47104
	v_mfma_f32_16x16x32_bf16 v[88:91], v[208:211], v[180:183], v[88:91]
	s_add_u32 m0, s100, 0x20000
	v_mfma_f32_16x16x32_bf16 v[80:83], v[212:215], v[180:183], v[80:83]
	global_load_lds_dwordx4 v[240:241], off
	v_lshl_add_u64 v[240:241], v[240:241], 0, s[34:35]
	v_mfma_f32_16x16x32_bf16 v[92:95], v[216:219], v[180:183], v[92:95]
	s_add_u32 m0, s100, 0x22000
	v_mfma_f32_16x16x32_bf16 v[84:87], v[220:223], v[180:183], v[84:87]
	global_load_lds_dwordx4 v[242:243], off
	v_lshl_add_u64 v[242:243], v[242:243], 0, s[34:35]
	v_mfma_f32_16x16x32_bf16 v[56:59], v[208:211], v[184:187], v[56:59]
	s_add_u32 m0, s100, 0x24000
	v_mfma_f32_16x16x32_bf16 v[48:51], v[212:215], v[184:187], v[48:51]
	global_load_lds_dwordx4 v[244:245], off
	v_lshl_add_u64 v[244:245], v[244:245], 0, s[34:35]
	v_mfma_f32_16x16x32_bf16 v[60:63], v[216:219], v[184:187], v[60:63]
	s_add_u32 m0, s100, 0x26000
	v_mfma_f32_16x16x32_bf16 v[52:55], v[220:223], v[184:187], v[52:55]
	global_load_lds_dwordx4 v[246:247], off
	v_lshl_add_u64 v[246:247], v[246:247], 0, s[34:35]
	v_mfma_f32_16x16x32_bf16 v[24:27], v[208:211], v[188:191], v[24:27]
	v_mfma_f32_16x16x32_bf16 v[16:19], v[212:215], v[188:191], v[16:19]
	v_mfma_f32_16x16x32_bf16 v[28:31], v[216:219], v[188:191], v[28:31]
	v_mfma_f32_16x16x32_bf16 v[20:23], v[220:223], v[188:191], v[20:23]
	s_waitcnt lgkmcnt(0)
	s_nop 0
	v_mfma_f32_16x16x32_bf16 v[104:107], v[224:227], v[176:179], v[104:107]
	ds_read_b128 v[192:195], v173 offset:0
	v_mfma_f32_16x16x32_bf16 v[96:99], v[228:231], v[176:179], v[96:99]
	ds_read_b128 v[196:199], v173 offset:2048
	v_mfma_f32_16x16x32_bf16 v[108:111], v[232:235], v[176:179], v[108:111]
	ds_read_b128 v[200:203], v173 offset:4096
	v_mfma_f32_16x16x32_bf16 v[100:103], v[236:239], v[176:179], v[100:103]
	ds_read_b128 v[204:207], v173 offset:6144
	v_mfma_f32_16x16x32_bf16 v[72:75], v[224:227], v[180:183], v[72:75]
	ds_read_b128 v[208:211], v175 offset:32768
	v_mfma_f32_16x16x32_bf16 v[64:67], v[228:231], v[180:183], v[64:67]
	ds_read_b128 v[212:215], v175 offset:34816
	v_mfma_f32_16x16x32_bf16 v[76:79], v[232:235], v[180:183], v[76:79]
	ds_read_b128 v[216:219], v175 offset:36864
	v_mfma_f32_16x16x32_bf16 v[68:71], v[236:239], v[180:183], v[68:71]
	ds_read_b128 v[220:223], v175 offset:38912
	v_mfma_f32_16x16x32_bf16 v[40:43], v[224:227], v[184:187], v[40:43]
	v_mfma_f32_16x16x32_bf16 v[32:35], v[228:231], v[184:187], v[32:35]
	v_mfma_f32_16x16x32_bf16 v[44:47], v[232:235], v[184:187], v[44:47]
	v_mfma_f32_16x16x32_bf16 v[36:39], v[236:239], v[184:187], v[36:39]
	v_mfma_f32_16x16x32_bf16 v[8:11], v[224:227], v[188:191], v[8:11]
	v_mfma_f32_16x16x32_bf16 v[0:3], v[228:231], v[188:191], v[0:3]
	v_mfma_f32_16x16x32_bf16 v[12:15], v[232:235], v[188:191], v[12:15]
	v_mfma_f32_16x16x32_bf16 v[4:7], v[236:239], v[188:191], v[4:7]
	s_waitcnt lgkmcnt(0)
	s_nop 0
	v_mfma_f32_16x16x32_bf16 v[120:123], v[208:211], v[192:195], v[120:123]
	ds_read_b128 v[224:227], v175 offset:40960
	v_mfma_f32_16x16x32_bf16 v[112:115], v[212:215], v[192:195], v[112:115]
	ds_read_b128 v[228:231], v175 offset:43008
	v_mfma_f32_16x16x32_bf16 v[124:127], v[216:219], v[192:195], v[124:127]
	ds_read_b128 v[232:235], v175 offset:45056
	v_mfma_f32_16x16x32_bf16 v[116:119], v[220:223], v[192:195], v[116:119]
	ds_read_b128 v[236:239], v175 offset:47104
	v_mfma_f32_16x16x32_bf16 v[88:91], v[208:211], v[196:199], v[88:91]
	v_mfma_f32_16x16x32_bf16 v[80:83], v[212:215], v[196:199], v[80:83]
	v_mfma_f32_16x16x32_bf16 v[92:95], v[216:219], v[196:199], v[92:95]
	v_mfma_f32_16x16x32_bf16 v[84:87], v[220:223], v[196:199], v[84:87]
	v_mfma_f32_16x16x32_bf16 v[56:59], v[208:211], v[200:203], v[56:59]
	v_mfma_f32_16x16x32_bf16 v[48:51], v[212:215], v[200:203], v[48:51]
	v_mfma_f32_16x16x32_bf16 v[60:63], v[216:219], v[200:203], v[60:63]
	v_mfma_f32_16x16x32_bf16 v[52:55], v[220:223], v[200:203], v[52:55]
	v_mfma_f32_16x16x32_bf16 v[24:27], v[208:211], v[204:207], v[24:27]
	v_mfma_f32_16x16x32_bf16 v[16:19], v[212:215], v[204:207], v[16:19]
	v_mfma_f32_16x16x32_bf16 v[28:31], v[216:219], v[204:207], v[28:31]
	v_mfma_f32_16x16x32_bf16 v[20:23], v[220:223], v[204:207], v[20:23]
	s_waitcnt lgkmcnt(0)
	s_waitcnt vmcnt(4)
	s_barrier
	s_nop 0
	v_mfma_f32_16x16x32_bf16 v[104:107], v[224:227], v[192:195], v[104:107]
	ds_read_b128 v[176:179], v172 offset:32768
	s_add_u32 m0, s101, 0x8000
	v_mfma_f32_16x16x32_bf16 v[96:99], v[228:231], v[192:195], v[96:99]
	ds_read_b128 v[180:183], v172 offset:34816
	global_load_lds_dwordx4 v[138:139], off
	v_lshl_add_u64 v[138:139], v[138:139], 0, s[34:35]
	v_mfma_f32_16x16x32_bf16 v[108:111], v[232:235], v[192:195], v[108:111]
	ds_read_b128 v[184:187], v172 offset:36864
	s_add_u32 m0, s101, 0xa000
	v_mfma_f32_16x16x32_bf16 v[100:103], v[236:239], v[192:195], v[100:103]
	ds_read_b128 v[188:191], v172 offset:38912
	global_load_lds_dwordx4 v[140:141], off
	v_lshl_add_u64 v[140:141], v[140:141], 0, s[34:35]
	v_mfma_f32_16x16x32_bf16 v[72:75], v[224:227], v[196:199], v[72:75]
	ds_read_b128 v[208:211], v174 offset:0
	s_add_u32 m0, s101, 0xc000
	v_mfma_f32_16x16x32_bf16 v[64:67], v[228:231], v[196:199], v[64:67]
	ds_read_b128 v[212:215], v174 offset:2048
	global_load_lds_dwordx4 v[250:251], off
	v_lshl_add_u64 v[250:251], v[250:251], 0, s[34:35]
	v_mfma_f32_16x16x32_bf16 v[76:79], v[232:235], v[196:199], v[76:79]
	ds_read_b128 v[216:219], v174 offset:4096
	s_add_u32 m0, s101, 0xe000
	v_mfma_f32_16x16x32_bf16 v[68:71], v[236:239], v[196:199], v[68:71]
	ds_read_b128 v[220:223], v174 offset:6144
	global_load_lds_dwordx4 v[252:253], off
	v_lshl_add_u64 v[252:253], v[252:253], 0, s[34:35]
	v_mfma_f32_16x16x32_bf16 v[40:43], v[224:227], v[200:203], v[40:43]
	v_mfma_f32_16x16x32_bf16 v[32:35], v[228:231], v[200:203], v[32:35]
	v_mfma_f32_16x16x32_bf16 v[44:47], v[232:235], v[200:203], v[44:47]
	v_mfma_f32_16x16x32_bf16 v[36:39], v[236:239], v[200:203], v[36:39]
	v_mfma_f32_16x16x32_bf16 v[8:11], v[224:227], v[204:207], v[8:11]
	v_mfma_f32_16x16x32_bf16 v[0:3], v[228:231], v[204:207], v[0:3]
	v_mfma_f32_16x16x32_bf16 v[12:15], v[232:235], v[204:207], v[12:15]
	v_mfma_f32_16x16x32_bf16 v[4:7], v[236:239], v[204:207], v[4:7]
	s_waitcnt lgkmcnt(0)
	s_nop 0
	v_mfma_f32_16x16x32_bf16 v[120:123], v[208:211], v[176:179], v[120:123]
	ds_read_b128 v[224:227], v174 offset:8192
	v_mfma_f32_16x16x32_bf16 v[112:115], v[212:215], v[176:179], v[112:115]
	ds_read_b128 v[228:231], v174 offset:10240
	v_mfma_f32_16x16x32_bf16 v[124:127], v[216:219], v[176:179], v[124:127]
	ds_read_b128 v[232:235], v174 offset:12288
	v_mfma_f32_16x16x32_bf16 v[116:119], v[220:223], v[176:179], v[116:119]
	ds_read_b128 v[236:239], v174 offset:14336
	v_mfma_f32_16x16x32_bf16 v[88:91], v[208:211], v[180:183], v[88:91]
	s_mov_b32 m0, s100
	s_nop 0
	v_mfma_f32_16x16x32_bf16 v[80:83], v[212:215], v[180:183], v[80:83]
	global_load_lds_dwordx4 v[240:241], off
	v_lshl_add_u64 v[240:241], v[240:241], 0, s[34:35]
	v_mfma_f32_16x16x32_bf16 v[92:95], v[216:219], v[180:183], v[92:95]
	s_add_u32 m0, s100, 0x2000
	v_mfma_f32_16x16x32_bf16 v[84:87], v[220:223], v[180:183], v[84:87]
	global_load_lds_dwordx4 v[242:243], off
	v_lshl_add_u64 v[242:243], v[242:243], 0, s[34:35]
	v_mfma_f32_16x16x32_bf16 v[56:59], v[208:211], v[184:187], v[56:59]
	s_add_u32 m0, s100, 0x4000
	v_mfma_f32_16x16x32_bf16 v[48:51], v[212:215], v[184:187], v[48:51]
	global_load_lds_dwordx4 v[244:245], off
	v_lshl_add_u64 v[244:245], v[244:245], 0, s[34:35]
	v_mfma_f32_16x16x32_bf16 v[60:63], v[216:219], v[184:187], v[60:63]
	s_add_u32 m0, s100, 0x6000
	v_mfma_f32_16x16x32_bf16 v[52:55], v[220:223], v[184:187], v[52:55]
	global_load_lds_dwordx4 v[246:247], off
	v_lshl_add_u64 v[246:247], v[246:247], 0, s[34:35]
	v_mfma_f32_16x16x32_bf16 v[24:27], v[208:211], v[188:191], v[24:27]
	v_mfma_f32_16x16x32_bf16 v[16:19], v[212:215], v[188:191], v[16:19]
	v_mfma_f32_16x16x32_bf16 v[28:31], v[216:219], v[188:191], v[28:31]
	v_mfma_f32_16x16x32_bf16 v[20:23], v[220:223], v[188:191], v[20:23]
	s_waitcnt lgkmcnt(0)
	s_nop 0
	v_mfma_f32_16x16x32_bf16 v[104:107], v[224:227], v[176:179], v[104:107]
	ds_read_b128 v[192:195], v173 offset:32768
	v_mfma_f32_16x16x32_bf16 v[96:99], v[228:231], v[176:179], v[96:99]
	ds_read_b128 v[196:199], v173 offset:34816
	v_mfma_f32_16x16x32_bf16 v[108:111], v[232:235], v[176:179], v[108:111]
	ds_read_b128 v[200:203], v173 offset:36864
	v_mfma_f32_16x16x32_bf16 v[100:103], v[236:239], v[176:179], v[100:103]
	ds_read_b128 v[204:207], v173 offset:38912
	v_mfma_f32_16x16x32_bf16 v[72:75], v[224:227], v[180:183], v[72:75]
	ds_read_b128 v[208:211], v175 offset:0
	v_mfma_f32_16x16x32_bf16 v[64:67], v[228:231], v[180:183], v[64:67]
	ds_read_b128 v[212:215], v175 offset:2048
	v_mfma_f32_16x16x32_bf16 v[76:79], v[232:235], v[180:183], v[76:79]
	ds_read_b128 v[216:219], v175 offset:4096
	v_mfma_f32_16x16x32_bf16 v[68:71], v[236:239], v[180:183], v[68:71]
	ds_read_b128 v[220:223], v175 offset:6144
	v_mfma_f32_16x16x32_bf16 v[40:43], v[224:227], v[184:187], v[40:43]
	v_mfma_f32_16x16x32_bf16 v[32:35], v[228:231], v[184:187], v[32:35]
	v_mfma_f32_16x16x32_bf16 v[44:47], v[232:235], v[184:187], v[44:47]
	v_mfma_f32_16x16x32_bf16 v[36:39], v[236:239], v[184:187], v[36:39]
	v_mfma_f32_16x16x32_bf16 v[8:11], v[224:227], v[188:191], v[8:11]
	v_mfma_f32_16x16x32_bf16 v[0:3], v[228:231], v[188:191], v[0:3]
	v_mfma_f32_16x16x32_bf16 v[12:15], v[232:235], v[188:191], v[12:15]
	v_mfma_f32_16x16x32_bf16 v[4:7], v[236:239], v[188:191], v[4:7]
	s_waitcnt lgkmcnt(0)
	s_nop 0
	v_mfma_f32_16x16x32_bf16 v[120:123], v[208:211], v[192:195], v[120:123]
	ds_read_b128 v[224:227], v175 offset:8192
	v_mfma_f32_16x16x32_bf16 v[112:115], v[212:215], v[192:195], v[112:115]
	ds_read_b128 v[228:231], v175 offset:10240
	v_mfma_f32_16x16x32_bf16 v[124:127], v[216:219], v[192:195], v[124:127]
	ds_read_b128 v[232:235], v175 offset:12288
	v_mfma_f32_16x16x32_bf16 v[116:119], v[220:223], v[192:195], v[116:119]
	ds_read_b128 v[236:239], v175 offset:14336
	v_mfma_f32_16x16x32_bf16 v[88:91], v[208:211], v[196:199], v[88:91]
	v_mfma_f32_16x16x32_bf16 v[80:83], v[212:215], v[196:199], v[80:83]
	v_mfma_f32_16x16x32_bf16 v[92:95], v[216:219], v[196:199], v[92:95]
	v_mfma_f32_16x16x32_bf16 v[84:87], v[220:223], v[196:199], v[84:87]
	v_mfma_f32_16x16x32_bf16 v[56:59], v[208:211], v[200:203], v[56:59]
	v_mfma_f32_16x16x32_bf16 v[48:51], v[212:215], v[200:203], v[48:51]
	v_mfma_f32_16x16x32_bf16 v[60:63], v[216:219], v[200:203], v[60:63]
	v_mfma_f32_16x16x32_bf16 v[52:55], v[220:223], v[200:203], v[52:55]
	v_mfma_f32_16x16x32_bf16 v[24:27], v[208:211], v[204:207], v[24:27]
	v_mfma_f32_16x16x32_bf16 v[16:19], v[212:215], v[204:207], v[16:19]
	v_mfma_f32_16x16x32_bf16 v[28:31], v[216:219], v[204:207], v[28:31]
	v_mfma_f32_16x16x32_bf16 v[20:23], v[220:223], v[204:207], v[20:23]
	s_waitcnt lgkmcnt(0)
	s_waitcnt vmcnt(4)
	s_barrier
	s_nop 0
	v_mfma_f32_16x16x32_bf16 v[104:107], v[224:227], v[192:195], v[104:107]
	ds_read_b128 v[176:179], v254 offset:0
	s_mov_b32 m0, s101
	s_nop 0
	v_mfma_f32_16x16x32_bf16 v[96:99], v[228:231], v[192:195], v[96:99]
	ds_read_b128 v[180:183], v254 offset:2048
	global_load_lds_dwordx4 v[138:139], off
	v_lshl_add_u64 v[138:139], v[138:139], 0, s[34:35]
	v_mfma_f32_16x16x32_bf16 v[108:111], v[232:235], v[192:195], v[108:111]
	ds_read_b128 v[184:187], v254 offset:4096
	s_add_u32 m0, s101, 0x2000
	v_mfma_f32_16x16x32_bf16 v[100:103], v[236:239], v[192:195], v[100:103]
	ds_read_b128 v[188:191], v254 offset:6144
	global_load_lds_dwordx4 v[140:141], off
	v_lshl_add_u64 v[140:141], v[140:141], 0, s[34:35]
	v_mfma_f32_16x16x32_bf16 v[72:75], v[224:227], v[196:199], v[72:75]
	ds_read_b128 v[208:211], v174 offset:32768
	s_add_u32 m0, s101, 0x4000
	v_mfma_f32_16x16x32_bf16 v[64:67], v[228:231], v[196:199], v[64:67]
	ds_read_b128 v[212:215], v174 offset:34816
	global_load_lds_dwordx4 v[250:251], off
	v_lshl_add_u64 v[250:251], v[250:251], 0, s[34:35]
	v_mfma_f32_16x16x32_bf16 v[76:79], v[232:235], v[196:199], v[76:79]
	ds_read_b128 v[216:219], v174 offset:36864
	s_add_u32 m0, s101, 0x6000
	v_mfma_f32_16x16x32_bf16 v[68:71], v[236:239], v[196:199], v[68:71]
	ds_read_b128 v[220:223], v174 offset:38912
	global_load_lds_dwordx4 v[252:253], off
	v_lshl_add_u64 v[252:253], v[252:253], 0, s[34:35]
	v_mfma_f32_16x16x32_bf16 v[40:43], v[224:227], v[200:203], v[40:43]
	v_mfma_f32_16x16x32_bf16 v[32:35], v[228:231], v[200:203], v[32:35]
	v_mfma_f32_16x16x32_bf16 v[44:47], v[232:235], v[200:203], v[44:47]
	v_mfma_f32_16x16x32_bf16 v[36:39], v[236:239], v[200:203], v[36:39]
	v_mfma_f32_16x16x32_bf16 v[8:11], v[224:227], v[204:207], v[8:11]
	v_mfma_f32_16x16x32_bf16 v[0:3], v[228:231], v[204:207], v[0:3]
	v_mfma_f32_16x16x32_bf16 v[12:15], v[232:235], v[204:207], v[12:15]
	v_mfma_f32_16x16x32_bf16 v[4:7], v[236:239], v[204:207], v[4:7]
	s_waitcnt lgkmcnt(0)
	s_nop 0
	v_mfma_f32_16x16x32_bf16 v[120:123], v[208:211], v[176:179], v[120:123]
	ds_read_b128 v[224:227], v174 offset:40960
	v_mfma_f32_16x16x32_bf16 v[112:115], v[212:215], v[176:179], v[112:115]
	ds_read_b128 v[228:231], v174 offset:43008
	v_mfma_f32_16x16x32_bf16 v[124:127], v[216:219], v[176:179], v[124:127]
	ds_read_b128 v[232:235], v174 offset:45056
	v_mfma_f32_16x16x32_bf16 v[116:119], v[220:223], v[176:179], v[116:119]
	ds_read_b128 v[236:239], v174 offset:47104
	v_mfma_f32_16x16x32_bf16 v[88:91], v[208:211], v[180:183], v[88:91]
	s_add_u32 m0, s100, 0x8000
	v_mfma_f32_16x16x32_bf16 v[80:83], v[212:215], v[180:183], v[80:83]
	global_load_lds_dwordx4 v[240:241], off
	v_lshl_add_u64 v[240:241], v[240:241], 0, s[34:35]
	v_mfma_f32_16x16x32_bf16 v[92:95], v[216:219], v[180:183], v[92:95]
	s_add_u32 m0, s100, 0xa000
	v_mfma_f32_16x16x32_bf16 v[84:87], v[220:223], v[180:183], v[84:87]
	global_load_lds_dwordx4 v[242:243], off
	v_lshl_add_u64 v[242:243], v[242:243], 0, s[34:35]
	v_mfma_f32_16x16x32_bf16 v[56:59], v[208:211], v[184:187], v[56:59]
	s_add_u32 m0, s100, 0xc000
	v_mfma_f32_16x16x32_bf16 v[48:51], v[212:215], v[184:187], v[48:51]
	global_load_lds_dwordx4 v[244:245], off
	v_lshl_add_u64 v[244:245], v[244:245], 0, s[34:35]
	v_mfma_f32_16x16x32_bf16 v[60:63], v[216:219], v[184:187], v[60:63]
	s_add_u32 m0, s100, 0xe000
	v_mfma_f32_16x16x32_bf16 v[52:55], v[220:223], v[184:187], v[52:55]
	global_load_lds_dwordx4 v[246:247], off
	v_lshl_add_u64 v[246:247], v[246:247], 0, s[34:35]
	v_mfma_f32_16x16x32_bf16 v[24:27], v[208:211], v[188:191], v[24:27]
	v_mfma_f32_16x16x32_bf16 v[16:19], v[212:215], v[188:191], v[16:19]
	v_mfma_f32_16x16x32_bf16 v[28:31], v[216:219], v[188:191], v[28:31]
	v_mfma_f32_16x16x32_bf16 v[20:23], v[220:223], v[188:191], v[20:23]
	s_waitcnt lgkmcnt(0)
	s_nop 0
	v_mfma_f32_16x16x32_bf16 v[104:107], v[224:227], v[176:179], v[104:107]
	ds_read_b128 v[192:195], v255 offset:0
	v_mfma_f32_16x16x32_bf16 v[96:99], v[228:231], v[176:179], v[96:99]
	ds_read_b128 v[196:199], v255 offset:2048
	v_mfma_f32_16x16x32_bf16 v[108:111], v[232:235], v[176:179], v[108:111]
	ds_read_b128 v[200:203], v255 offset:4096
	v_mfma_f32_16x16x32_bf16 v[100:103], v[236:239], v[176:179], v[100:103]
	ds_read_b128 v[204:207], v255 offset:6144
	v_mfma_f32_16x16x32_bf16 v[72:75], v[224:227], v[180:183], v[72:75]
	ds_read_b128 v[208:211], v175 offset:32768
	v_mfma_f32_16x16x32_bf16 v[64:67], v[228:231], v[180:183], v[64:67]
	ds_read_b128 v[212:215], v175 offset:34816
	v_mfma_f32_16x16x32_bf16 v[76:79], v[232:235], v[180:183], v[76:79]
	ds_read_b128 v[216:219], v175 offset:36864
	v_mfma_f32_16x16x32_bf16 v[68:71], v[236:239], v[180:183], v[68:71]
	ds_read_b128 v[220:223], v175 offset:38912
	v_mfma_f32_16x16x32_bf16 v[40:43], v[224:227], v[184:187], v[40:43]
	v_mfma_f32_16x16x32_bf16 v[32:35], v[228:231], v[184:187], v[32:35]
	v_mfma_f32_16x16x32_bf16 v[44:47], v[232:235], v[184:187], v[44:47]
	v_mfma_f32_16x16x32_bf16 v[36:39], v[236:239], v[184:187], v[36:39]
	v_mfma_f32_16x16x32_bf16 v[8:11], v[224:227], v[188:191], v[8:11]
	v_mfma_f32_16x16x32_bf16 v[0:3], v[228:231], v[188:191], v[0:3]
	v_mfma_f32_16x16x32_bf16 v[12:15], v[232:235], v[188:191], v[12:15]
	v_mfma_f32_16x16x32_bf16 v[4:7], v[236:239], v[188:191], v[4:7]
	s_waitcnt lgkmcnt(0)
	s_nop 0
	v_mfma_f32_16x16x32_bf16 v[120:123], v[208:211], v[192:195], v[120:123]
	ds_read_b128 v[224:227], v175 offset:40960
	v_mfma_f32_16x16x32_bf16 v[112:115], v[212:215], v[192:195], v[112:115]
	ds_read_b128 v[228:231], v175 offset:43008
	v_mfma_f32_16x16x32_bf16 v[124:127], v[216:219], v[192:195], v[124:127]
	ds_read_b128 v[232:235], v175 offset:45056
	v_mfma_f32_16x16x32_bf16 v[116:119], v[220:223], v[192:195], v[116:119]
	ds_read_b128 v[236:239], v175 offset:47104
	v_mfma_f32_16x16x32_bf16 v[88:91], v[208:211], v[196:199], v[88:91]
	v_mfma_f32_16x16x32_bf16 v[80:83], v[212:215], v[196:199], v[80:83]
	v_mfma_f32_16x16x32_bf16 v[92:95], v[216:219], v[196:199], v[92:95]
	v_mfma_f32_16x16x32_bf16 v[84:87], v[220:223], v[196:199], v[84:87]
	v_mfma_f32_16x16x32_bf16 v[56:59], v[208:211], v[200:203], v[56:59]
	v_mfma_f32_16x16x32_bf16 v[48:51], v[212:215], v[200:203], v[48:51]
	v_mfma_f32_16x16x32_bf16 v[60:63], v[216:219], v[200:203], v[60:63]
	v_mfma_f32_16x16x32_bf16 v[52:55], v[220:223], v[200:203], v[52:55]
	v_mfma_f32_16x16x32_bf16 v[24:27], v[208:211], v[204:207], v[24:27]
	v_mfma_f32_16x16x32_bf16 v[16:19], v[212:215], v[204:207], v[16:19]
	v_mfma_f32_16x16x32_bf16 v[28:31], v[216:219], v[204:207], v[28:31]
	v_mfma_f32_16x16x32_bf16 v[20:23], v[220:223], v[204:207], v[20:23]
	s_waitcnt lgkmcnt(0)
	s_waitcnt vmcnt(4)
	s_barrier
	s_nop 0
	v_mfma_f32_16x16x32_bf16 v[104:107], v[224:227], v[192:195], v[104:107]
	ds_read_b128 v[176:179], v172 offset:0
	s_add_u32 m0, s101, 0x8000
	v_mfma_f32_16x16x32_bf16 v[96:99], v[228:231], v[192:195], v[96:99]
	ds_read_b128 v[180:183], v172 offset:2048
	global_load_lds_dwordx4 v[138:139], off
	v_lshl_add_u64 v[138:139], v[138:139], 0, s[34:35]
	v_mfma_f32_16x16x32_bf16 v[108:111], v[232:235], v[192:195], v[108:111]
	ds_read_b128 v[184:187], v172 offset:4096
	s_add_u32 m0, s101, 0xa000
	v_mfma_f32_16x16x32_bf16 v[100:103], v[236:239], v[192:195], v[100:103]
	ds_read_b128 v[188:191], v172 offset:6144
	global_load_lds_dwordx4 v[140:141], off
	v_lshl_add_u64 v[140:141], v[140:141], 0, s[34:35]
	v_mfma_f32_16x16x32_bf16 v[72:75], v[224:227], v[196:199], v[72:75]
	ds_read_b128 v[208:211], v174 offset:0
	s_add_u32 m0, s101, 0xc000
	v_mfma_f32_16x16x32_bf16 v[64:67], v[228:231], v[196:199], v[64:67]
	ds_read_b128 v[212:215], v174 offset:2048
	global_load_lds_dwordx4 v[250:251], off
	v_lshl_add_u64 v[250:251], v[250:251], 0, s[34:35]
	v_mfma_f32_16x16x32_bf16 v[76:79], v[232:235], v[196:199], v[76:79]
	ds_read_b128 v[216:219], v174 offset:4096
	s_add_u32 m0, s101, 0xe000
	v_mfma_f32_16x16x32_bf16 v[68:71], v[236:239], v[196:199], v[68:71]
	ds_read_b128 v[220:223], v174 offset:6144
	global_load_lds_dwordx4 v[252:253], off
	v_lshl_add_u64 v[252:253], v[252:253], 0, s[34:35]
	v_mfma_f32_16x16x32_bf16 v[40:43], v[224:227], v[200:203], v[40:43]
	v_mfma_f32_16x16x32_bf16 v[32:35], v[228:231], v[200:203], v[32:35]
	v_mfma_f32_16x16x32_bf16 v[44:47], v[232:235], v[200:203], v[44:47]
	v_mfma_f32_16x16x32_bf16 v[36:39], v[236:239], v[200:203], v[36:39]
	v_mfma_f32_16x16x32_bf16 v[8:11], v[224:227], v[204:207], v[8:11]
	v_mfma_f32_16x16x32_bf16 v[0:3], v[228:231], v[204:207], v[0:3]
	v_mfma_f32_16x16x32_bf16 v[12:15], v[232:235], v[204:207], v[12:15]
	v_mfma_f32_16x16x32_bf16 v[4:7], v[236:239], v[204:207], v[4:7]
	s_waitcnt lgkmcnt(0)
	s_nop 0
	v_mfma_f32_16x16x32_bf16 v[120:123], v[208:211], v[176:179], v[120:123]
	ds_read_b128 v[224:227], v174 offset:8192
	v_mfma_f32_16x16x32_bf16 v[112:115], v[212:215], v[176:179], v[112:115]
	ds_read_b128 v[228:231], v174 offset:10240
	v_mfma_f32_16x16x32_bf16 v[124:127], v[216:219], v[176:179], v[124:127]
	ds_read_b128 v[232:235], v174 offset:12288
	v_mfma_f32_16x16x32_bf16 v[116:119], v[220:223], v[176:179], v[116:119]
	ds_read_b128 v[236:239], v174 offset:14336
	v_mfma_f32_16x16x32_bf16 v[88:91], v[208:211], v[180:183], v[88:91]
	s_add_u32 m0, s100, 0x20000
	v_mfma_f32_16x16x32_bf16 v[80:83], v[212:215], v[180:183], v[80:83]
	global_load_lds_dwordx4 v[240:241], off
	v_lshl_add_u64 v[240:241], v[240:241], 0, s[34:35]
	v_mfma_f32_16x16x32_bf16 v[92:95], v[216:219], v[180:183], v[92:95]
	s_add_u32 m0, s100, 0x22000
	v_mfma_f32_16x16x32_bf16 v[84:87], v[220:223], v[180:183], v[84:87]
	global_load_lds_dwordx4 v[242:243], off
	v_lshl_add_u64 v[242:243], v[242:243], 0, s[34:35]
	v_mfma_f32_16x16x32_bf16 v[56:59], v[208:211], v[184:187], v[56:59]
	s_add_u32 m0, s100, 0x24000
	v_mfma_f32_16x16x32_bf16 v[48:51], v[212:215], v[184:187], v[48:51]
	global_load_lds_dwordx4 v[244:245], off
	v_lshl_add_u64 v[244:245], v[244:245], 0, s[34:35]
	v_mfma_f32_16x16x32_bf16 v[60:63], v[216:219], v[184:187], v[60:63]
	s_add_u32 m0, s100, 0x26000
	v_mfma_f32_16x16x32_bf16 v[52:55], v[220:223], v[184:187], v[52:55]
	global_load_lds_dwordx4 v[246:247], off
	v_lshl_add_u64 v[246:247], v[246:247], 0, s[34:35]
	v_mfma_f32_16x16x32_bf16 v[24:27], v[208:211], v[188:191], v[24:27]
	v_mfma_f32_16x16x32_bf16 v[16:19], v[212:215], v[188:191], v[16:19]
	v_mfma_f32_16x16x32_bf16 v[28:31], v[216:219], v[188:191], v[28:31]
	v_mfma_f32_16x16x32_bf16 v[20:23], v[220:223], v[188:191], v[20:23]
	s_waitcnt lgkmcnt(0)
	s_nop 0
	v_mfma_f32_16x16x32_bf16 v[104:107], v[224:227], v[176:179], v[104:107]
	ds_read_b128 v[192:195], v173 offset:0
	v_mfma_f32_16x16x32_bf16 v[96:99], v[228:231], v[176:179], v[96:99]
	ds_read_b128 v[196:199], v173 offset:2048
	v_mfma_f32_16x16x32_bf16 v[108:111], v[232:235], v[176:179], v[108:111]
	ds_read_b128 v[200:203], v173 offset:4096
	v_mfma_f32_16x16x32_bf16 v[100:103], v[236:239], v[176:179], v[100:103]
	ds_read_b128 v[204:207], v173 offset:6144
	v_mfma_f32_16x16x32_bf16 v[72:75], v[224:227], v[180:183], v[72:75]
	ds_read_b128 v[208:211], v175 offset:0
	v_mfma_f32_16x16x32_bf16 v[64:67], v[228:231], v[180:183], v[64:67]
	ds_read_b128 v[212:215], v175 offset:2048
	v_mfma_f32_16x16x32_bf16 v[76:79], v[232:235], v[180:183], v[76:79]
	ds_read_b128 v[216:219], v175 offset:4096
	v_mfma_f32_16x16x32_bf16 v[68:71], v[236:239], v[180:183], v[68:71]
	ds_read_b128 v[220:223], v175 offset:6144
	v_mfma_f32_16x16x32_bf16 v[40:43], v[224:227], v[184:187], v[40:43]
	v_mfma_f32_16x16x32_bf16 v[32:35], v[228:231], v[184:187], v[32:35]
	v_mfma_f32_16x16x32_bf16 v[44:47], v[232:235], v[184:187], v[44:47]
	v_mfma_f32_16x16x32_bf16 v[36:39], v[236:239], v[184:187], v[36:39]
	v_mfma_f32_16x16x32_bf16 v[8:11], v[224:227], v[188:191], v[8:11]
	v_mfma_f32_16x16x32_bf16 v[0:3], v[228:231], v[188:191], v[0:3]
	v_mfma_f32_16x16x32_bf16 v[12:15], v[232:235], v[188:191], v[12:15]
	v_mfma_f32_16x16x32_bf16 v[4:7], v[236:239], v[188:191], v[4:7]
	s_waitcnt lgkmcnt(0)
	s_nop 0
	v_mfma_f32_16x16x32_bf16 v[120:123], v[208:211], v[192:195], v[120:123]
	ds_read_b128 v[224:227], v175 offset:8192
	v_mfma_f32_16x16x32_bf16 v[112:115], v[212:215], v[192:195], v[112:115]
	ds_read_b128 v[228:231], v175 offset:10240
	v_mfma_f32_16x16x32_bf16 v[124:127], v[216:219], v[192:195], v[124:127]
	ds_read_b128 v[232:235], v175 offset:12288
	v_mfma_f32_16x16x32_bf16 v[116:119], v[220:223], v[192:195], v[116:119]
	ds_read_b128 v[236:239], v175 offset:14336
	v_mfma_f32_16x16x32_bf16 v[88:91], v[208:211], v[196:199], v[88:91]
	v_mfma_f32_16x16x32_bf16 v[80:83], v[212:215], v[196:199], v[80:83]
	v_mfma_f32_16x16x32_bf16 v[92:95], v[216:219], v[196:199], v[92:95]
	v_mfma_f32_16x16x32_bf16 v[84:87], v[220:223], v[196:199], v[84:87]
	v_mfma_f32_16x16x32_bf16 v[56:59], v[208:211], v[200:203], v[56:59]
	v_mfma_f32_16x16x32_bf16 v[48:51], v[212:215], v[200:203], v[48:51]
	v_mfma_f32_16x16x32_bf16 v[60:63], v[216:219], v[200:203], v[60:63]
	v_mfma_f32_16x16x32_bf16 v[52:55], v[220:223], v[200:203], v[52:55]
	v_mfma_f32_16x16x32_bf16 v[24:27], v[208:211], v[204:207], v[24:27]
	v_mfma_f32_16x16x32_bf16 v[16:19], v[212:215], v[204:207], v[16:19]
	v_mfma_f32_16x16x32_bf16 v[28:31], v[216:219], v[204:207], v[28:31]
	v_mfma_f32_16x16x32_bf16 v[20:23], v[220:223], v[204:207], v[20:23]
	s_waitcnt lgkmcnt(0)
	s_waitcnt vmcnt(4)
	s_barrier
	s_add_i32 s7, s7, -1
	s_cmp_lg_u32 s7, 0
	s_cbranch_scc1 .Lgemm_p2_loop
	v_mfma_f32_16x16x32_bf16 v[104:107], v[224:227], v[192:195], v[104:107]
	ds_read_b128 v[176:179], v172 offset:32768
	s_mov_b32 m0, s101
	s_nop 0
	v_mfma_f32_16x16x32_bf16 v[96:99], v[228:231], v[192:195], v[96:99]
	ds_read_b128 v[180:183], v172 offset:34816
	global_load_lds_dwordx4 v[138:139], off
	v_lshl_add_u64 v[138:139], v[138:139], 0, s[34:35]
	v_mfma_f32_16x16x32_bf16 v[108:111], v[232:235], v[192:195], v[108:111]
	ds_read_b128 v[184:187], v172 offset:36864
	s_add_u32 m0, s101, 0x2000
	v_mfma_f32_16x16x32_bf16 v[100:103], v[236:239], v[192:195], v[100:103]
	ds_read_b128 v[188:191], v172 offset:38912
	global_load_lds_dwordx4 v[140:141], off
	v_lshl_add_u64 v[140:141], v[140:141], 0, s[34:35]
	v_mfma_f32_16x16x32_bf16 v[72:75], v[224:227], v[196:199], v[72:75]
	ds_read_b128 v[208:211], v174 offset:32768
	s_add_u32 m0, s101, 0x4000
	v_mfma_f32_16x16x32_bf16 v[64:67], v[228:231], v[196:199], v[64:67]
	ds_read_b128 v[212:215], v174 offset:34816
	global_load_lds_dwordx4 v[250:251], off
	v_lshl_add_u64 v[250:251], v[250:251], 0, s[34:35]
	v_mfma_f32_16x16x32_bf16 v[76:79], v[232:235], v[196:199], v[76:79]
	ds_read_b128 v[216:219], v174 offset:36864
	s_add_u32 m0, s101, 0x6000
	v_mfma_f32_16x16x32_bf16 v[68:71], v[236:239], v[196:199], v[68:71]
	ds_read_b128 v[220:223], v174 offset:38912
	global_load_lds_dwordx4 v[252:253], off
	v_lshl_add_u64 v[252:253], v[252:253], 0, s[34:35]
	v_mfma_f32_16x16x32_bf16 v[40:43], v[224:227], v[200:203], v[40:43]
	v_mfma_f32_16x16x32_bf16 v[32:35], v[228:231], v[200:203], v[32:35]
	v_mfma_f32_16x16x32_bf16 v[44:47], v[232:235], v[200:203], v[44:47]
	v_mfma_f32_16x16x32_bf16 v[36:39], v[236:239], v[200:203], v[36:39]
	v_mfma_f32_16x16x32_bf16 v[8:11], v[224:227], v[204:207], v[8:11]
	v_mfma_f32_16x16x32_bf16 v[0:3], v[228:231], v[204:207], v[0:3]
	v_mfma_f32_16x16x32_bf16 v[12:15], v[232:235], v[204:207], v[12:15]
	v_mfma_f32_16x16x32_bf16 v[4:7], v[236:239], v[204:207], v[4:7]
	s_waitcnt lgkmcnt(0)
	s_nop 0
	v_mfma_f32_16x16x32_bf16 v[120:123], v[208:211], v[176:179], v[120:123]
	ds_read_b128 v[224:227], v174 offset:40960
	v_mfma_f32_16x16x32_bf16 v[112:115], v[212:215], v[176:179], v[112:115]
	ds_read_b128 v[228:231], v174 offset:43008
	v_mfma_f32_16x16x32_bf16 v[124:127], v[216:219], v[176:179], v[124:127]
	ds_read_b128 v[232:235], v174 offset:45056
	v_mfma_f32_16x16x32_bf16 v[116:119], v[220:223], v[176:179], v[116:119]
	ds_read_b128 v[236:239], v174 offset:47104
	v_mfma_f32_16x16x32_bf16 v[88:91], v[208:211], v[180:183], v[88:91]
	s_mov_b32 m0, s100
	s_nop 0
	v_mfma_f32_16x16x32_bf16 v[80:83], v[212:215], v[180:183], v[80:83]
	global_load_lds_dwordx4 v[240:241], off
	v_lshl_add_u64 v[240:241], v[240:241], 0, s[34:35]
	v_mfma_f32_16x16x32_bf16 v[92:95], v[216:219], v[180:183], v[92:95]
	s_add_u32 m0, s100, 0x2000
	v_mfma_f32_16x16x32_bf16 v[84:87], v[220:223], v[180:183], v[84:87]
	global_load_lds_dwordx4 v[242:243], off
	v_lshl_add_u64 v[242:243], v[242:243], 0, s[34:35]
	v_mfma_f32_16x16x32_bf16 v[56:59], v[208:211], v[184:187], v[56:59]
	s_add_u32 m0, s100, 0x4000
	v_mfma_f32_16x16x32_bf16 v[48:51], v[212:215], v[184:187], v[48:51]
	global_load_lds_dwordx4 v[244:245], off
	v_lshl_add_u64 v[244:245], v[244:245], 0, s[34:35]
	v_mfma_f32_16x16x32_bf16 v[60:63], v[216:219], v[184:187], v[60:63]
	s_add_u32 m0, s100, 0x6000
	v_mfma_f32_16x16x32_bf16 v[52:55], v[220:223], v[184:187], v[52:55]
	global_load_lds_dwordx4 v[246:247], off
	v_lshl_add_u64 v[246:247], v[246:247], 0, s[34:35]
	v_mfma_f32_16x16x32_bf16 v[24:27], v[208:211], v[188:191], v[24:27]
	v_mfma_f32_16x16x32_bf16 v[16:19], v[212:215], v[188:191], v[16:19]
	v_mfma_f32_16x16x32_bf16 v[28:31], v[216:219], v[188:191], v[28:31]
	v_mfma_f32_16x16x32_bf16 v[20:23], v[220:223], v[188:191], v[20:23]
	s_waitcnt lgkmcnt(0)
	s_nop 0
	v_mfma_f32_16x16x32_bf16 v[104:107], v[224:227], v[176:179], v[104:107]
	ds_read_b128 v[192:195], v173 offset:32768
	v_mfma_f32_16x16x32_bf16 v[96:99], v[228:231], v[176:179], v[96:99]
	ds_read_b128 v[196:199], v173 offset:34816
	v_mfma_f32_16x16x32_bf16 v[108:111], v[232:235], v[176:179], v[108:111]
	ds_read_b128 v[200:203], v173 offset:36864
	v_mfma_f32_16x16x32_bf16 v[100:103], v[236:239], v[176:179], v[100:103]
	ds_read_b128 v[204:207], v173 offset:38912
	v_mfma_f32_16x16x32_bf16 v[72:75], v[224:227], v[180:183], v[72:75]
	ds_read_b128 v[208:211], v175 offset:32768
	v_mfma_f32_16x16x32_bf16 v[64:67], v[228:231], v[180:183], v[64:67]
	ds_read_b128 v[212:215], v175 offset:34816
	v_mfma_f32_16x16x32_bf16 v[76:79], v[232:235], v[180:183], v[76:79]
	ds_read_b128 v[216:219], v175 offset:36864
	v_mfma_f32_16x16x32_bf16 v[68:71], v[236:239], v[180:183], v[68:71]
	ds_read_b128 v[220:223], v175 offset:38912
	v_mfma_f32_16x16x32_bf16 v[40:43], v[224:227], v[184:187], v[40:43]
	v_mfma_f32_16x16x32_bf16 v[32:35], v[228:231], v[184:187], v[32:35]
	v_mfma_f32_16x16x32_bf16 v[44:47], v[232:235], v[184:187], v[44:47]
	v_mfma_f32_16x16x32_bf16 v[36:39], v[236:239], v[184:187], v[36:39]
	v_mfma_f32_16x16x32_bf16 v[8:11], v[224:227], v[188:191], v[8:11]
	v_mfma_f32_16x16x32_bf16 v[0:3], v[228:231], v[188:191], v[0:3]
	v_mfma_f32_16x16x32_bf16 v[12:15], v[232:235], v[188:191], v[12:15]
	v_mfma_f32_16x16x32_bf16 v[4:7], v[236:239], v[188:191], v[4:7]
	s_waitcnt lgkmcnt(0)
	s_nop 0
	v_mfma_f32_16x16x32_bf16 v[120:123], v[208:211], v[192:195], v[120:123]
	ds_read_b128 v[224:227], v175 offset:40960
	v_mfma_f32_16x16x32_bf16 v[112:115], v[212:215], v[192:195], v[112:115]
	ds_read_b128 v[228:231], v175 offset:43008
	v_mfma_f32_16x16x32_bf16 v[124:127], v[216:219], v[192:195], v[124:127]
	ds_read_b128 v[232:235], v175 offset:45056
	v_mfma_f32_16x16x32_bf16 v[116:119], v[220:223], v[192:195], v[116:119]
	ds_read_b128 v[236:239], v175 offset:47104
	v_mfma_f32_16x16x32_bf16 v[88:91], v[208:211], v[196:199], v[88:91]
	v_mfma_f32_16x16x32_bf16 v[80:83], v[212:215], v[196:199], v[80:83]
	v_mfma_f32_16x16x32_bf16 v[92:95], v[216:219], v[196:199], v[92:95]
	v_mfma_f32_16x16x32_bf16 v[84:87], v[220:223], v[196:199], v[84:87]
	v_mfma_f32_16x16x32_bf16 v[56:59], v[208:211], v[200:203], v[56:59]
	v_mfma_f32_16x16x32_bf16 v[48:51], v[212:215], v[200:203], v[48:51]
	v_mfma_f32_16x16x32_bf16 v[60:63], v[216:219], v[200:203], v[60:63]
	v_mfma_f32_16x16x32_bf16 v[52:55], v[220:223], v[200:203], v[52:55]
	v_mfma_f32_16x16x32_bf16 v[24:27], v[208:211], v[204:207], v[24:27]
	v_mfma_f32_16x16x32_bf16 v[16:19], v[212:215], v[204:207], v[16:19]
	v_mfma_f32_16x16x32_bf16 v[28:31], v[216:219], v[204:207], v[28:31]
	v_mfma_f32_16x16x32_bf16 v[20:23], v[220:223], v[204:207], v[20:23]
	s_waitcnt lgkmcnt(0)
	s_waitcnt vmcnt(4)
	s_barrier
	s_nop 0
	v_mfma_f32_16x16x32_bf16 v[104:107], v[224:227], v[192:195], v[104:107]
	ds_read_b128 v[176:179], v254 offset:0
	s_add_u32 m0, s101, 0x8000
	v_mfma_f32_16x16x32_bf16 v[96:99], v[228:231], v[192:195], v[96:99]
	ds_read_b128 v[180:183], v254 offset:2048
	global_load_lds_dwordx4 v[138:139], off
	v_lshl_add_u64 v[138:139], v[138:139], 0, s[34:35]
	v_mfma_f32_16x16x32_bf16 v[108:111], v[232:235], v[192:195], v[108:111]
	ds_read_b128 v[184:187], v254 offset:4096
	s_add_u32 m0, s101, 0xa000
	v_mfma_f32_16x16x32_bf16 v[100:103], v[236:239], v[192:195], v[100:103]
	ds_read_b128 v[188:191], v254 offset:6144
	global_load_lds_dwordx4 v[140:141], off
	v_lshl_add_u64 v[140:141], v[140:141], 0, s[34:35]
	v_mfma_f32_16x16x32_bf16 v[72:75], v[224:227], v[196:199], v[72:75]
	ds_read_b128 v[208:211], v174 offset:0
	s_add_u32 m0, s101, 0xc000
	v_mfma_f32_16x16x32_bf16 v[64:67], v[228:231], v[196:199], v[64:67]
	ds_read_b128 v[212:215], v174 offset:2048
	global_load_lds_dwordx4 v[250:251], off
	v_lshl_add_u64 v[250:251], v[250:251], 0, s[34:35]
	v_mfma_f32_16x16x32_bf16 v[76:79], v[232:235], v[196:199], v[76:79]
	ds_read_b128 v[216:219], v174 offset:4096
	s_add_u32 m0, s101, 0xe000
	v_mfma_f32_16x16x32_bf16 v[68:71], v[236:239], v[196:199], v[68:71]
	ds_read_b128 v[220:223], v174 offset:6144
	global_load_lds_dwordx4 v[252:253], off
	v_lshl_add_u64 v[252:253], v[252:253], 0, s[34:35]
	v_mfma_f32_16x16x32_bf16 v[40:43], v[224:227], v[200:203], v[40:43]
	v_mfma_f32_16x16x32_bf16 v[32:35], v[228:231], v[200:203], v[32:35]
	v_mfma_f32_16x16x32_bf16 v[44:47], v[232:235], v[200:203], v[44:47]
	v_mfma_f32_16x16x32_bf16 v[36:39], v[236:239], v[200:203], v[36:39]
	v_mfma_f32_16x16x32_bf16 v[8:11], v[224:227], v[204:207], v[8:11]
	v_mfma_f32_16x16x32_bf16 v[0:3], v[228:231], v[204:207], v[0:3]
	v_mfma_f32_16x16x32_bf16 v[12:15], v[232:235], v[204:207], v[12:15]
	v_mfma_f32_16x16x32_bf16 v[4:7], v[236:239], v[204:207], v[4:7]
	s_waitcnt lgkmcnt(0)
	s_nop 0
	v_mfma_f32_16x16x32_bf16 v[120:123], v[208:211], v[176:179], v[120:123]
	ds_read_b128 v[224:227], v174 offset:8192
	v_mfma_f32_16x16x32_bf16 v[112:115], v[212:215], v[176:179], v[112:115]
	ds_read_b128 v[228:231], v174 offset:10240
	v_mfma_f32_16x16x32_bf16 v[124:127], v[216:219], v[176:179], v[124:127]
	ds_read_b128 v[232:235], v174 offset:12288
	v_mfma_f32_16x16x32_bf16 v[116:119], v[220:223], v[176:179], v[116:119]
	ds_read_b128 v[236:239], v174 offset:14336
	v_mfma_f32_16x16x32_bf16 v[88:91], v[208:211], v[180:183], v[88:91]
	v_mfma_f32_16x16x32_bf16 v[80:83], v[212:215], v[180:183], v[80:83]
	v_mfma_f32_16x16x32_bf16 v[92:95], v[216:219], v[180:183], v[92:95]
	v_mfma_f32_16x16x32_bf16 v[84:87], v[220:223], v[180:183], v[84:87]
	v_mfma_f32_16x16x32_bf16 v[56:59], v[208:211], v[184:187], v[56:59]
	v_mfma_f32_16x16x32_bf16 v[48:51], v[212:215], v[184:187], v[48:51]
	v_mfma_f32_16x16x32_bf16 v[60:63], v[216:219], v[184:187], v[60:63]
	v_mfma_f32_16x16x32_bf16 v[52:55], v[220:223], v[184:187], v[52:55]
	v_mfma_f32_16x16x32_bf16 v[24:27], v[208:211], v[188:191], v[24:27]
	v_mfma_f32_16x16x32_bf16 v[16:19], v[212:215], v[188:191], v[16:19]
	v_mfma_f32_16x16x32_bf16 v[28:31], v[216:219], v[188:191], v[28:31]
	v_mfma_f32_16x16x32_bf16 v[20:23], v[220:223], v[188:191], v[20:23]
	s_waitcnt lgkmcnt(0)
	s_nop 0
	v_mfma_f32_16x16x32_bf16 v[104:107], v[224:227], v[176:179], v[104:107]
	ds_read_b128 v[192:195], v255 offset:0
	v_mfma_f32_16x16x32_bf16 v[96:99], v[228:231], v[176:179], v[96:99]
	ds_read_b128 v[196:199], v255 offset:2048
	v_mfma_f32_16x16x32_bf16 v[108:111], v[232:235], v[176:179], v[108:111]
	ds_read_b128 v[200:203], v255 offset:4096
	v_mfma_f32_16x16x32_bf16 v[100:103], v[236:239], v[176:179], v[100:103]
	ds_read_b128 v[204:207], v255 offset:6144
	v_mfma_f32_16x16x32_bf16 v[72:75], v[224:227], v[180:183], v[72:75]
	ds_read_b128 v[208:211], v175 offset:0
	v_mfma_f32_16x16x32_bf16 v[64:67], v[228:231], v[180:183], v[64:67]
	ds_read_b128 v[212:215], v175 offset:2048
	v_mfma_f32_16x16x32_bf16 v[76:79], v[232:235], v[180:183], v[76:79]
	ds_read_b128 v[216:219], v175 offset:4096
	v_mfma_f32_16x16x32_bf16 v[68:71], v[236:239], v[180:183], v[68:71]
	ds_read_b128 v[220:223], v175 offset:6144
	v_mfma_f32_16x16x32_bf16 v[40:43], v[224:227], v[184:187], v[40:43]
	v_mfma_f32_16x16x32_bf16 v[32:35], v[228:231], v[184:187], v[32:35]
	v_mfma_f32_16x16x32_bf16 v[44:47], v[232:235], v[184:187], v[44:47]
	v_mfma_f32_16x16x32_bf16 v[36:39], v[236:239], v[184:187], v[36:39]
	v_mfma_f32_16x16x32_bf16 v[8:11], v[224:227], v[188:191], v[8:11]
	v_mfma_f32_16x16x32_bf16 v[0:3], v[228:231], v[188:191], v[0:3]
	v_mfma_f32_16x16x32_bf16 v[12:15], v[232:235], v[188:191], v[12:15]
	v_mfma_f32_16x16x32_bf16 v[4:7], v[236:239], v[188:191], v[4:7]
	s_waitcnt lgkmcnt(0)
	s_nop 0
	v_mfma_f32_16x16x32_bf16 v[120:123], v[208:211], v[192:195], v[120:123]
	ds_read_b128 v[224:227], v175 offset:8192
	v_mfma_f32_16x16x32_bf16 v[112:115], v[212:215], v[192:195], v[112:115]
	ds_read_b128 v[228:231], v175 offset:10240
	v_mfma_f32_16x16x32_bf16 v[124:127], v[216:219], v[192:195], v[124:127]
	ds_read_b128 v[232:235], v175 offset:12288
	v_mfma_f32_16x16x32_bf16 v[116:119], v[220:223], v[192:195], v[116:119]
	ds_read_b128 v[236:239], v175 offset:14336
	v_mfma_f32_16x16x32_bf16 v[88:91], v[208:211], v[196:199], v[88:91]
	v_mfma_f32_16x16x32_bf16 v[80:83], v[212:215], v[196:199], v[80:83]
	v_mfma_f32_16x16x32_bf16 v[92:95], v[216:219], v[196:199], v[92:95]
	v_mfma_f32_16x16x32_bf16 v[84:87], v[220:223], v[196:199], v[84:87]
	v_mfma_f32_16x16x32_bf16 v[56:59], v[208:211], v[200:203], v[56:59]
	v_mfma_f32_16x16x32_bf16 v[48:51], v[212:215], v[200:203], v[48:51]
	v_mfma_f32_16x16x32_bf16 v[60:63], v[216:219], v[200:203], v[60:63]
	v_mfma_f32_16x16x32_bf16 v[52:55], v[220:223], v[200:203], v[52:55]
	v_mfma_f32_16x16x32_bf16 v[24:27], v[208:211], v[204:207], v[24:27]
	v_mfma_f32_16x16x32_bf16 v[16:19], v[212:215], v[204:207], v[16:19]
	v_mfma_f32_16x16x32_bf16 v[28:31], v[216:219], v[204:207], v[28:31]
	v_mfma_f32_16x16x32_bf16 v[20:23], v[220:223], v[204:207], v[20:23]
	s_waitcnt lgkmcnt(0)
	s_waitcnt vmcnt(0)
	s_barrier
	s_nop 0
	v_mfma_f32_16x16x32_bf16 v[104:107], v[224:227], v[192:195], v[104:107]
	ds_read_b128 v[176:179], v172 offset:0
	v_mfma_f32_16x16x32_bf16 v[96:99], v[228:231], v[192:195], v[96:99]
	ds_read_b128 v[180:183], v172 offset:2048
	v_mfma_f32_16x16x32_bf16 v[108:111], v[232:235], v[192:195], v[108:111]
	ds_read_b128 v[184:187], v172 offset:4096
	v_mfma_f32_16x16x32_bf16 v[100:103], v[236:239], v[192:195], v[100:103]
	ds_read_b128 v[188:191], v172 offset:6144
	v_mfma_f32_16x16x32_bf16 v[72:75], v[224:227], v[196:199], v[72:75]
	ds_read_b128 v[208:211], v174 offset:32768
	v_mfma_f32_16x16x32_bf16 v[64:67], v[228:231], v[196:199], v[64:67]
	ds_read_b128 v[212:215], v174 offset:34816
	v_mfma_f32_16x16x32_bf16 v[76:79], v[232:235], v[196:199], v[76:79]
	ds_read_b128 v[216:219], v174 offset:36864
	v_mfma_f32_16x16x32_bf16 v[68:71], v[236:239], v[196:199], v[68:71]
	ds_read_b128 v[220:223], v174 offset:38912
	v_mfma_f32_16x16x32_bf16 v[40:43], v[224:227], v[200:203], v[40:43]
	v_mfma_f32_16x16x32_bf16 v[32:35], v[228:231], v[200:203], v[32:35]
	v_mfma_f32_16x16x32_bf16 v[44:47], v[232:235], v[200:203], v[44:47]
	v_mfma_f32_16x16x32_bf16 v[36:39], v[236:239], v[200:203], v[36:39]
	v_mfma_f32_16x16x32_bf16 v[8:11], v[224:227], v[204:207], v[8:11]
	v_mfma_f32_16x16x32_bf16 v[0:3], v[228:231], v[204:207], v[0:3]
	v_mfma_f32_16x16x32_bf16 v[12:15], v[232:235], v[204:207], v[12:15]
	v_mfma_f32_16x16x32_bf16 v[4:7], v[236:239], v[204:207], v[4:7]
	s_waitcnt lgkmcnt(0)
	s_nop 0
	v_mfma_f32_16x16x32_bf16 v[120:123], v[208:211], v[176:179], v[120:123]
	ds_read_b128 v[224:227], v174 offset:40960
	v_mfma_f32_16x16x32_bf16 v[112:115], v[212:215], v[176:179], v[112:115]
	ds_read_b128 v[228:231], v174 offset:43008
	v_mfma_f32_16x16x32_bf16 v[124:127], v[216:219], v[176:179], v[124:127]
	ds_read_b128 v[232:235], v174 offset:45056
	v_mfma_f32_16x16x32_bf16 v[116:119], v[220:223], v[176:179], v[116:119]
	ds_read_b128 v[236:239], v174 offset:47104
	v_mfma_f32_16x16x32_bf16 v[88:91], v[208:211], v[180:183], v[88:91]
	v_mfma_f32_16x16x32_bf16 v[80:83], v[212:215], v[180:183], v[80:83]
	v_mfma_f32_16x16x32_bf16 v[92:95], v[216:219], v[180:183], v[92:95]
	v_mfma_f32_16x16x32_bf16 v[84:87], v[220:223], v[180:183], v[84:87]
	v_mfma_f32_16x16x32_bf16 v[56:59], v[208:211], v[184:187], v[56:59]
	v_mfma_f32_16x16x32_bf16 v[48:51], v[212:215], v[184:187], v[48:51]
	v_mfma_f32_16x16x32_bf16 v[60:63], v[216:219], v[184:187], v[60:63]
	v_mfma_f32_16x16x32_bf16 v[52:55], v[220:223], v[184:187], v[52:55]
	v_mfma_f32_16x16x32_bf16 v[24:27], v[208:211], v[188:191], v[24:27]
	v_mfma_f32_16x16x32_bf16 v[16:19], v[212:215], v[188:191], v[16:19]
	v_mfma_f32_16x16x32_bf16 v[28:31], v[216:219], v[188:191], v[28:31]
	v_mfma_f32_16x16x32_bf16 v[20:23], v[220:223], v[188:191], v[20:23]
	s_waitcnt lgkmcnt(0)
	s_nop 0
	v_mfma_f32_16x16x32_bf16 v[104:107], v[224:227], v[176:179], v[104:107]
	ds_read_b128 v[192:195], v173 offset:0
	v_mfma_f32_16x16x32_bf16 v[96:99], v[228:231], v[176:179], v[96:99]
	ds_read_b128 v[196:199], v173 offset:2048
	v_mfma_f32_16x16x32_bf16 v[108:111], v[232:235], v[176:179], v[108:111]
	ds_read_b128 v[200:203], v173 offset:4096
	v_mfma_f32_16x16x32_bf16 v[100:103], v[236:239], v[176:179], v[100:103]
	ds_read_b128 v[204:207], v173 offset:6144
	v_mfma_f32_16x16x32_bf16 v[72:75], v[224:227], v[180:183], v[72:75]
	ds_read_b128 v[208:211], v175 offset:32768
	v_mfma_f32_16x16x32_bf16 v[64:67], v[228:231], v[180:183], v[64:67]
	ds_read_b128 v[212:215], v175 offset:34816
	v_mfma_f32_16x16x32_bf16 v[76:79], v[232:235], v[180:183], v[76:79]
	ds_read_b128 v[216:219], v175 offset:36864
	v_mfma_f32_16x16x32_bf16 v[68:71], v[236:239], v[180:183], v[68:71]
	ds_read_b128 v[220:223], v175 offset:38912
	v_mfma_f32_16x16x32_bf16 v[40:43], v[224:227], v[184:187], v[40:43]
	v_mfma_f32_16x16x32_bf16 v[32:35], v[228:231], v[184:187], v[32:35]
	v_mfma_f32_16x16x32_bf16 v[44:47], v[232:235], v[184:187], v[44:47]
	v_mfma_f32_16x16x32_bf16 v[36:39], v[236:239], v[184:187], v[36:39]
	v_mfma_f32_16x16x32_bf16 v[8:11], v[224:227], v[188:191], v[8:11]
	v_mfma_f32_16x16x32_bf16 v[0:3], v[228:231], v[188:191], v[0:3]
	v_mfma_f32_16x16x32_bf16 v[12:15], v[232:235], v[188:191], v[12:15]
	v_mfma_f32_16x16x32_bf16 v[4:7], v[236:239], v[188:191], v[4:7]
	s_waitcnt lgkmcnt(0)
	s_nop 0
	v_mfma_f32_16x16x32_bf16 v[120:123], v[208:211], v[192:195], v[120:123]
	ds_read_b128 v[224:227], v175 offset:40960
	v_mfma_f32_16x16x32_bf16 v[112:115], v[212:215], v[192:195], v[112:115]
	ds_read_b128 v[228:231], v175 offset:43008
	v_mfma_f32_16x16x32_bf16 v[124:127], v[216:219], v[192:195], v[124:127]
	ds_read_b128 v[232:235], v175 offset:45056
	v_mfma_f32_16x16x32_bf16 v[116:119], v[220:223], v[192:195], v[116:119]
	ds_read_b128 v[236:239], v175 offset:47104
	v_mfma_f32_16x16x32_bf16 v[88:91], v[208:211], v[196:199], v[88:91]
	v_mfma_f32_16x16x32_bf16 v[80:83], v[212:215], v[196:199], v[80:83]
	v_mfma_f32_16x16x32_bf16 v[92:95], v[216:219], v[196:199], v[92:95]
	v_mfma_f32_16x16x32_bf16 v[84:87], v[220:223], v[196:199], v[84:87]
	v_mfma_f32_16x16x32_bf16 v[56:59], v[208:211], v[200:203], v[56:59]
	v_mfma_f32_16x16x32_bf16 v[48:51], v[212:215], v[200:203], v[48:51]
	v_mfma_f32_16x16x32_bf16 v[60:63], v[216:219], v[200:203], v[60:63]
	v_mfma_f32_16x16x32_bf16 v[52:55], v[220:223], v[200:203], v[52:55]
	v_mfma_f32_16x16x32_bf16 v[24:27], v[208:211], v[204:207], v[24:27]
	v_mfma_f32_16x16x32_bf16 v[16:19], v[212:215], v[204:207], v[16:19]
	v_mfma_f32_16x16x32_bf16 v[28:31], v[216:219], v[204:207], v[28:31]
	v_mfma_f32_16x16x32_bf16 v[20:23], v[220:223], v[204:207], v[20:23]
	s_waitcnt lgkmcnt(0)
	s_barrier
	v_mfma_f32_16x16x32_bf16 v[104:107], v[224:227], v[192:195], v[104:107]
	v_mfma_f32_16x16x32_bf16 v[96:99], v[228:231], v[192:195], v[96:99]
	v_mfma_f32_16x16x32_bf16 v[108:111], v[232:235], v[192:195], v[108:111]
	v_mfma_f32_16x16x32_bf16 v[100:103], v[236:239], v[192:195], v[100:103]
	v_mfma_f32_16x16x32_bf16 v[72:75], v[224:227], v[196:199], v[72:75]
	v_mfma_f32_16x16x32_bf16 v[64:67], v[228:231], v[196:199], v[64:67]
	v_mfma_f32_16x16x32_bf16 v[76:79], v[232:235], v[196:199], v[76:79]
	v_mfma_f32_16x16x32_bf16 v[68:71], v[236:239], v[196:199], v[68:71]
	v_mfma_f32_16x16x32_bf16 v[40:43], v[224:227], v[200:203], v[40:43]
	v_mfma_f32_16x16x32_bf16 v[32:35], v[228:231], v[200:203], v[32:35]
	v_mfma_f32_16x16x32_bf16 v[44:47], v[232:235], v[200:203], v[44:47]
	v_mfma_f32_16x16x32_bf16 v[36:39], v[236:239], v[200:203], v[36:39]
	v_mfma_f32_16x16x32_bf16 v[8:11], v[224:227], v[204:207], v[8:11]
	v_mfma_f32_16x16x32_bf16 v[0:3], v[228:231], v[204:207], v[0:3]
	v_mfma_f32_16x16x32_bf16 v[12:15], v[232:235], v[204:207], v[12:15]
	v_mfma_f32_16x16x32_bf16 v[4:7], v[236:239], v[204:207], v[4:7]
	s_nop 7
	s_nop 3
	s_branch .LBB0_115

.LBB0_1104:
	v_mov_b64_e32 v[0:1], v[132:133]
	v_mov_b64_e32 v[2:3], v[132:133]
	v_mov_b32_e32 v4, v154
	s_lshl_b32 s6, s93, 8
	v_lshrrev_b32_e32 v6, 4, v4
	v_lshl_add_u64 v[0:1], v[0:1], 0, s[22:23]
	v_ashrrev_i32_e32 v7, 3, v4
	v_xor_b32_e32 v8, v6, v4
	v_add_u32_e32 v9, s6, v7
	v_lshlrev_b32_e32 v8, 4, v8
	s_lshl_b32 s7, s89, 8
	v_mad_i64_i32 v[0:1], s[4:5], v9, s50, v[0:1]
	v_and_b32_e32 v134, 0x70, v8
	v_lshl_add_u64 v[128:129], v[0:1], 0, v[134:135]
	v_add_u32_e32 v0, s7, v7
	v_ashrrev_i32_e32 v1, 31, v0
	v_lshl_add_u64 v[2:3], v[2:3], 0, s[16:17]
	v_lshlrev_b64 v[0:1], 11, v[0:1]
	v_ashrrev_i32_e32 v5, 6, v4
	v_lshl_add_u64 v[0:1], v[2:3], 0, v[0:1]
	v_lshl_add_u64 v[130:131], v[0:1], 0, v[134:135]
	v_ashrrev_i32_e32 v0, 1, v4
	v_and_b32_e32 v134, 0xffffffc0, v0
	v_lshlrev_b32_e32 v0, 7, v5
	v_and_b32_e32 v143, 0x80, v0
	v_lshlrev_b32_e32 v0, 10, v5
	v_add_u32_e32 v144, 0, v0
	v_add_u32_e32 v145, s79, v0
	v_readfirstlane_b32 s4, v144
	s_mov_b32 m0, s4
	v_readfirstlane_b32 s4, v145
	global_load_lds_dwordx4 v[128:129], off
	s_mov_b32 m0, s4
	s_mov_b64 s[4:5], 0x6c000
	v_add_u32_e32 v146, 0x2000, v144
	v_lshl_add_u64 v[0:1], v[128:129], 0, s[4:5]
	v_readfirstlane_b32 s4, v146
	global_load_lds_dwordx4 v[130:131], off
	s_mov_b32 m0, s4
	s_mov_b64 s[4:5], 0x20000
	v_add_u32_e32 v147, 0x2000, v145
	global_load_lds_dwordx4 v[0:1], off
	v_lshl_add_u64 v[0:1], v[130:131], 0, s[4:5]
	v_readfirstlane_b32 s4, v147
	s_mov_b32 m0, s4
	s_mov_b64 s[4:5], 0xd8000
	v_add_u32_e32 v148, 0x4000, v144
	global_load_lds_dwordx4 v[0:1], off
	v_lshl_add_u64 v[0:1], v[128:129], 0, s[4:5]
	v_readfirstlane_b32 s4, v148
	s_mov_b32 m0, s4
	s_mov_b64 s[4:5], 0x40000
	v_add_u32_e32 v149, 0x4000, v145
	global_load_lds_dwordx4 v[0:1], off
	v_lshl_add_u64 v[0:1], v[130:131], 0, s[4:5]
	v_readfirstlane_b32 s4, v149
	s_mov_b32 m0, s4
	s_mov_b64 s[4:5], 0x144000
	v_add_u32_e32 v151, 0x6000, v144
	global_load_lds_dwordx4 v[0:1], off
	v_lshl_add_u64 v[0:1], v[128:129], 0, s[4:5]
	v_readfirstlane_b32 s4, v151
	s_mov_b32 m0, s4
	s_mov_b64 s[4:5], 0x60000
	v_add_u32_e32 v152, 0x6000, v145
	global_load_lds_dwordx4 v[0:1], off
	v_lshl_add_u64 v[0:1], v[130:131], 0, s[4:5]
	v_readfirstlane_b32 s4, v152
	s_mov_b32 m0, s4
	v_bfe_u32 v150, v4, 4, 2
	global_load_lds_dwordx4 v[0:1], off
	s_mov_b64 s[100:101], 0x80
	v_lshl_add_u64 v[240:241], v[128:129], 0, s[100:101]
	s_mov_b64 s[100:101], 0x6c080
	v_lshl_add_u64 v[242:243], v[128:129], 0, s[100:101]
	s_mov_b64 s[100:101], 0xd8080
	v_lshl_add_u64 v[244:245], v[128:129], 0, s[100:101]
	s_mov_b64 s[100:101], 0x144080
	v_lshl_add_u64 v[246:247], v[128:129], 0, s[100:101]
	s_mov_b64 s[100:101], 0x80
	v_lshl_add_u64 v[138:139], v[130:131], 0, s[100:101]
	s_mov_b64 s[100:101], 0x20080
	v_lshl_add_u64 v[140:141], v[130:131], 0, s[100:101]
	s_mov_b64 s[100:101], 0x40080
	v_lshl_add_u64 v[250:251], v[130:131], 0, s[100:101]
	s_mov_b64 s[100:101], 0x60080
	v_lshl_add_u64 v[252:253], v[130:131], 0, s[100:101]
	v_readfirstlane_b32 s100, v144
	v_readfirstlane_b32 s101, v145
	s_nop 3
	s_add_u32 m0, s100, 0x8000
	s_nop 0
	global_load_lds_dwordx4 v[240:241], off
	v_lshl_add_u64 v[240:241], v[240:241], 0, s[34:35]
	s_add_u32 m0, s100, 0xa000
	s_nop 0
	global_load_lds_dwordx4 v[242:243], off
	v_lshl_add_u64 v[242:243], v[242:243], 0, s[34:35]
	s_add_u32 m0, s100, 0xc000
	s_nop 0
	global_load_lds_dwordx4 v[244:245], off
	v_lshl_add_u64 v[244:245], v[244:245], 0, s[34:35]
	s_add_u32 m0, s100, 0xe000
	s_nop 0
	global_load_lds_dwordx4 v[246:247], off
	v_lshl_add_u64 v[246:247], v[246:247], 0, s[34:35]
	s_add_u32 m0, s101, 0x8000
	s_nop 0
	global_load_lds_dwordx4 v[138:139], off
	v_lshl_add_u64 v[138:139], v[138:139], 0, s[34:35]
	s_add_u32 m0, s101, 0xa000
	s_nop 0
	global_load_lds_dwordx4 v[140:141], off
	v_lshl_add_u64 v[140:141], v[140:141], 0, s[34:35]
	s_add_u32 m0, s101, 0xc000
	s_nop 0
	global_load_lds_dwordx4 v[250:251], off
	v_lshl_add_u64 v[250:251], v[250:251], 0, s[34:35]
	s_add_u32 m0, s101, 0xe000
	s_nop 0
	global_load_lds_dwordx4 v[252:253], off
	v_lshl_add_u64 v[252:253], v[252:253], 0, s[34:35]
	s_add_u32 m0, s100, 0x20000
	s_nop 0
	global_load_lds_dwordx4 v[240:241], off
	v_lshl_add_u64 v[240:241], v[240:241], 0, s[34:35]
	s_add_u32 m0, s100, 0x22000
	s_nop 0
	global_load_lds_dwordx4 v[242:243], off
	v_lshl_add_u64 v[242:243], v[242:243], 0, s[34:35]
	s_add_u32 m0, s100, 0x24000
	s_nop 0
	global_load_lds_dwordx4 v[244:245], off
	v_lshl_add_u64 v[244:245], v[244:245], 0, s[34:35]
	s_add_u32 m0, s100, 0x26000
	s_nop 0
	global_load_lds_dwordx4 v[246:247], off
	v_lshl_add_u64 v[246:247], v[246:247], 0, s[34:35]
	v_bfe_u32 v0, v4, 1, 3
	v_and_b32_e32 v142, 15, v4
	v_bitop3_b32 v1, v6, v0, 3 bitop3:0x6c
	v_bitop3_b32 v0, v150, v0, 4 bitop3:0x36
	v_or_b32_e32 v2, v134, v142
	v_or_b32_e32 v3, v143, v142
	v_lshlrev_b32_e32 v171, 4, v0
	v_lshl_add_u32 v153, v2, 7, 0
	v_lshl_add_u32 v169, v3, 7, s79
	v_lshlrev_b32_e32 v170, 4, v1
	s_mov_b64 s[4:5], 0
	s_waitcnt vmcnt(12)
	s_waitcnt lgkmcnt(0)
	s_barrier
	s_branch .LBB0_1106
	s_nop 0
.LBB0_1106:
	v_add_u32_e32 v172, v153, v170
	v_add_u32_e32 v173, v153, v171
	v_add_u32_e32 v174, v169, v170
	v_add_u32_e32 v175, v169, v171
	v_add_u32_e32 v254, 0x20000, v172
	v_add_u32_e32 v255, 0x20000, v173
	s_nop 1
	s_nop 0
	ds_read_b128 v[176:179], v172 offset:0
	ds_read_b128 v[180:183], v172 offset:2048
	ds_read_b128 v[184:187], v172 offset:4096
	ds_read_b128 v[188:191], v172 offset:6144
	ds_read_b128 v[208:211], v174 offset:0
	ds_read_b128 v[212:215], v174 offset:2048
	ds_read_b128 v[216:219], v174 offset:4096
	ds_read_b128 v[220:223], v174 offset:6144
	s_waitcnt lgkmcnt(0)
	s_nop 0
	v_mfma_f32_16x16x32_bf16 v[124:127], v[208:211], v[176:179], 0
	ds_read_b128 v[224:227], v174 offset:8192
	v_mfma_f32_16x16x32_bf16 v[120:123], v[212:215], v[176:179], 0
	ds_read_b128 v[228:231], v174 offset:10240
	v_mfma_f32_16x16x32_bf16 v[116:119], v[216:219], v[176:179], 0
	ds_read_b128 v[232:235], v174 offset:12288
	v_mfma_f32_16x16x32_bf16 v[112:115], v[220:223], v[176:179], 0
	ds_read_b128 v[236:239], v174 offset:14336
	v_mfma_f32_16x16x32_bf16 v[92:95], v[208:211], v[180:183], 0
	v_mfma_f32_16x16x32_bf16 v[88:91], v[212:215], v[180:183], 0
	v_mfma_f32_16x16x32_bf16 v[84:87], v[216:219], v[180:183], 0
	v_mfma_f32_16x16x32_bf16 v[80:83], v[220:223], v[180:183], 0
	v_mfma_f32_16x16x32_bf16 v[60:63], v[208:211], v[184:187], 0
	v_mfma_f32_16x16x32_bf16 v[56:59], v[212:215], v[184:187], 0
	v_mfma_f32_16x16x32_bf16 v[52:55], v[216:219], v[184:187], 0
	v_mfma_f32_16x16x32_bf16 v[48:51], v[220:223], v[184:187], 0
	v_mfma_f32_16x16x32_bf16 v[28:31], v[208:211], v[188:191], 0
	v_mfma_f32_16x16x32_bf16 v[24:27], v[212:215], v[188:191], 0
	v_mfma_f32_16x16x32_bf16 v[20:23], v[216:219], v[188:191], 0
	v_mfma_f32_16x16x32_bf16 v[16:19], v[220:223], v[188:191], 0
	s_waitcnt lgkmcnt(0)
	s_nop 0
	v_mfma_f32_16x16x32_bf16 v[108:111], v[224:227], v[176:179], 0
	ds_read_b128 v[192:195], v173 offset:0
	v_mfma_f32_16x16x32_bf16 v[104:107], v[228:231], v[176:179], 0
	ds_read_b128 v[196:199], v173 offset:2048
	v_mfma_f32_16x16x32_bf16 v[100:103], v[232:235], v[176:179], 0
	ds_read_b128 v[200:203], v173 offset:4096
	v_mfma_f32_16x16x32_bf16 v[96:99], v[236:239], v[176:179], 0
	ds_read_b128 v[204:207], v173 offset:6144
	v_mfma_f32_16x16x32_bf16 v[76:79], v[224:227], v[180:183], 0
	ds_read_b128 v[208:211], v175 offset:0
	v_mfma_f32_16x16x32_bf16 v[72:75], v[228:231], v[180:183], 0
	ds_read_b128 v[212:215], v175 offset:2048
	v_mfma_f32_16x16x32_bf16 v[68:71], v[232:235], v[180:183], 0
	ds_read_b128 v[216:219], v175 offset:4096
	v_mfma_f32_16x16x32_bf16 v[64:67], v[236:239], v[180:183], 0
	ds_read_b128 v[220:223], v175 offset:6144
	v_mfma_f32_16x16x32_bf16 v[44:47], v[224:227], v[184:187], 0
	v_mfma_f32_16x16x32_bf16 v[40:43], v[228:231], v[184:187], 0
	v_mfma_f32_16x16x32_bf16 v[36:39], v[232:235], v[184:187], 0
	v_mfma_f32_16x16x32_bf16 v[32:35], v[236:239], v[184:187], 0
	v_mfma_f32_16x16x32_bf16 v[12:15], v[224:227], v[188:191], 0
	v_mfma_f32_16x16x32_bf16 v[8:11], v[228:231], v[188:191], 0
	v_mfma_f32_16x16x32_bf16 v[4:7], v[232:235], v[188:191], 0
	v_mfma_f32_16x16x32_bf16 v[0:3], v[236:239], v[188:191], 0
	s_waitcnt lgkmcnt(0)
	s_nop 0
	v_mfma_f32_16x16x32_bf16 v[124:127], v[208:211], v[192:195], v[124:127]
	ds_read_b128 v[224:227], v175 offset:8192
	v_mfma_f32_16x16x32_bf16 v[120:123], v[212:215], v[192:195], v[120:123]
	ds_read_b128 v[228:231], v175 offset:10240
	v_mfma_f32_16x16x32_bf16 v[116:119], v[216:219], v[192:195], v[116:119]
	ds_read_b128 v[232:235], v175 offset:12288
	v_mfma_f32_16x16x32_bf16 v[112:115], v[220:223], v[192:195], v[112:115]
	ds_read_b128 v[236:239], v175 offset:14336
	v_mfma_f32_16x16x32_bf16 v[92:95], v[208:211], v[196:199], v[92:95]
	v_mfma_f32_16x16x32_bf16 v[88:91], v[212:215], v[196:199], v[88:91]
	v_mfma_f32_16x16x32_bf16 v[84:87], v[216:219], v[196:199], v[84:87]
	v_mfma_f32_16x16x32_bf16 v[80:83], v[220:223], v[196:199], v[80:83]
	v_mfma_f32_16x16x32_bf16 v[60:63], v[208:211], v[200:203], v[60:63]
	v_mfma_f32_16x16x32_bf16 v[56:59], v[212:215], v[200:203], v[56:59]
	v_mfma_f32_16x16x32_bf16 v[52:55], v[216:219], v[200:203], v[52:55]
	v_mfma_f32_16x16x32_bf16 v[48:51], v[220:223], v[200:203], v[48:51]
	v_mfma_f32_16x16x32_bf16 v[28:31], v[208:211], v[204:207], v[28:31]
	v_mfma_f32_16x16x32_bf16 v[24:27], v[212:215], v[204:207], v[24:27]
	v_mfma_f32_16x16x32_bf16 v[20:23], v[216:219], v[204:207], v[20:23]
	v_mfma_f32_16x16x32_bf16 v[16:19], v[220:223], v[204:207], v[16:19]
	s_waitcnt lgkmcnt(0)
	s_waitcnt vmcnt(4)
	s_barrier
	s_mov_b32 s46, 2
.Lgemm_p7_loop:
	v_mfma_f32_16x16x32_bf16 v[108:111], v[224:227], v[192:195], v[108:111]
	ds_read_b128 v[176:179], v172 offset:32768
	s_mov_b32 m0, s101
	s_nop 0
	v_mfma_f32_16x16x32_bf16 v[104:107], v[228:231], v[192:195], v[104:107]
	ds_read_b128 v[180:183], v172 offset:34816
	global_load_lds_dwordx4 v[138:139], off
	v_lshl_add_u64 v[138:139], v[138:139], 0, s[34:35]
	v_mfma_f32_16x16x32_bf16 v[100:103], v[232:235], v[192:195], v[100:103]
	ds_read_b128 v[184:187], v172 offset:36864
	s_add_u32 m0, s101, 0x2000
	v_mfma_f32_16x16x32_bf16 v[96:99], v[236:239], v[192:195], v[96:99]
	ds_read_b128 v[188:191], v172 offset:38912
	global_load_lds_dwordx4 v[140:141], off
	v_lshl_add_u64 v[140:141], v[140:141], 0, s[34:35]
	v_mfma_f32_16x16x32_bf16 v[76:79], v[224:227], v[196:199], v[76:79]
	ds_read_b128 v[208:211], v174 offset:32768
	s_add_u32 m0, s101, 0x4000
	v_mfma_f32_16x16x32_bf16 v[72:75], v[228:231], v[196:199], v[72:75]
	ds_read_b128 v[212:215], v174 offset:34816
	global_load_lds_dwordx4 v[250:251], off
	v_lshl_add_u64 v[250:251], v[250:251], 0, s[34:35]
	v_mfma_f32_16x16x32_bf16 v[68:71], v[232:235], v[196:199], v[68:71]
	ds_read_b128 v[216:219], v174 offset:36864
	s_add_u32 m0, s101, 0x6000
	v_mfma_f32_16x16x32_bf16 v[64:67], v[236:239], v[196:199], v[64:67]
	ds_read_b128 v[220:223], v174 offset:38912
	global_load_lds_dwordx4 v[252:253], off
	v_lshl_add_u64 v[252:253], v[252:253], 0, s[34:35]
	v_mfma_f32_16x16x32_bf16 v[44:47], v[224:227], v[200:203], v[44:47]
	v_mfma_f32_16x16x32_bf16 v[40:43], v[228:231], v[200:203], v[40:43]
	v_mfma_f32_16x16x32_bf16 v[36:39], v[232:235], v[200:203], v[36:39]
	v_mfma_f32_16x16x32_bf16 v[32:35], v[236:239], v[200:203], v[32:35]
	v_mfma_f32_16x16x32_bf16 v[12:15], v[224:227], v[204:207], v[12:15]
	v_mfma_f32_16x16x32_bf16 v[8:11], v[228:231], v[204:207], v[8:11]
	v_mfma_f32_16x16x32_bf16 v[4:7], v[232:235], v[204:207], v[4:7]
	v_mfma_f32_16x16x32_bf16 v[0:3], v[236:239], v[204:207], v[0:3]
	s_waitcnt lgkmcnt(0)
	s_nop 0
	v_mfma_f32_16x16x32_bf16 v[124:127], v[208:211], v[176:179], v[124:127]
	ds_read_b128 v[224:227], v174 offset:40960
	v_mfma_f32_16x16x32_bf16 v[120:123], v[212:215], v[176:179], v[120:123]
	ds_read_b128 v[228:231], v174 offset:43008
	v_mfma_f32_16x16x32_bf16 v[116:119], v[216:219], v[176:179], v[116:119]
	ds_read_b128 v[232:235], v174 offset:45056
	v_mfma_f32_16x16x32_bf16 v[112:115], v[220:223], v[176:179], v[112:115]
	ds_read_b128 v[236:239], v174 offset:47104
	v_mfma_f32_16x16x32_bf16 v[92:95], v[208:211], v[180:183], v[92:95]
	s_mov_b32 m0, s100
	s_nop 0
	v_mfma_f32_16x16x32_bf16 v[88:91], v[212:215], v[180:183], v[88:91]
	global_load_lds_dwordx4 v[240:241], off
	v_lshl_add_u64 v[240:241], v[240:241], 0, s[34:35]
	v_mfma_f32_16x16x32_bf16 v[84:87], v[216:219], v[180:183], v[84:87]
	s_add_u32 m0, s100, 0x2000
	v_mfma_f32_16x16x32_bf16 v[80:83], v[220:223], v[180:183], v[80:83]
	global_load_lds_dwordx4 v[242:243], off
	v_lshl_add_u64 v[242:243], v[242:243], 0, s[34:35]
	v_mfma_f32_16x16x32_bf16 v[60:63], v[208:211], v[184:187], v[60:63]
	s_add_u32 m0, s100, 0x4000
	v_mfma_f32_16x16x32_bf16 v[56:59], v[212:215], v[184:187], v[56:59]
	global_load_lds_dwordx4 v[244:245], off
	v_lshl_add_u64 v[244:245], v[244:245], 0, s[34:35]
	v_mfma_f32_16x16x32_bf16 v[52:55], v[216:219], v[184:187], v[52:55]
	s_add_u32 m0, s100, 0x6000
	v_mfma_f32_16x16x32_bf16 v[48:51], v[220:223], v[184:187], v[48:51]
	global_load_lds_dwordx4 v[246:247], off
	v_lshl_add_u64 v[246:247], v[246:247], 0, s[34:35]
	v_mfma_f32_16x16x32_bf16 v[28:31], v[208:211], v[188:191], v[28:31]
	v_mfma_f32_16x16x32_bf16 v[24:27], v[212:215], v[188:191], v[24:27]
	v_mfma_f32_16x16x32_bf16 v[20:23], v[216:219], v[188:191], v[20:23]
	v_mfma_f32_16x16x32_bf16 v[16:19], v[220:223], v[188:191], v[16:19]
	s_waitcnt lgkmcnt(0)
	s_nop 0
	v_mfma_f32_16x16x32_bf16 v[108:111], v[224:227], v[176:179], v[108:111]
	ds_read_b128 v[192:195], v173 offset:32768
	v_mfma_f32_16x16x32_bf16 v[104:107], v[228:231], v[176:179], v[104:107]
	ds_read_b128 v[196:199], v173 offset:34816
	v_mfma_f32_16x16x32_bf16 v[100:103], v[232:235], v[176:179], v[100:103]
	ds_read_b128 v[200:203], v173 offset:36864
	v_mfma_f32_16x16x32_bf16 v[96:99], v[236:239], v[176:179], v[96:99]
	ds_read_b128 v[204:207], v173 offset:38912
	v_mfma_f32_16x16x32_bf16 v[76:79], v[224:227], v[180:183], v[76:79]
	ds_read_b128 v[208:211], v175 offset:32768
	v_mfma_f32_16x16x32_bf16 v[72:75], v[228:231], v[180:183], v[72:75]
	ds_read_b128 v[212:215], v175 offset:34816
	v_mfma_f32_16x16x32_bf16 v[68:71], v[232:235], v[180:183], v[68:71]
	ds_read_b128 v[216:219], v175 offset:36864
	v_mfma_f32_16x16x32_bf16 v[64:67], v[236:239], v[180:183], v[64:67]
	ds_read_b128 v[220:223], v175 offset:38912
	v_mfma_f32_16x16x32_bf16 v[44:47], v[224:227], v[184:187], v[44:47]
	v_mfma_f32_16x16x32_bf16 v[40:43], v[228:231], v[184:187], v[40:43]
	v_mfma_f32_16x16x32_bf16 v[36:39], v[232:235], v[184:187], v[36:39]
	v_mfma_f32_16x16x32_bf16 v[32:35], v[236:239], v[184:187], v[32:35]
	v_mfma_f32_16x16x32_bf16 v[12:15], v[224:227], v[188:191], v[12:15]
	v_mfma_f32_16x16x32_bf16 v[8:11], v[228:231], v[188:191], v[8:11]
	v_mfma_f32_16x16x32_bf16 v[4:7], v[232:235], v[188:191], v[4:7]
	v_mfma_f32_16x16x32_bf16 v[0:3], v[236:239], v[188:191], v[0:3]
	s_waitcnt lgkmcnt(0)
	s_nop 0
	v_mfma_f32_16x16x32_bf16 v[124:127], v[208:211], v[192:195], v[124:127]
	ds_read_b128 v[224:227], v175 offset:40960
	v_mfma_f32_16x16x32_bf16 v[120:123], v[212:215], v[192:195], v[120:123]
	ds_read_b128 v[228:231], v175 offset:43008
	v_mfma_f32_16x16x32_bf16 v[116:119], v[216:219], v[192:195], v[116:119]
	ds_read_b128 v[232:235], v175 offset:45056
	v_mfma_f32_16x16x32_bf16 v[112:115], v[220:223], v[192:195], v[112:115]
	ds_read_b128 v[236:239], v175 offset:47104
	v_mfma_f32_16x16x32_bf16 v[92:95], v[208:211], v[196:199], v[92:95]
	v_mfma_f32_16x16x32_bf16 v[88:91], v[212:215], v[196:199], v[88:91]
	v_mfma_f32_16x16x32_bf16 v[84:87], v[216:219], v[196:199], v[84:87]
	v_mfma_f32_16x16x32_bf16 v[80:83], v[220:223], v[196:199], v[80:83]
	v_mfma_f32_16x16x32_bf16 v[60:63], v[208:211], v[200:203], v[60:63]
	v_mfma_f32_16x16x32_bf16 v[56:59], v[212:215], v[200:203], v[56:59]
	v_mfma_f32_16x16x32_bf16 v[52:55], v[216:219], v[200:203], v[52:55]
	v_mfma_f32_16x16x32_bf16 v[48:51], v[220:223], v[200:203], v[48:51]
	v_mfma_f32_16x16x32_bf16 v[28:31], v[208:211], v[204:207], v[28:31]
	v_mfma_f32_16x16x32_bf16 v[24:27], v[212:215], v[204:207], v[24:27]
	v_mfma_f32_16x16x32_bf16 v[20:23], v[216:219], v[204:207], v[20:23]
	v_mfma_f32_16x16x32_bf16 v[16:19], v[220:223], v[204:207], v[16:19]
	s_waitcnt lgkmcnt(0)
	s_waitcnt vmcnt(4)
	s_barrier
	s_nop 0
	v_mfma_f32_16x16x32_bf16 v[108:111], v[224:227], v[192:195], v[108:111]
	ds_read_b128 v[176:179], v254 offset:0
	s_add_u32 m0, s101, 0x8000
	v_mfma_f32_16x16x32_bf16 v[104:107], v[228:231], v[192:195], v[104:107]
	ds_read_b128 v[180:183], v254 offset:2048
	global_load_lds_dwordx4 v[138:139], off
	v_lshl_add_u64 v[138:139], v[138:139], 0, s[34:35]
	v_mfma_f32_16x16x32_bf16 v[100:103], v[232:235], v[192:195], v[100:103]
	ds_read_b128 v[184:187], v254 offset:4096
	s_add_u32 m0, s101, 0xa000
	v_mfma_f32_16x16x32_bf16 v[96:99], v[236:239], v[192:195], v[96:99]
	ds_read_b128 v[188:191], v254 offset:6144
	global_load_lds_dwordx4 v[140:141], off
	v_lshl_add_u64 v[140:141], v[140:141], 0, s[34:35]
	v_mfma_f32_16x16x32_bf16 v[76:79], v[224:227], v[196:199], v[76:79]
	ds_read_b128 v[208:211], v174 offset:0
	s_add_u32 m0, s101, 0xc000
	v_mfma_f32_16x16x32_bf16 v[72:75], v[228:231], v[196:199], v[72:75]
	ds_read_b128 v[212:215], v174 offset:2048
	global_load_lds_dwordx4 v[250:251], off
	v_lshl_add_u64 v[250:251], v[250:251], 0, s[34:35]
	v_mfma_f32_16x16x32_bf16 v[68:71], v[232:235], v[196:199], v[68:71]
	ds_read_b128 v[216:219], v174 offset:4096
	s_add_u32 m0, s101, 0xe000
	v_mfma_f32_16x16x32_bf16 v[64:67], v[236:239], v[196:199], v[64:67]
	ds_read_b128 v[220:223], v174 offset:6144
	global_load_lds_dwordx4 v[252:253], off
	v_lshl_add_u64 v[252:253], v[252:253], 0, s[34:35]
	v_mfma_f32_16x16x32_bf16 v[44:47], v[224:227], v[200:203], v[44:47]
	v_mfma_f32_16x16x32_bf16 v[40:43], v[228:231], v[200:203], v[40:43]
	v_mfma_f32_16x16x32_bf16 v[36:39], v[232:235], v[200:203], v[36:39]
	v_mfma_f32_16x16x32_bf16 v[32:35], v[236:239], v[200:203], v[32:35]
	v_mfma_f32_16x16x32_bf16 v[12:15], v[224:227], v[204:207], v[12:15]
	v_mfma_f32_16x16x32_bf16 v[8:11], v[228:231], v[204:207], v[8:11]
	v_mfma_f32_16x16x32_bf16 v[4:7], v[232:235], v[204:207], v[4:7]
	v_mfma_f32_16x16x32_bf16 v[0:3], v[236:239], v[204:207], v[0:3]
	s_waitcnt lgkmcnt(0)
	s_nop 0
	v_mfma_f32_16x16x32_bf16 v[124:127], v[208:211], v[176:179], v[124:127]
	ds_read_b128 v[224:227], v174 offset:8192
	v_mfma_f32_16x16x32_bf16 v[120:123], v[212:215], v[176:179], v[120:123]
	ds_read_b128 v[228:231], v174 offset:10240
	v_mfma_f32_16x16x32_bf16 v[116:119], v[216:219], v[176:179], v[116:119]
	ds_read_b128 v[232:235], v174 offset:12288
	v_mfma_f32_16x16x32_bf16 v[112:115], v[220:223], v[176:179], v[112:115]
	ds_read_b128 v[236:239], v174 offset:14336
	v_mfma_f32_16x16x32_bf16 v[92:95], v[208:211], v[180:183], v[92:95]
	s_add_u32 m0, s100, 0x8000
	v_mfma_f32_16x16x32_bf16 v[88:91], v[212:215], v[180:183], v[88:91]
	global_load_lds_dwordx4 v[240:241], off
	v_lshl_add_u64 v[240:241], v[240:241], 0, s[34:35]
	v_mfma_f32_16x16x32_bf16 v[84:87], v[216:219], v[180:183], v[84:87]
	s_add_u32 m0, s100, 0xa000
	v_mfma_f32_16x16x32_bf16 v[80:83], v[220:223], v[180:183], v[80:83]
	global_load_lds_dwordx4 v[242:243], off
	v_lshl_add_u64 v[242:243], v[242:243], 0, s[34:35]
	v_mfma_f32_16x16x32_bf16 v[60:63], v[208:211], v[184:187], v[60:63]
	s_add_u32 m0, s100, 0xc000
	v_mfma_f32_16x16x32_bf16 v[56:59], v[212:215], v[184:187], v[56:59]
	global_load_lds_dwordx4 v[244:245], off
	v_lshl_add_u64 v[244:245], v[244:245], 0, s[34:35]
	v_mfma_f32_16x16x32_bf16 v[52:55], v[216:219], v[184:187], v[52:55]
	s_add_u32 m0, s100, 0xe000
	v_mfma_f32_16x16x32_bf16 v[48:51], v[220:223], v[184:187], v[48:51]
	global_load_lds_dwordx4 v[246:247], off
	v_lshl_add_u64 v[246:247], v[246:247], 0, s[34:35]
	v_mfma_f32_16x16x32_bf16 v[28:31], v[208:211], v[188:191], v[28:31]
	v_mfma_f32_16x16x32_bf16 v[24:27], v[212:215], v[188:191], v[24:27]
	v_mfma_f32_16x16x32_bf16 v[20:23], v[216:219], v[188:191], v[20:23]
	v_mfma_f32_16x16x32_bf16 v[16:19], v[220:223], v[188:191], v[16:19]
	s_waitcnt lgkmcnt(0)
	s_nop 0
	v_mfma_f32_16x16x32_bf16 v[108:111], v[224:227], v[176:179], v[108:111]
	ds_read_b128 v[192:195], v255 offset:0
	v_mfma_f32_16x16x32_bf16 v[104:107], v[228:231], v[176:179], v[104:107]
	ds_read_b128 v[196:199], v255 offset:2048
	v_mfma_f32_16x16x32_bf16 v[100:103], v[232:235], v[176:179], v[100:103]
	ds_read_b128 v[200:203], v255 offset:4096
	v_mfma_f32_16x16x32_bf16 v[96:99], v[236:239], v[176:179], v[96:99]
	ds_read_b128 v[204:207], v255 offset:6144
	v_mfma_f32_16x16x32_bf16 v[76:79], v[224:227], v[180:183], v[76:79]
	ds_read_b128 v[208:211], v175 offset:0
	v_mfma_f32_16x16x32_bf16 v[72:75], v[228:231], v[180:183], v[72:75]
	ds_read_b128 v[212:215], v175 offset:2048
	v_mfma_f32_16x16x32_bf16 v[68:71], v[232:235], v[180:183], v[68:71]
	ds_read_b128 v[216:219], v175 offset:4096
	v_mfma_f32_16x16x32_bf16 v[64:67], v[236:239], v[180:183], v[64:67]
	ds_read_b128 v[220:223], v175 offset:6144
	v_mfma_f32_16x16x32_bf16 v[44:47], v[224:227], v[184:187], v[44:47]
	v_mfma_f32_16x16x32_bf16 v[40:43], v[228:231], v[184:187], v[40:43]
	v_mfma_f32_16x16x32_bf16 v[36:39], v[232:235], v[184:187], v[36:39]
	v_mfma_f32_16x16x32_bf16 v[32:35], v[236:239], v[184:187], v[32:35]
	v_mfma_f32_16x16x32_bf16 v[12:15], v[224:227], v[188:191], v[12:15]
	v_mfma_f32_16x16x32_bf16 v[8:11], v[228:231], v[188:191], v[8:11]
	v_mfma_f32_16x16x32_bf16 v[4:7], v[232:235], v[188:191], v[4:7]
	v_mfma_f32_16x16x32_bf16 v[0:3], v[236:239], v[188:191], v[0:3]
	s_waitcnt lgkmcnt(0)
	s_nop 0
	v_mfma_f32_16x16x32_bf16 v[124:127], v[208:211], v[192:195], v[124:127]
	ds_read_b128 v[224:227], v175 offset:8192
	v_mfma_f32_16x16x32_bf16 v[120:123], v[212:215], v[192:195], v[120:123]
	ds_read_b128 v[228:231], v175 offset:10240
	v_mfma_f32_16x16x32_bf16 v[116:119], v[216:219], v[192:195], v[116:119]
	ds_read_b128 v[232:235], v175 offset:12288
	v_mfma_f32_16x16x32_bf16 v[112:115], v[220:223], v[192:195], v[112:115]
	ds_read_b128 v[236:239], v175 offset:14336
	v_mfma_f32_16x16x32_bf16 v[92:95], v[208:211], v[196:199], v[92:95]
	v_mfma_f32_16x16x32_bf16 v[88:91], v[212:215], v[196:199], v[88:91]
	v_mfma_f32_16x16x32_bf16 v[84:87], v[216:219], v[196:199], v[84:87]
	v_mfma_f32_16x16x32_bf16 v[80:83], v[220:223], v[196:199], v[80:83]
	v_mfma_f32_16x16x32_bf16 v[60:63], v[208:211], v[200:203], v[60:63]
	v_mfma_f32_16x16x32_bf16 v[56:59], v[212:215], v[200:203], v[56:59]
	v_mfma_f32_16x16x32_bf16 v[52:55], v[216:219], v[200:203], v[52:55]
	v_mfma_f32_16x16x32_bf16 v[48:51], v[220:223], v[200:203], v[48:51]
	v_mfma_f32_16x16x32_bf16 v[28:31], v[208:211], v[204:207], v[28:31]
	v_mfma_f32_16x16x32_bf16 v[24:27], v[212:215], v[204:207], v[24:27]
	v_mfma_f32_16x16x32_bf16 v[20:23], v[216:219], v[204:207], v[20:23]
	v_mfma_f32_16x16x32_bf16 v[16:19], v[220:223], v[204:207], v[16:19]
	s_waitcnt lgkmcnt(0)
	s_waitcnt vmcnt(4)
	s_barrier
	s_nop 0
	v_mfma_f32_16x16x32_bf16 v[108:111], v[224:227], v[192:195], v[108:111]
	ds_read_b128 v[176:179], v172 offset:0
	s_mov_b32 m0, s101
	s_nop 0
	v_mfma_f32_16x16x32_bf16 v[104:107], v[228:231], v[192:195], v[104:107]
	ds_read_b128 v[180:183], v172 offset:2048
	global_load_lds_dwordx4 v[138:139], off
	v_lshl_add_u64 v[138:139], v[138:139], 0, s[34:35]
	v_mfma_f32_16x16x32_bf16 v[100:103], v[232:235], v[192:195], v[100:103]
	ds_read_b128 v[184:187], v172 offset:4096
	s_add_u32 m0, s101, 0x2000
	v_mfma_f32_16x16x32_bf16 v[96:99], v[236:239], v[192:195], v[96:99]
	ds_read_b128 v[188:191], v172 offset:6144
	global_load_lds_dwordx4 v[140:141], off
	v_lshl_add_u64 v[140:141], v[140:141], 0, s[34:35]
	v_mfma_f32_16x16x32_bf16 v[76:79], v[224:227], v[196:199], v[76:79]
	ds_read_b128 v[208:211], v174 offset:32768
	s_add_u32 m0, s101, 0x4000
	v_mfma_f32_16x16x32_bf16 v[72:75], v[228:231], v[196:199], v[72:75]
	ds_read_b128 v[212:215], v174 offset:34816
	global_load_lds_dwordx4 v[250:251], off
	v_lshl_add_u64 v[250:251], v[250:251], 0, s[34:35]
	v_mfma_f32_16x16x32_bf16 v[68:71], v[232:235], v[196:199], v[68:71]
	ds_read_b128 v[216:219], v174 offset:36864
	s_add_u32 m0, s101, 0x6000
	v_mfma_f32_16x16x32_bf16 v[64:67], v[236:239], v[196:199], v[64:67]
	ds_read_b128 v[220:223], v174 offset:38912
	global_load_lds_dwordx4 v[252:253], off
	v_lshl_add_u64 v[252:253], v[252:253], 0, s[34:35]
	v_mfma_f32_16x16x32_bf16 v[44:47], v[224:227], v[200:203], v[44:47]
	v_mfma_f32_16x16x32_bf16 v[40:43], v[228:231], v[200:203], v[40:43]
	v_mfma_f32_16x16x32_bf16 v[36:39], v[232:235], v[200:203], v[36:39]
	v_mfma_f32_16x16x32_bf16 v[32:35], v[236:239], v[200:203], v[32:35]
	v_mfma_f32_16x16x32_bf16 v[12:15], v[224:227], v[204:207], v[12:15]
	v_mfma_f32_16x16x32_bf16 v[8:11], v[228:231], v[204:207], v[8:11]
	v_mfma_f32_16x16x32_bf16 v[4:7], v[232:235], v[204:207], v[4:7]
	v_mfma_f32_16x16x32_bf16 v[0:3], v[236:239], v[204:207], v[0:3]
	s_waitcnt lgkmcnt(0)
	s_nop 0
	v_mfma_f32_16x16x32_bf16 v[124:127], v[208:211], v[176:179], v[124:127]
	ds_read_b128 v[224:227], v174 offset:40960
	v_mfma_f32_16x16x32_bf16 v[120:123], v[212:215], v[176:179], v[120:123]
	ds_read_b128 v[228:231], v174 offset:43008
	v_mfma_f32_16x16x32_bf16 v[116:119], v[216:219], v[176:179], v[116:119]
	ds_read_b128 v[232:235], v174 offset:45056
	v_mfma_f32_16x16x32_bf16 v[112:115], v[220:223], v[176:179], v[112:115]
	ds_read_b128 v[236:239], v174 offset:47104
	v_mfma_f32_16x16x32_bf16 v[92:95], v[208:211], v[180:183], v[92:95]
	s_add_u32 m0, s100, 0x20000
	v_mfma_f32_16x16x32_bf16 v[88:91], v[212:215], v[180:183], v[88:91]
	global_load_lds_dwordx4 v[240:241], off
	v_lshl_add_u64 v[240:241], v[240:241], 0, s[34:35]
	v_mfma_f32_16x16x32_bf16 v[84:87], v[216:219], v[180:183], v[84:87]
	s_add_u32 m0, s100, 0x22000
	v_mfma_f32_16x16x32_bf16 v[80:83], v[220:223], v[180:183], v[80:83]
	global_load_lds_dwordx4 v[242:243], off
	v_lshl_add_u64 v[242:243], v[242:243], 0, s[34:35]
	v_mfma_f32_16x16x32_bf16 v[60:63], v[208:211], v[184:187], v[60:63]
	s_add_u32 m0, s100, 0x24000
	v_mfma_f32_16x16x32_bf16 v[56:59], v[212:215], v[184:187], v[56:59]
	global_load_lds_dwordx4 v[244:245], off
	v_lshl_add_u64 v[244:245], v[244:245], 0, s[34:35]
	v_mfma_f32_16x16x32_bf16 v[52:55], v[216:219], v[184:187], v[52:55]
	s_add_u32 m0, s100, 0x26000
	v_mfma_f32_16x16x32_bf16 v[48:51], v[220:223], v[184:187], v[48:51]
	global_load_lds_dwordx4 v[246:247], off
	v_lshl_add_u64 v[246:247], v[246:247], 0, s[34:35]
	v_mfma_f32_16x16x32_bf16 v[28:31], v[208:211], v[188:191], v[28:31]
	v_mfma_f32_16x16x32_bf16 v[24:27], v[212:215], v[188:191], v[24:27]
	v_mfma_f32_16x16x32_bf16 v[20:23], v[216:219], v[188:191], v[20:23]
	v_mfma_f32_16x16x32_bf16 v[16:19], v[220:223], v[188:191], v[16:19]
	s_waitcnt lgkmcnt(0)
	s_nop 0
	v_mfma_f32_16x16x32_bf16 v[108:111], v[224:227], v[176:179], v[108:111]
	ds_read_b128 v[192:195], v173 offset:0
	v_mfma_f32_16x16x32_bf16 v[104:107], v[228:231], v[176:179], v[104:107]
	ds_read_b128 v[196:199], v173 offset:2048
	v_mfma_f32_16x16x32_bf16 v[100:103], v[232:235], v[176:179], v[100:103]
	ds_read_b128 v[200:203], v173 offset:4096
	v_mfma_f32_16x16x32_bf16 v[96:99], v[236:239], v[176:179], v[96:99]
	ds_read_b128 v[204:207], v173 offset:6144
	v_mfma_f32_16x16x32_bf16 v[76:79], v[224:227], v[180:183], v[76:79]
	ds_read_b128 v[208:211], v175 offset:32768
	v_mfma_f32_16x16x32_bf16 v[72:75], v[228:231], v[180:183], v[72:75]
	ds_read_b128 v[212:215], v175 offset:34816
	v_mfma_f32_16x16x32_bf16 v[68:71], v[232:235], v[180:183], v[68:71]
	ds_read_b128 v[216:219], v175 offset:36864
	v_mfma_f32_16x16x32_bf16 v[64:67], v[236:239], v[180:183], v[64:67]
	ds_read_b128 v[220:223], v175 offset:38912
	v_mfma_f32_16x16x32_bf16 v[44:47], v[224:227], v[184:187], v[44:47]
	v_mfma_f32_16x16x32_bf16 v[40:43], v[228:231], v[184:187], v[40:43]
	v_mfma_f32_16x16x32_bf16 v[36:39], v[232:235], v[184:187], v[36:39]
	v_mfma_f32_16x16x32_bf16 v[32:35], v[236:239], v[184:187], v[32:35]
	v_mfma_f32_16x16x32_bf16 v[12:15], v[224:227], v[188:191], v[12:15]
	v_mfma_f32_16x16x32_bf16 v[8:11], v[228:231], v[188:191], v[8:11]
	v_mfma_f32_16x16x32_bf16 v[4:7], v[232:235], v[188:191], v[4:7]
	v_mfma_f32_16x16x32_bf16 v[0:3], v[236:239], v[188:191], v[0:3]
	s_waitcnt lgkmcnt(0)
	s_nop 0
	v_mfma_f32_16x16x32_bf16 v[124:127], v[208:211], v[192:195], v[124:127]
	ds_read_b128 v[224:227], v175 offset:40960
	v_mfma_f32_16x16x32_bf16 v[120:123], v[212:215], v[192:195], v[120:123]
	ds_read_b128 v[228:231], v175 offset:43008
	v_mfma_f32_16x16x32_bf16 v[116:119], v[216:219], v[192:195], v[116:119]
	ds_read_b128 v[232:235], v175 offset:45056
	v_mfma_f32_16x16x32_bf16 v[112:115], v[220:223], v[192:195], v[112:115]
	ds_read_b128 v[236:239], v175 offset:47104
	v_mfma_f32_16x16x32_bf16 v[92:95], v[208:211], v[196:199], v[92:95]
	v_mfma_f32_16x16x32_bf16 v[88:91], v[212:215], v[196:199], v[88:91]
	v_mfma_f32_16x16x32_bf16 v[84:87], v[216:219], v[196:199], v[84:87]
	v_mfma_f32_16x16x32_bf16 v[80:83], v[220:223], v[196:199], v[80:83]
	v_mfma_f32_16x16x32_bf16 v[60:63], v[208:211], v[200:203], v[60:63]
	v_mfma_f32_16x16x32_bf16 v[56:59], v[212:215], v[200:203], v[56:59]
	v_mfma_f32_16x16x32_bf16 v[52:55], v[216:219], v[200:203], v[52:55]
	v_mfma_f32_16x16x32_bf16 v[48:51], v[220:223], v[200:203], v[48:51]
	v_mfma_f32_16x16x32_bf16 v[28:31], v[208:211], v[204:207], v[28:31]
	v_mfma_f32_16x16x32_bf16 v[24:27], v[212:215], v[204:207], v[24:27]
	v_mfma_f32_16x16x32_bf16 v[20:23], v[216:219], v[204:207], v[20:23]
	v_mfma_f32_16x16x32_bf16 v[16:19], v[220:223], v[204:207], v[16:19]
	s_waitcnt lgkmcnt(0)
	s_waitcnt vmcnt(4)
	s_barrier
	s_nop 0
	v_mfma_f32_16x16x32_bf16 v[108:111], v[224:227], v[192:195], v[108:111]
	ds_read_b128 v[176:179], v172 offset:32768
	s_add_u32 m0, s101, 0x8000
	v_mfma_f32_16x16x32_bf16 v[104:107], v[228:231], v[192:195], v[104:107]
	ds_read_b128 v[180:183], v172 offset:34816
	global_load_lds_dwordx4 v[138:139], off
	v_lshl_add_u64 v[138:139], v[138:139], 0, s[34:35]
	v_mfma_f32_16x16x32_bf16 v[100:103], v[232:235], v[192:195], v[100:103]
	ds_read_b128 v[184:187], v172 offset:36864
	s_add_u32 m0, s101, 0xa000
	v_mfma_f32_16x16x32_bf16 v[96:99], v[236:239], v[192:195], v[96:99]
	ds_read_b128 v[188:191], v172 offset:38912
	global_load_lds_dwordx4 v[140:141], off
	v_lshl_add_u64 v[140:141], v[140:141], 0, s[34:35]
	v_mfma_f32_16x16x32_bf16 v[76:79], v[224:227], v[196:199], v[76:79]
	ds_read_b128 v[208:211], v174 offset:0
	s_add_u32 m0, s101, 0xc000
	v_mfma_f32_16x16x32_bf16 v[72:75], v[228:231], v[196:199], v[72:75]
	ds_read_b128 v[212:215], v174 offset:2048
	global_load_lds_dwordx4 v[250:251], off
	v_lshl_add_u64 v[250:251], v[250:251], 0, s[34:35]
	v_mfma_f32_16x16x32_bf16 v[68:71], v[232:235], v[196:199], v[68:71]
	ds_read_b128 v[216:219], v174 offset:4096
	s_add_u32 m0, s101, 0xe000
	v_mfma_f32_16x16x32_bf16 v[64:67], v[236:239], v[196:199], v[64:67]
	ds_read_b128 v[220:223], v174 offset:6144
	global_load_lds_dwordx4 v[252:253], off
	v_lshl_add_u64 v[252:253], v[252:253], 0, s[34:35]
	v_mfma_f32_16x16x32_bf16 v[44:47], v[224:227], v[200:203], v[44:47]
	v_mfma_f32_16x16x32_bf16 v[40:43], v[228:231], v[200:203], v[40:43]
	v_mfma_f32_16x16x32_bf16 v[36:39], v[232:235], v[200:203], v[36:39]
	v_mfma_f32_16x16x32_bf16 v[32:35], v[236:239], v[200:203], v[32:35]
	v_mfma_f32_16x16x32_bf16 v[12:15], v[224:227], v[204:207], v[12:15]
	v_mfma_f32_16x16x32_bf16 v[8:11], v[228:231], v[204:207], v[8:11]
	v_mfma_f32_16x16x32_bf16 v[4:7], v[232:235], v[204:207], v[4:7]
	v_mfma_f32_16x16x32_bf16 v[0:3], v[236:239], v[204:207], v[0:3]
	s_waitcnt lgkmcnt(0)
	s_nop 0
	v_mfma_f32_16x16x32_bf16 v[124:127], v[208:211], v[176:179], v[124:127]
	ds_read_b128 v[224:227], v174 offset:8192
	v_mfma_f32_16x16x32_bf16 v[120:123], v[212:215], v[176:179], v[120:123]
	ds_read_b128 v[228:231], v174 offset:10240
	v_mfma_f32_16x16x32_bf16 v[116:119], v[216:219], v[176:179], v[116:119]
	ds_read_b128 v[232:235], v174 offset:12288
	v_mfma_f32_16x16x32_bf16 v[112:115], v[220:223], v[176:179], v[112:115]
	ds_read_b128 v[236:239], v174 offset:14336
	v_mfma_f32_16x16x32_bf16 v[92:95], v[208:211], v[180:183], v[92:95]
	s_mov_b32 m0, s100
	s_nop 0
	v_mfma_f32_16x16x32_bf16 v[88:91], v[212:215], v[180:183], v[88:91]
	global_load_lds_dwordx4 v[240:241], off
	v_lshl_add_u64 v[240:241], v[240:241], 0, s[34:35]
	v_mfma_f32_16x16x32_bf16 v[84:87], v[216:219], v[180:183], v[84:87]
	s_add_u32 m0, s100, 0x2000
	v_mfma_f32_16x16x32_bf16 v[80:83], v[220:223], v[180:183], v[80:83]
	global_load_lds_dwordx4 v[242:243], off
	v_lshl_add_u64 v[242:243], v[242:243], 0, s[34:35]
	v_mfma_f32_16x16x32_bf16 v[60:63], v[208:211], v[184:187], v[60:63]
	s_add_u32 m0, s100, 0x4000
	v_mfma_f32_16x16x32_bf16 v[56:59], v[212:215], v[184:187], v[56:59]
	global_load_lds_dwordx4 v[244:245], off
	v_lshl_add_u64 v[244:245], v[244:245], 0, s[34:35]
	v_mfma_f32_16x16x32_bf16 v[52:55], v[216:219], v[184:187], v[52:55]
	s_add_u32 m0, s100, 0x6000
	v_mfma_f32_16x16x32_bf16 v[48:51], v[220:223], v[184:187], v[48:51]
	global_load_lds_dwordx4 v[246:247], off
	v_lshl_add_u64 v[246:247], v[246:247], 0, s[34:35]
	v_mfma_f32_16x16x32_bf16 v[28:31], v[208:211], v[188:191], v[28:31]
	v_mfma_f32_16x16x32_bf16 v[24:27], v[212:215], v[188:191], v[24:27]
	v_mfma_f32_16x16x32_bf16 v[20:23], v[216:219], v[188:191], v[20:23]
	v_mfma_f32_16x16x32_bf16 v[16:19], v[220:223], v[188:191], v[16:19]
	s_waitcnt lgkmcnt(0)
	s_nop 0
	v_mfma_f32_16x16x32_bf16 v[108:111], v[224:227], v[176:179], v[108:111]
	ds_read_b128 v[192:195], v173 offset:32768
	v_mfma_f32_16x16x32_bf16 v[104:107], v[228:231], v[176:179], v[104:107]
	ds_read_b128 v[196:199], v173 offset:34816
	v_mfma_f32_16x16x32_bf16 v[100:103], v[232:235], v[176:179], v[100:103]
	ds_read_b128 v[200:203], v173 offset:36864
	v_mfma_f32_16x16x32_bf16 v[96:99], v[236:239], v[176:179], v[96:99]
	ds_read_b128 v[204:207], v173 offset:38912
	v_mfma_f32_16x16x32_bf16 v[76:79], v[224:227], v[180:183], v[76:79]
	ds_read_b128 v[208:211], v175 offset:0
	v_mfma_f32_16x16x32_bf16 v[72:75], v[228:231], v[180:183], v[72:75]
	ds_read_b128 v[212:215], v175 offset:2048
	v_mfma_f32_16x16x32_bf16 v[68:71], v[232:235], v[180:183], v[68:71]
	ds_read_b128 v[216:219], v175 offset:4096
	v_mfma_f32_16x16x32_bf16 v[64:67], v[236:239], v[180:183], v[64:67]
	ds_read_b128 v[220:223], v175 offset:6144
	v_mfma_f32_16x16x32_bf16 v[44:47], v[224:227], v[184:187], v[44:47]
	v_mfma_f32_16x16x32_bf16 v[40:43], v[228:231], v[184:187], v[40:43]
	v_mfma_f32_16x16x32_bf16 v[36:39], v[232:235], v[184:187], v[36:39]
	v_mfma_f32_16x16x32_bf16 v[32:35], v[236:239], v[184:187], v[32:35]
	v_mfma_f32_16x16x32_bf16 v[12:15], v[224:227], v[188:191], v[12:15]
	v_mfma_f32_16x16x32_bf16 v[8:11], v[228:231], v[188:191], v[8:11]
	v_mfma_f32_16x16x32_bf16 v[4:7], v[232:235], v[188:191], v[4:7]
	v_mfma_f32_16x16x32_bf16 v[0:3], v[236:239], v[188:191], v[0:3]
	s_waitcnt lgkmcnt(0)
	s_nop 0
	v_mfma_f32_16x16x32_bf16 v[124:127], v[208:211], v[192:195], v[124:127]
	ds_read_b128 v[224:227], v175 offset:8192
	v_mfma_f32_16x16x32_bf16 v[120:123], v[212:215], v[192:195], v[120:123]
	ds_read_b128 v[228:231], v175 offset:10240
	v_mfma_f32_16x16x32_bf16 v[116:119], v[216:219], v[192:195], v[116:119]
	ds_read_b128 v[232:235], v175 offset:12288
	v_mfma_f32_16x16x32_bf16 v[112:115], v[220:223], v[192:195], v[112:115]
	ds_read_b128 v[236:239], v175 offset:14336
	v_mfma_f32_16x16x32_bf16 v[92:95], v[208:211], v[196:199], v[92:95]
	v_mfma_f32_16x16x32_bf16 v[88:91], v[212:215], v[196:199], v[88:91]
	v_mfma_f32_16x16x32_bf16 v[84:87], v[216:219], v[196:199], v[84:87]
	v_mfma_f32_16x16x32_bf16 v[80:83], v[220:223], v[196:199], v[80:83]
	v_mfma_f32_16x16x32_bf16 v[60:63], v[208:211], v[200:203], v[60:63]
	v_mfma_f32_16x16x32_bf16 v[56:59], v[212:215], v[200:203], v[56:59]
	v_mfma_f32_16x16x32_bf16 v[52:55], v[216:219], v[200:203], v[52:55]
	v_mfma_f32_16x16x32_bf16 v[48:51], v[220:223], v[200:203], v[48:51]
	v_mfma_f32_16x16x32_bf16 v[28:31], v[208:211], v[204:207], v[28:31]
	v_mfma_f32_16x16x32_bf16 v[24:27], v[212:215], v[204:207], v[24:27]
	v_mfma_f32_16x16x32_bf16 v[20:23], v[216:219], v[204:207], v[20:23]
	v_mfma_f32_16x16x32_bf16 v[16:19], v[220:223], v[204:207], v[16:19]
	s_waitcnt lgkmcnt(0)
	s_waitcnt vmcnt(4)
	s_barrier
	s_nop 0
	v_mfma_f32_16x16x32_bf16 v[108:111], v[224:227], v[192:195], v[108:111]
	ds_read_b128 v[176:179], v254 offset:0
	s_mov_b32 m0, s101
	s_nop 0
	v_mfma_f32_16x16x32_bf16 v[104:107], v[228:231], v[192:195], v[104:107]
	ds_read_b128 v[180:183], v254 offset:2048
	global_load_lds_dwordx4 v[138:139], off
	v_lshl_add_u64 v[138:139], v[138:139], 0, s[34:35]
	v_mfma_f32_16x16x32_bf16 v[100:103], v[232:235], v[192:195], v[100:103]
	ds_read_b128 v[184:187], v254 offset:4096
	s_add_u32 m0, s101, 0x2000
	v_mfma_f32_16x16x32_bf16 v[96:99], v[236:239], v[192:195], v[96:99]
	ds_read_b128 v[188:191], v254 offset:6144
	global_load_lds_dwordx4 v[140:141], off
	v_lshl_add_u64 v[140:141], v[140:141], 0, s[34:35]
	v_mfma_f32_16x16x32_bf16 v[76:79], v[224:227], v[196:199], v[76:79]
	ds_read_b128 v[208:211], v174 offset:32768
	s_add_u32 m0, s101, 0x4000
	v_mfma_f32_16x16x32_bf16 v[72:75], v[228:231], v[196:199], v[72:75]
	ds_read_b128 v[212:215], v174 offset:34816
	global_load_lds_dwordx4 v[250:251], off
	v_lshl_add_u64 v[250:251], v[250:251], 0, s[34:35]
	v_mfma_f32_16x16x32_bf16 v[68:71], v[232:235], v[196:199], v[68:71]
	ds_read_b128 v[216:219], v174 offset:36864
	s_add_u32 m0, s101, 0x6000
	v_mfma_f32_16x16x32_bf16 v[64:67], v[236:239], v[196:199], v[64:67]
	ds_read_b128 v[220:223], v174 offset:38912
	global_load_lds_dwordx4 v[252:253], off
	v_lshl_add_u64 v[252:253], v[252:253], 0, s[34:35]
	v_mfma_f32_16x16x32_bf16 v[44:47], v[224:227], v[200:203], v[44:47]
	v_mfma_f32_16x16x32_bf16 v[40:43], v[228:231], v[200:203], v[40:43]
	v_mfma_f32_16x16x32_bf16 v[36:39], v[232:235], v[200:203], v[36:39]
	v_mfma_f32_16x16x32_bf16 v[32:35], v[236:239], v[200:203], v[32:35]
	v_mfma_f32_16x16x32_bf16 v[12:15], v[224:227], v[204:207], v[12:15]
	v_mfma_f32_16x16x32_bf16 v[8:11], v[228:231], v[204:207], v[8:11]
	v_mfma_f32_16x16x32_bf16 v[4:7], v[232:235], v[204:207], v[4:7]
	v_mfma_f32_16x16x32_bf16 v[0:3], v[236:239], v[204:207], v[0:3]
	s_waitcnt lgkmcnt(0)
	s_nop 0
	v_mfma_f32_16x16x32_bf16 v[124:127], v[208:211], v[176:179], v[124:127]
	ds_read_b128 v[224:227], v174 offset:40960
	v_mfma_f32_16x16x32_bf16 v[120:123], v[212:215], v[176:179], v[120:123]
	ds_read_b128 v[228:231], v174 offset:43008
	v_mfma_f32_16x16x32_bf16 v[116:119], v[216:219], v[176:179], v[116:119]
	ds_read_b128 v[232:235], v174 offset:45056
	v_mfma_f32_16x16x32_bf16 v[112:115], v[220:223], v[176:179], v[112:115]
	ds_read_b128 v[236:239], v174 offset:47104
	v_mfma_f32_16x16x32_bf16 v[92:95], v[208:211], v[180:183], v[92:95]
	s_add_u32 m0, s100, 0x8000
	v_mfma_f32_16x16x32_bf16 v[88:91], v[212:215], v[180:183], v[88:91]
	global_load_lds_dwordx4 v[240:241], off
	v_lshl_add_u64 v[240:241], v[240:241], 0, s[34:35]
	v_mfma_f32_16x16x32_bf16 v[84:87], v[216:219], v[180:183], v[84:87]
	s_add_u32 m0, s100, 0xa000
	v_mfma_f32_16x16x32_bf16 v[80:83], v[220:223], v[180:183], v[80:83]
	global_load_lds_dwordx4 v[242:243], off
	v_lshl_add_u64 v[242:243], v[242:243], 0, s[34:35]
	v_mfma_f32_16x16x32_bf16 v[60:63], v[208:211], v[184:187], v[60:63]
	s_add_u32 m0, s100, 0xc000
	v_mfma_f32_16x16x32_bf16 v[56:59], v[212:215], v[184:187], v[56:59]
	global_load_lds_dwordx4 v[244:245], off
	v_lshl_add_u64 v[244:245], v[244:245], 0, s[34:35]
	v_mfma_f32_16x16x32_bf16 v[52:55], v[216:219], v[184:187], v[52:55]
	s_add_u32 m0, s100, 0xe000
	v_mfma_f32_16x16x32_bf16 v[48:51], v[220:223], v[184:187], v[48:51]
	global_load_lds_dwordx4 v[246:247], off
	v_lshl_add_u64 v[246:247], v[246:247], 0, s[34:35]
	v_mfma_f32_16x16x32_bf16 v[28:31], v[208:211], v[188:191], v[28:31]
	v_mfma_f32_16x16x32_bf16 v[24:27], v[212:215], v[188:191], v[24:27]
	v_mfma_f32_16x16x32_bf16 v[20:23], v[216:219], v[188:191], v[20:23]
	v_mfma_f32_16x16x32_bf16 v[16:19], v[220:223], v[188:191], v[16:19]
	s_waitcnt lgkmcnt(0)
	s_nop 0
	v_mfma_f32_16x16x32_bf16 v[108:111], v[224:227], v[176:179], v[108:111]
	ds_read_b128 v[192:195], v255 offset:0
	v_mfma_f32_16x16x32_bf16 v[104:107], v[228:231], v[176:179], v[104:107]
	ds_read_b128 v[196:199], v255 offset:2048
	v_mfma_f32_16x16x32_bf16 v[100:103], v[232:235], v[176:179], v[100:103]
	ds_read_b128 v[200:203], v255 offset:4096
	v_mfma_f32_16x16x32_bf16 v[96:99], v[236:239], v[176:179], v[96:99]
	ds_read_b128 v[204:207], v255 offset:6144
	v_mfma_f32_16x16x32_bf16 v[76:79], v[224:227], v[180:183], v[76:79]
	ds_read_b128 v[208:211], v175 offset:32768
	v_mfma_f32_16x16x32_bf16 v[72:75], v[228:231], v[180:183], v[72:75]
	ds_read_b128 v[212:215], v175 offset:34816
	v_mfma_f32_16x16x32_bf16 v[68:71], v[232:235], v[180:183], v[68:71]
	ds_read_b128 v[216:219], v175 offset:36864
	v_mfma_f32_16x16x32_bf16 v[64:67], v[236:239], v[180:183], v[64:67]
	ds_read_b128 v[220:223], v175 offset:38912
	v_mfma_f32_16x16x32_bf16 v[44:47], v[224:227], v[184:187], v[44:47]
	v_mfma_f32_16x16x32_bf16 v[40:43], v[228:231], v[184:187], v[40:43]
	v_mfma_f32_16x16x32_bf16 v[36:39], v[232:235], v[184:187], v[36:39]
	v_mfma_f32_16x16x32_bf16 v[32:35], v[236:239], v[184:187], v[32:35]
	v_mfma_f32_16x16x32_bf16 v[12:15], v[224:227], v[188:191], v[12:15]
	v_mfma_f32_16x16x32_bf16 v[8:11], v[228:231], v[188:191], v[8:11]
	v_mfma_f32_16x16x32_bf16 v[4:7], v[232:235], v[188:191], v[4:7]
	v_mfma_f32_16x16x32_bf16 v[0:3], v[236:239], v[188:191], v[0:3]
	s_waitcnt lgkmcnt(0)
	s_nop 0
	v_mfma_f32_16x16x32_bf16 v[124:127], v[208:211], v[192:195], v[124:127]
	ds_read_b128 v[224:227], v175 offset:40960
	v_mfma_f32_16x16x32_bf16 v[120:123], v[212:215], v[192:195], v[120:123]
	ds_read_b128 v[228:231], v175 offset:43008
	v_mfma_f32_16x16x32_bf16 v[116:119], v[216:219], v[192:195], v[116:119]
	ds_read_b128 v[232:235], v175 offset:45056
	v_mfma_f32_16x16x32_bf16 v[112:115], v[220:223], v[192:195], v[112:115]
	ds_read_b128 v[236:239], v175 offset:47104
	v_mfma_f32_16x16x32_bf16 v[92:95], v[208:211], v[196:199], v[92:95]
	v_mfma_f32_16x16x32_bf16 v[88:91], v[212:215], v[196:199], v[88:91]
	v_mfma_f32_16x16x32_bf16 v[84:87], v[216:219], v[196:199], v[84:87]
	v_mfma_f32_16x16x32_bf16 v[80:83], v[220:223], v[196:199], v[80:83]
	v_mfma_f32_16x16x32_bf16 v[60:63], v[208:211], v[200:203], v[60:63]
	v_mfma_f32_16x16x32_bf16 v[56:59], v[212:215], v[200:203], v[56:59]
	v_mfma_f32_16x16x32_bf16 v[52:55], v[216:219], v[200:203], v[52:55]
	v_mfma_f32_16x16x32_bf16 v[48:51], v[220:223], v[200:203], v[48:51]
	v_mfma_f32_16x16x32_bf16 v[28:31], v[208:211], v[204:207], v[28:31]
	v_mfma_f32_16x16x32_bf16 v[24:27], v[212:215], v[204:207], v[24:27]
	v_mfma_f32_16x16x32_bf16 v[20:23], v[216:219], v[204:207], v[20:23]
	v_mfma_f32_16x16x32_bf16 v[16:19], v[220:223], v[204:207], v[16:19]
	s_waitcnt lgkmcnt(0)
	s_waitcnt vmcnt(4)
	s_barrier
	s_nop 0
	v_mfma_f32_16x16x32_bf16 v[108:111], v[224:227], v[192:195], v[108:111]
	ds_read_b128 v[176:179], v172 offset:0
	s_add_u32 m0, s101, 0x8000
	v_mfma_f32_16x16x32_bf16 v[104:107], v[228:231], v[192:195], v[104:107]
	ds_read_b128 v[180:183], v172 offset:2048
	global_load_lds_dwordx4 v[138:139], off
	v_lshl_add_u64 v[138:139], v[138:139], 0, s[34:35]
	v_mfma_f32_16x16x32_bf16 v[100:103], v[232:235], v[192:195], v[100:103]
	ds_read_b128 v[184:187], v172 offset:4096
	s_add_u32 m0, s101, 0xa000
	v_mfma_f32_16x16x32_bf16 v[96:99], v[236:239], v[192:195], v[96:99]
	ds_read_b128 v[188:191], v172 offset:6144
	global_load_lds_dwordx4 v[140:141], off
	v_lshl_add_u64 v[140:141], v[140:141], 0, s[34:35]
	v_mfma_f32_16x16x32_bf16 v[76:79], v[224:227], v[196:199], v[76:79]
	ds_read_b128 v[208:211], v174 offset:0
	s_add_u32 m0, s101, 0xc000
	v_mfma_f32_16x16x32_bf16 v[72:75], v[228:231], v[196:199], v[72:75]
	ds_read_b128 v[212:215], v174 offset:2048
	global_load_lds_dwordx4 v[250:251], off
	v_lshl_add_u64 v[250:251], v[250:251], 0, s[34:35]
	v_mfma_f32_16x16x32_bf16 v[68:71], v[232:235], v[196:199], v[68:71]
	ds_read_b128 v[216:219], v174 offset:4096
	s_add_u32 m0, s101, 0xe000
	v_mfma_f32_16x16x32_bf16 v[64:67], v[236:239], v[196:199], v[64:67]
	ds_read_b128 v[220:223], v174 offset:6144
	global_load_lds_dwordx4 v[252:253], off
	v_lshl_add_u64 v[252:253], v[252:253], 0, s[34:35]
	v_mfma_f32_16x16x32_bf16 v[44:47], v[224:227], v[200:203], v[44:47]
	v_mfma_f32_16x16x32_bf16 v[40:43], v[228:231], v[200:203], v[40:43]
	v_mfma_f32_16x16x32_bf16 v[36:39], v[232:235], v[200:203], v[36:39]
	v_mfma_f32_16x16x32_bf16 v[32:35], v[236:239], v[200:203], v[32:35]
	v_mfma_f32_16x16x32_bf16 v[12:15], v[224:227], v[204:207], v[12:15]
	v_mfma_f32_16x16x32_bf16 v[8:11], v[228:231], v[204:207], v[8:11]
	v_mfma_f32_16x16x32_bf16 v[4:7], v[232:235], v[204:207], v[4:7]
	v_mfma_f32_16x16x32_bf16 v[0:3], v[236:239], v[204:207], v[0:3]
	s_waitcnt lgkmcnt(0)
	s_nop 0
	v_mfma_f32_16x16x32_bf16 v[124:127], v[208:211], v[176:179], v[124:127]
	ds_read_b128 v[224:227], v174 offset:8192
	v_mfma_f32_16x16x32_bf16 v[120:123], v[212:215], v[176:179], v[120:123]
	ds_read_b128 v[228:231], v174 offset:10240
	v_mfma_f32_16x16x32_bf16 v[116:119], v[216:219], v[176:179], v[116:119]
	ds_read_b128 v[232:235], v174 offset:12288
	v_mfma_f32_16x16x32_bf16 v[112:115], v[220:223], v[176:179], v[112:115]
	ds_read_b128 v[236:239], v174 offset:14336
	v_mfma_f32_16x16x32_bf16 v[92:95], v[208:211], v[180:183], v[92:95]
	s_add_u32 m0, s100, 0x20000
	v_mfma_f32_16x16x32_bf16 v[88:91], v[212:215], v[180:183], v[88:91]
	global_load_lds_dwordx4 v[240:241], off
	v_lshl_add_u64 v[240:241], v[240:241], 0, s[34:35]
	v_mfma_f32_16x16x32_bf16 v[84:87], v[216:219], v[180:183], v[84:87]
	s_add_u32 m0, s100, 0x22000
	v_mfma_f32_16x16x32_bf16 v[80:83], v[220:223], v[180:183], v[80:83]
	global_load_lds_dwordx4 v[242:243], off
	v_lshl_add_u64 v[242:243], v[242:243], 0, s[34:35]
	v_mfma_f32_16x16x32_bf16 v[60:63], v[208:211], v[184:187], v[60:63]
	s_add_u32 m0, s100, 0x24000
	v_mfma_f32_16x16x32_bf16 v[56:59], v[212:215], v[184:187], v[56:59]
	global_load_lds_dwordx4 v[244:245], off
	v_lshl_add_u64 v[244:245], v[244:245], 0, s[34:35]
	v_mfma_f32_16x16x32_bf16 v[52:55], v[216:219], v[184:187], v[52:55]
	s_add_u32 m0, s100, 0x26000
	v_mfma_f32_16x16x32_bf16 v[48:51], v[220:223], v[184:187], v[48:51]
	global_load_lds_dwordx4 v[246:247], off
	v_lshl_add_u64 v[246:247], v[246:247], 0, s[34:35]
	v_mfma_f32_16x16x32_bf16 v[28:31], v[208:211], v[188:191], v[28:31]
	v_mfma_f32_16x16x32_bf16 v[24:27], v[212:215], v[188:191], v[24:27]
	v_mfma_f32_16x16x32_bf16 v[20:23], v[216:219], v[188:191], v[20:23]
	v_mfma_f32_16x16x32_bf16 v[16:19], v[220:223], v[188:191], v[16:19]
	s_waitcnt lgkmcnt(0)
	s_nop 0
	v_mfma_f32_16x16x32_bf16 v[108:111], v[224:227], v[176:179], v[108:111]
	ds_read_b128 v[192:195], v173 offset:0
	v_mfma_f32_16x16x32_bf16 v[104:107], v[228:231], v[176:179], v[104:107]
	ds_read_b128 v[196:199], v173 offset:2048
	v_mfma_f32_16x16x32_bf16 v[100:103], v[232:235], v[176:179], v[100:103]
	ds_read_b128 v[200:203], v173 offset:4096
	v_mfma_f32_16x16x32_bf16 v[96:99], v[236:239], v[176:179], v[96:99]
	ds_read_b128 v[204:207], v173 offset:6144
	v_mfma_f32_16x16x32_bf16 v[76:79], v[224:227], v[180:183], v[76:79]
	ds_read_b128 v[208:211], v175 offset:0
	v_mfma_f32_16x16x32_bf16 v[72:75], v[228:231], v[180:183], v[72:75]
	ds_read_b128 v[212:215], v175 offset:2048
	v_mfma_f32_16x16x32_bf16 v[68:71], v[232:235], v[180:183], v[68:71]
	ds_read_b128 v[216:219], v175 offset:4096
	v_mfma_f32_16x16x32_bf16 v[64:67], v[236:239], v[180:183], v[64:67]
	ds_read_b128 v[220:223], v175 offset:6144
	v_mfma_f32_16x16x32_bf16 v[44:47], v[224:227], v[184:187], v[44:47]
	v_mfma_f32_16x16x32_bf16 v[40:43], v[228:231], v[184:187], v[40:43]
	v_mfma_f32_16x16x32_bf16 v[36:39], v[232:235], v[184:187], v[36:39]
	v_mfma_f32_16x16x32_bf16 v[32:35], v[236:239], v[184:187], v[32:35]
	v_mfma_f32_16x16x32_bf16 v[12:15], v[224:227], v[188:191], v[12:15]
	v_mfma_f32_16x16x32_bf16 v[8:11], v[228:231], v[188:191], v[8:11]
	v_mfma_f32_16x16x32_bf16 v[4:7], v[232:235], v[188:191], v[4:7]
	v_mfma_f32_16x16x32_bf16 v[0:3], v[236:239], v[188:191], v[0:3]
	s_waitcnt lgkmcnt(0)
	s_nop 0
	v_mfma_f32_16x16x32_bf16 v[124:127], v[208:211], v[192:195], v[124:127]
	ds_read_b128 v[224:227], v175 offset:8192
	v_mfma_f32_16x16x32_bf16 v[120:123], v[212:215], v[192:195], v[120:123]
	ds_read_b128 v[228:231], v175 offset:10240
	v_mfma_f32_16x16x32_bf16 v[116:119], v[216:219], v[192:195], v[116:119]
	ds_read_b128 v[232:235], v175 offset:12288
	v_mfma_f32_16x16x32_bf16 v[112:115], v[220:223], v[192:195], v[112:115]
	ds_read_b128 v[236:239], v175 offset:14336
	v_mfma_f32_16x16x32_bf16 v[92:95], v[208:211], v[196:199], v[92:95]
	v_mfma_f32_16x16x32_bf16 v[88:91], v[212:215], v[196:199], v[88:91]
	v_mfma_f32_16x16x32_bf16 v[84:87], v[216:219], v[196:199], v[84:87]
	v_mfma_f32_16x16x32_bf16 v[80:83], v[220:223], v[196:199], v[80:83]
	v_mfma_f32_16x16x32_bf16 v[60:63], v[208:211], v[200:203], v[60:63]
	v_mfma_f32_16x16x32_bf16 v[56:59], v[212:215], v[200:203], v[56:59]
	v_mfma_f32_16x16x32_bf16 v[52:55], v[216:219], v[200:203], v[52:55]
	v_mfma_f32_16x16x32_bf16 v[48:51], v[220:223], v[200:203], v[48:51]
	v_mfma_f32_16x16x32_bf16 v[28:31], v[208:211], v[204:207], v[28:31]
	v_mfma_f32_16x16x32_bf16 v[24:27], v[212:215], v[204:207], v[24:27]
	v_mfma_f32_16x16x32_bf16 v[20:23], v[216:219], v[204:207], v[20:23]
	v_mfma_f32_16x16x32_bf16 v[16:19], v[220:223], v[204:207], v[16:19]
	s_waitcnt lgkmcnt(0)
	s_waitcnt vmcnt(4)
	s_barrier
	s_add_i32 s46, s46, -1
	s_cmp_lg_u32 s46, 0
	s_cbranch_scc1 .Lgemm_p7_loop
	v_mfma_f32_16x16x32_bf16 v[108:111], v[224:227], v[192:195], v[108:111]
	ds_read_b128 v[176:179], v172 offset:32768
	s_mov_b32 m0, s101
	s_nop 0
	v_mfma_f32_16x16x32_bf16 v[104:107], v[228:231], v[192:195], v[104:107]
	ds_read_b128 v[180:183], v172 offset:34816
	global_load_lds_dwordx4 v[138:139], off
	v_lshl_add_u64 v[138:139], v[138:139], 0, s[34:35]
	v_mfma_f32_16x16x32_bf16 v[100:103], v[232:235], v[192:195], v[100:103]
	ds_read_b128 v[184:187], v172 offset:36864
	s_add_u32 m0, s101, 0x2000
	v_mfma_f32_16x16x32_bf16 v[96:99], v[236:239], v[192:195], v[96:99]
	ds_read_b128 v[188:191], v172 offset:38912
	global_load_lds_dwordx4 v[140:141], off
	v_lshl_add_u64 v[140:141], v[140:141], 0, s[34:35]
	v_mfma_f32_16x16x32_bf16 v[76:79], v[224:227], v[196:199], v[76:79]
	ds_read_b128 v[208:211], v174 offset:32768
	s_add_u32 m0, s101, 0x4000
	v_mfma_f32_16x16x32_bf16 v[72:75], v[228:231], v[196:199], v[72:75]
	ds_read_b128 v[212:215], v174 offset:34816
	global_load_lds_dwordx4 v[250:251], off
	v_lshl_add_u64 v[250:251], v[250:251], 0, s[34:35]
	v_mfma_f32_16x16x32_bf16 v[68:71], v[232:235], v[196:199], v[68:71]
	ds_read_b128 v[216:219], v174 offset:36864
	s_add_u32 m0, s101, 0x6000
	v_mfma_f32_16x16x32_bf16 v[64:67], v[236:239], v[196:199], v[64:67]
	ds_read_b128 v[220:223], v174 offset:38912
	global_load_lds_dwordx4 v[252:253], off
	v_lshl_add_u64 v[252:253], v[252:253], 0, s[34:35]
	v_mfma_f32_16x16x32_bf16 v[44:47], v[224:227], v[200:203], v[44:47]
	v_mfma_f32_16x16x32_bf16 v[40:43], v[228:231], v[200:203], v[40:43]
	v_mfma_f32_16x16x32_bf16 v[36:39], v[232:235], v[200:203], v[36:39]
	v_mfma_f32_16x16x32_bf16 v[32:35], v[236:239], v[200:203], v[32:35]
	v_mfma_f32_16x16x32_bf16 v[12:15], v[224:227], v[204:207], v[12:15]
	v_mfma_f32_16x16x32_bf16 v[8:11], v[228:231], v[204:207], v[8:11]
	v_mfma_f32_16x16x32_bf16 v[4:7], v[232:235], v[204:207], v[4:7]
	v_mfma_f32_16x16x32_bf16 v[0:3], v[236:239], v[204:207], v[0:3]
	s_waitcnt lgkmcnt(0)
	s_nop 0
	v_mfma_f32_16x16x32_bf16 v[124:127], v[208:211], v[176:179], v[124:127]
	ds_read_b128 v[224:227], v174 offset:40960
	v_mfma_f32_16x16x32_bf16 v[120:123], v[212:215], v[176:179], v[120:123]
	ds_read_b128 v[228:231], v174 offset:43008
	v_mfma_f32_16x16x32_bf16 v[116:119], v[216:219], v[176:179], v[116:119]
	ds_read_b128 v[232:235], v174 offset:45056
	v_mfma_f32_16x16x32_bf16 v[112:115], v[220:223], v[176:179], v[112:115]
	ds_read_b128 v[236:239], v174 offset:47104
	v_mfma_f32_16x16x32_bf16 v[92:95], v[208:211], v[180:183], v[92:95]
	s_mov_b32 m0, s100
	s_nop 0
	v_mfma_f32_16x16x32_bf16 v[88:91], v[212:215], v[180:183], v[88:91]
	global_load_lds_dwordx4 v[240:241], off
	v_lshl_add_u64 v[240:241], v[240:241], 0, s[34:35]
	v_mfma_f32_16x16x32_bf16 v[84:87], v[216:219], v[180:183], v[84:87]
	s_add_u32 m0, s100, 0x2000
	v_mfma_f32_16x16x32_bf16 v[80:83], v[220:223], v[180:183], v[80:83]
	global_load_lds_dwordx4 v[242:243], off
	v_lshl_add_u64 v[242:243], v[242:243], 0, s[34:35]
	v_mfma_f32_16x16x32_bf16 v[60:63], v[208:211], v[184:187], v[60:63]
	s_add_u32 m0, s100, 0x4000
	v_mfma_f32_16x16x32_bf16 v[56:59], v[212:215], v[184:187], v[56:59]
	global_load_lds_dwordx4 v[244:245], off
	v_lshl_add_u64 v[244:245], v[244:245], 0, s[34:35]
	v_mfma_f32_16x16x32_bf16 v[52:55], v[216:219], v[184:187], v[52:55]
	s_add_u32 m0, s100, 0x6000
	v_mfma_f32_16x16x32_bf16 v[48:51], v[220:223], v[184:187], v[48:51]
	global_load_lds_dwordx4 v[246:247], off
	v_lshl_add_u64 v[246:247], v[246:247], 0, s[34:35]
	v_mfma_f32_16x16x32_bf16 v[28:31], v[208:211], v[188:191], v[28:31]
	v_mfma_f32_16x16x32_bf16 v[24:27], v[212:215], v[188:191], v[24:27]
	v_mfma_f32_16x16x32_bf16 v[20:23], v[216:219], v[188:191], v[20:23]
	v_mfma_f32_16x16x32_bf16 v[16:19], v[220:223], v[188:191], v[16:19]
	s_waitcnt lgkmcnt(0)
	s_nop 0
	v_mfma_f32_16x16x32_bf16 v[108:111], v[224:227], v[176:179], v[108:111]
	ds_read_b128 v[192:195], v173 offset:32768
	v_mfma_f32_16x16x32_bf16 v[104:107], v[228:231], v[176:179], v[104:107]
	ds_read_b128 v[196:199], v173 offset:34816
	v_mfma_f32_16x16x32_bf16 v[100:103], v[232:235], v[176:179], v[100:103]
	ds_read_b128 v[200:203], v173 offset:36864
	v_mfma_f32_16x16x32_bf16 v[96:99], v[236:239], v[176:179], v[96:99]
	ds_read_b128 v[204:207], v173 offset:38912
	v_mfma_f32_16x16x32_bf16 v[76:79], v[224:227], v[180:183], v[76:79]
	ds_read_b128 v[208:211], v175 offset:32768
	v_mfma_f32_16x16x32_bf16 v[72:75], v[228:231], v[180:183], v[72:75]
	ds_read_b128 v[212:215], v175 offset:34816
	v_mfma_f32_16x16x32_bf16 v[68:71], v[232:235], v[180:183], v[68:71]
	ds_read_b128 v[216:219], v175 offset:36864
	v_mfma_f32_16x16x32_bf16 v[64:67], v[236:239], v[180:183], v[64:67]
	ds_read_b128 v[220:223], v175 offset:38912
	v_mfma_f32_16x16x32_bf16 v[44:47], v[224:227], v[184:187], v[44:47]
	v_mfma_f32_16x16x32_bf16 v[40:43], v[228:231], v[184:187], v[40:43]
	v_mfma_f32_16x16x32_bf16 v[36:39], v[232:235], v[184:187], v[36:39]
	v_mfma_f32_16x16x32_bf16 v[32:35], v[236:239], v[184:187], v[32:35]
	v_mfma_f32_16x16x32_bf16 v[12:15], v[224:227], v[188:191], v[12:15]
	v_mfma_f32_16x16x32_bf16 v[8:11], v[228:231], v[188:191], v[8:11]
	v_mfma_f32_16x16x32_bf16 v[4:7], v[232:235], v[188:191], v[4:7]
	v_mfma_f32_16x16x32_bf16 v[0:3], v[236:239], v[188:191], v[0:3]
	s_waitcnt lgkmcnt(0)
	s_nop 0
	v_mfma_f32_16x16x32_bf16 v[124:127], v[208:211], v[192:195], v[124:127]
	ds_read_b128 v[224:227], v175 offset:40960
	v_mfma_f32_16x16x32_bf16 v[120:123], v[212:215], v[192:195], v[120:123]
	ds_read_b128 v[228:231], v175 offset:43008
	v_mfma_f32_16x16x32_bf16 v[116:119], v[216:219], v[192:195], v[116:119]
	ds_read_b128 v[232:235], v175 offset:45056
	v_mfma_f32_16x16x32_bf16 v[112:115], v[220:223], v[192:195], v[112:115]
	ds_read_b128 v[236:239], v175 offset:47104
	v_mfma_f32_16x16x32_bf16 v[92:95], v[208:211], v[196:199], v[92:95]
	v_mfma_f32_16x16x32_bf16 v[88:91], v[212:215], v[196:199], v[88:91]
	v_mfma_f32_16x16x32_bf16 v[84:87], v[216:219], v[196:199], v[84:87]
	v_mfma_f32_16x16x32_bf16 v[80:83], v[220:223], v[196:199], v[80:83]
	v_mfma_f32_16x16x32_bf16 v[60:63], v[208:211], v[200:203], v[60:63]
	v_mfma_f32_16x16x32_bf16 v[56:59], v[212:215], v[200:203], v[56:59]
	v_mfma_f32_16x16x32_bf16 v[52:55], v[216:219], v[200:203], v[52:55]
	v_mfma_f32_16x16x32_bf16 v[48:51], v[220:223], v[200:203], v[48:51]
	v_mfma_f32_16x16x32_bf16 v[28:31], v[208:211], v[204:207], v[28:31]
	v_mfma_f32_16x16x32_bf16 v[24:27], v[212:215], v[204:207], v[24:27]
	v_mfma_f32_16x16x32_bf16 v[20:23], v[216:219], v[204:207], v[20:23]
	v_mfma_f32_16x16x32_bf16 v[16:19], v[220:223], v[204:207], v[16:19]
	s_waitcnt lgkmcnt(0)
	s_waitcnt vmcnt(4)
	s_barrier
	s_nop 0
	v_mfma_f32_16x16x32_bf16 v[108:111], v[224:227], v[192:195], v[108:111]
	ds_read_b128 v[176:179], v254 offset:0
	s_add_u32 m0, s101, 0x8000
	v_mfma_f32_16x16x32_bf16 v[104:107], v[228:231], v[192:195], v[104:107]
	ds_read_b128 v[180:183], v254 offset:2048
	global_load_lds_dwordx4 v[138:139], off
	v_lshl_add_u64 v[138:139], v[138:139], 0, s[34:35]
	v_mfma_f32_16x16x32_bf16 v[100:103], v[232:235], v[192:195], v[100:103]
	ds_read_b128 v[184:187], v254 offset:4096
	s_add_u32 m0, s101, 0xa000
	v_mfma_f32_16x16x32_bf16 v[96:99], v[236:239], v[192:195], v[96:99]
	ds_read_b128 v[188:191], v254 offset:6144
	global_load_lds_dwordx4 v[140:141], off
	v_lshl_add_u64 v[140:141], v[140:141], 0, s[34:35]
	v_mfma_f32_16x16x32_bf16 v[76:79], v[224:227], v[196:199], v[76:79]
	ds_read_b128 v[208:211], v174 offset:0
	s_add_u32 m0, s101, 0xc000
	v_mfma_f32_16x16x32_bf16 v[72:75], v[228:231], v[196:199], v[72:75]
	ds_read_b128 v[212:215], v174 offset:2048
	global_load_lds_dwordx4 v[250:251], off
	v_lshl_add_u64 v[250:251], v[250:251], 0, s[34:35]
	v_mfma_f32_16x16x32_bf16 v[68:71], v[232:235], v[196:199], v[68:71]
	ds_read_b128 v[216:219], v174 offset:4096
	s_add_u32 m0, s101, 0xe000
	v_mfma_f32_16x16x32_bf16 v[64:67], v[236:239], v[196:199], v[64:67]
	ds_read_b128 v[220:223], v174 offset:6144
	global_load_lds_dwordx4 v[252:253], off
	v_lshl_add_u64 v[252:253], v[252:253], 0, s[34:35]
	v_mfma_f32_16x16x32_bf16 v[44:47], v[224:227], v[200:203], v[44:47]
	v_mfma_f32_16x16x32_bf16 v[40:43], v[228:231], v[200:203], v[40:43]
	v_mfma_f32_16x16x32_bf16 v[36:39], v[232:235], v[200:203], v[36:39]
	v_mfma_f32_16x16x32_bf16 v[32:35], v[236:239], v[200:203], v[32:35]
	v_mfma_f32_16x16x32_bf16 v[12:15], v[224:227], v[204:207], v[12:15]
	v_mfma_f32_16x16x32_bf16 v[8:11], v[228:231], v[204:207], v[8:11]
	v_mfma_f32_16x16x32_bf16 v[4:7], v[232:235], v[204:207], v[4:7]
	v_mfma_f32_16x16x32_bf16 v[0:3], v[236:239], v[204:207], v[0:3]
	s_waitcnt lgkmcnt(0)
	s_nop 0
	v_mfma_f32_16x16x32_bf16 v[124:127], v[208:211], v[176:179], v[124:127]
	ds_read_b128 v[224:227], v174 offset:8192
	v_mfma_f32_16x16x32_bf16 v[120:123], v[212:215], v[176:179], v[120:123]
	ds_read_b128 v[228:231], v174 offset:10240
	v_mfma_f32_16x16x32_bf16 v[116:119], v[216:219], v[176:179], v[116:119]
	ds_read_b128 v[232:235], v174 offset:12288
	v_mfma_f32_16x16x32_bf16 v[112:115], v[220:223], v[176:179], v[112:115]
	ds_read_b128 v[236:239], v174 offset:14336
	v_mfma_f32_16x16x32_bf16 v[92:95], v[208:211], v[180:183], v[92:95]
	v_mfma_f32_16x16x32_bf16 v[88:91], v[212:215], v[180:183], v[88:91]
	v_mfma_f32_16x16x32_bf16 v[84:87], v[216:219], v[180:183], v[84:87]
	v_mfma_f32_16x16x32_bf16 v[80:83], v[220:223], v[180:183], v[80:83]
	v_mfma_f32_16x16x32_bf16 v[60:63], v[208:211], v[184:187], v[60:63]
	v_mfma_f32_16x16x32_bf16 v[56:59], v[212:215], v[184:187], v[56:59]
	v_mfma_f32_16x16x32_bf16 v[52:55], v[216:219], v[184:187], v[52:55]
	v_mfma_f32_16x16x32_bf16 v[48:51], v[220:223], v[184:187], v[48:51]
	v_mfma_f32_16x16x32_bf16 v[28:31], v[208:211], v[188:191], v[28:31]
	v_mfma_f32_16x16x32_bf16 v[24:27], v[212:215], v[188:191], v[24:27]
	v_mfma_f32_16x16x32_bf16 v[20:23], v[216:219], v[188:191], v[20:23]
	v_mfma_f32_16x16x32_bf16 v[16:19], v[220:223], v[188:191], v[16:19]
	s_waitcnt lgkmcnt(0)
	s_nop 0
	v_mfma_f32_16x16x32_bf16 v[108:111], v[224:227], v[176:179], v[108:111]
	ds_read_b128 v[192:195], v255 offset:0
	v_mfma_f32_16x16x32_bf16 v[104:107], v[228:231], v[176:179], v[104:107]
	ds_read_b128 v[196:199], v255 offset:2048
	v_mfma_f32_16x16x32_bf16 v[100:103], v[232:235], v[176:179], v[100:103]
	ds_read_b128 v[200:203], v255 offset:4096
	v_mfma_f32_16x16x32_bf16 v[96:99], v[236:239], v[176:179], v[96:99]
	ds_read_b128 v[204:207], v255 offset:6144
	v_mfma_f32_16x16x32_bf16 v[76:79], v[224:227], v[180:183], v[76:79]
	ds_read_b128 v[208:211], v175 offset:0
	v_mfma_f32_16x16x32_bf16 v[72:75], v[228:231], v[180:183], v[72:75]
	ds_read_b128 v[212:215], v175 offset:2048
	v_mfma_f32_16x16x32_bf16 v[68:71], v[232:235], v[180:183], v[68:71]
	ds_read_b128 v[216:219], v175 offset:4096
	v_mfma_f32_16x16x32_bf16 v[64:67], v[236:239], v[180:183], v[64:67]
	ds_read_b128 v[220:223], v175 offset:6144
	v_mfma_f32_16x16x32_bf16 v[44:47], v[224:227], v[184:187], v[44:47]
	v_mfma_f32_16x16x32_bf16 v[40:43], v[228:231], v[184:187], v[40:43]
	v_mfma_f32_16x16x32_bf16 v[36:39], v[232:235], v[184:187], v[36:39]
	v_mfma_f32_16x16x32_bf16 v[32:35], v[236:239], v[184:187], v[32:35]
	v_mfma_f32_16x16x32_bf16 v[12:15], v[224:227], v[188:191], v[12:15]
	v_mfma_f32_16x16x32_bf16 v[8:11], v[228:231], v[188:191], v[8:11]
	v_mfma_f32_16x16x32_bf16 v[4:7], v[232:235], v[188:191], v[4:7]
	v_mfma_f32_16x16x32_bf16 v[0:3], v[236:239], v[188:191], v[0:3]
	s_waitcnt lgkmcnt(0)
	s_nop 0
	v_mfma_f32_16x16x32_bf16 v[124:127], v[208:211], v[192:195], v[124:127]
	ds_read_b128 v[224:227], v175 offset:8192
	v_mfma_f32_16x16x32_bf16 v[120:123], v[212:215], v[192:195], v[120:123]
	ds_read_b128 v[228:231], v175 offset:10240
	v_mfma_f32_16x16x32_bf16 v[116:119], v[216:219], v[192:195], v[116:119]
	ds_read_b128 v[232:235], v175 offset:12288
	v_mfma_f32_16x16x32_bf16 v[112:115], v[220:223], v[192:195], v[112:115]
	ds_read_b128 v[236:239], v175 offset:14336
	v_mfma_f32_16x16x32_bf16 v[92:95], v[208:211], v[196:199], v[92:95]
	v_mfma_f32_16x16x32_bf16 v[88:91], v[212:215], v[196:199], v[88:91]
	v_mfma_f32_16x16x32_bf16 v[84:87], v[216:219], v[196:199], v[84:87]
	v_mfma_f32_16x16x32_bf16 v[80:83], v[220:223], v[196:199], v[80:83]
	v_mfma_f32_16x16x32_bf16 v[60:63], v[208:211], v[200:203], v[60:63]
	v_mfma_f32_16x16x32_bf16 v[56:59], v[212:215], v[200:203], v[56:59]
	v_mfma_f32_16x16x32_bf16 v[52:55], v[216:219], v[200:203], v[52:55]
	v_mfma_f32_16x16x32_bf16 v[48:51], v[220:223], v[200:203], v[48:51]
	v_mfma_f32_16x16x32_bf16 v[28:31], v[208:211], v[204:207], v[28:31]
	v_mfma_f32_16x16x32_bf16 v[24:27], v[212:215], v[204:207], v[24:27]
	v_mfma_f32_16x16x32_bf16 v[20:23], v[216:219], v[204:207], v[20:23]
	v_mfma_f32_16x16x32_bf16 v[16:19], v[220:223], v[204:207], v[16:19]
	s_waitcnt lgkmcnt(0)
	s_waitcnt vmcnt(0)
	s_barrier
	s_nop 0
	v_mfma_f32_16x16x32_bf16 v[108:111], v[224:227], v[192:195], v[108:111]
	ds_read_b128 v[176:179], v172 offset:0
	v_mfma_f32_16x16x32_bf16 v[104:107], v[228:231], v[192:195], v[104:107]
	ds_read_b128 v[180:183], v172 offset:2048
	v_mfma_f32_16x16x32_bf16 v[100:103], v[232:235], v[192:195], v[100:103]
	ds_read_b128 v[184:187], v172 offset:4096
	v_mfma_f32_16x16x32_bf16 v[96:99], v[236:239], v[192:195], v[96:99]
	ds_read_b128 v[188:191], v172 offset:6144
	v_mfma_f32_16x16x32_bf16 v[76:79], v[224:227], v[196:199], v[76:79]
	ds_read_b128 v[208:211], v174 offset:32768
	v_mfma_f32_16x16x32_bf16 v[72:75], v[228:231], v[196:199], v[72:75]
	ds_read_b128 v[212:215], v174 offset:34816
	v_mfma_f32_16x16x32_bf16 v[68:71], v[232:235], v[196:199], v[68:71]
	ds_read_b128 v[216:219], v174 offset:36864
	v_mfma_f32_16x16x32_bf16 v[64:67], v[236:239], v[196:199], v[64:67]
	ds_read_b128 v[220:223], v174 offset:38912
	v_mfma_f32_16x16x32_bf16 v[44:47], v[224:227], v[200:203], v[44:47]
	v_mfma_f32_16x16x32_bf16 v[40:43], v[228:231], v[200:203], v[40:43]
	v_mfma_f32_16x16x32_bf16 v[36:39], v[232:235], v[200:203], v[36:39]
	v_mfma_f32_16x16x32_bf16 v[32:35], v[236:239], v[200:203], v[32:35]
	v_mfma_f32_16x16x32_bf16 v[12:15], v[224:227], v[204:207], v[12:15]
	v_mfma_f32_16x16x32_bf16 v[8:11], v[228:231], v[204:207], v[8:11]
	v_mfma_f32_16x16x32_bf16 v[4:7], v[232:235], v[204:207], v[4:7]
	v_mfma_f32_16x16x32_bf16 v[0:3], v[236:239], v[204:207], v[0:3]
	s_waitcnt lgkmcnt(0)
	s_nop 0
	v_mfma_f32_16x16x32_bf16 v[124:127], v[208:211], v[176:179], v[124:127]
	ds_read_b128 v[224:227], v174 offset:40960
	v_mfma_f32_16x16x32_bf16 v[120:123], v[212:215], v[176:179], v[120:123]
	ds_read_b128 v[228:231], v174 offset:43008
	v_mfma_f32_16x16x32_bf16 v[116:119], v[216:219], v[176:179], v[116:119]
	ds_read_b128 v[232:235], v174 offset:45056
	v_mfma_f32_16x16x32_bf16 v[112:115], v[220:223], v[176:179], v[112:115]
	ds_read_b128 v[236:239], v174 offset:47104
	v_mfma_f32_16x16x32_bf16 v[92:95], v[208:211], v[180:183], v[92:95]
	v_mfma_f32_16x16x32_bf16 v[88:91], v[212:215], v[180:183], v[88:91]
	v_mfma_f32_16x16x32_bf16 v[84:87], v[216:219], v[180:183], v[84:87]
	v_mfma_f32_16x16x32_bf16 v[80:83], v[220:223], v[180:183], v[80:83]
	v_mfma_f32_16x16x32_bf16 v[60:63], v[208:211], v[184:187], v[60:63]
	v_mfma_f32_16x16x32_bf16 v[56:59], v[212:215], v[184:187], v[56:59]
	v_mfma_f32_16x16x32_bf16 v[52:55], v[216:219], v[184:187], v[52:55]
	v_mfma_f32_16x16x32_bf16 v[48:51], v[220:223], v[184:187], v[48:51]
	v_mfma_f32_16x16x32_bf16 v[28:31], v[208:211], v[188:191], v[28:31]
	v_mfma_f32_16x16x32_bf16 v[24:27], v[212:215], v[188:191], v[24:27]
	v_mfma_f32_16x16x32_bf16 v[20:23], v[216:219], v[188:191], v[20:23]
	v_mfma_f32_16x16x32_bf16 v[16:19], v[220:223], v[188:191], v[16:19]
	s_waitcnt lgkmcnt(0)
	s_nop 0
	v_mfma_f32_16x16x32_bf16 v[108:111], v[224:227], v[176:179], v[108:111]
	ds_read_b128 v[192:195], v173 offset:0
	v_mfma_f32_16x16x32_bf16 v[104:107], v[228:231], v[176:179], v[104:107]
	ds_read_b128 v[196:199], v173 offset:2048
	v_mfma_f32_16x16x32_bf16 v[100:103], v[232:235], v[176:179], v[100:103]
	ds_read_b128 v[200:203], v173 offset:4096
	v_mfma_f32_16x16x32_bf16 v[96:99], v[236:239], v[176:179], v[96:99]
	ds_read_b128 v[204:207], v173 offset:6144
	v_mfma_f32_16x16x32_bf16 v[76:79], v[224:227], v[180:183], v[76:79]
	ds_read_b128 v[208:211], v175 offset:32768
	v_mfma_f32_16x16x32_bf16 v[72:75], v[228:231], v[180:183], v[72:75]
	ds_read_b128 v[212:215], v175 offset:34816
	v_mfma_f32_16x16x32_bf16 v[68:71], v[232:235], v[180:183], v[68:71]
	ds_read_b128 v[216:219], v175 offset:36864
	v_mfma_f32_16x16x32_bf16 v[64:67], v[236:239], v[180:183], v[64:67]
	ds_read_b128 v[220:223], v175 offset:38912
	v_mfma_f32_16x16x32_bf16 v[44:47], v[224:227], v[184:187], v[44:47]
	v_mfma_f32_16x16x32_bf16 v[40:43], v[228:231], v[184:187], v[40:43]
	v_mfma_f32_16x16x32_bf16 v[36:39], v[232:235], v[184:187], v[36:39]
	v_mfma_f32_16x16x32_bf16 v[32:35], v[236:239], v[184:187], v[32:35]
	v_mfma_f32_16x16x32_bf16 v[12:15], v[224:227], v[188:191], v[12:15]
	v_mfma_f32_16x16x32_bf16 v[8:11], v[228:231], v[188:191], v[8:11]
	v_mfma_f32_16x16x32_bf16 v[4:7], v[232:235], v[188:191], v[4:7]
	v_mfma_f32_16x16x32_bf16 v[0:3], v[236:239], v[188:191], v[0:3]
	s_waitcnt lgkmcnt(0)
	s_nop 0
	v_mfma_f32_16x16x32_bf16 v[124:127], v[208:211], v[192:195], v[124:127]
	ds_read_b128 v[224:227], v175 offset:40960
	v_mfma_f32_16x16x32_bf16 v[120:123], v[212:215], v[192:195], v[120:123]
	ds_read_b128 v[228:231], v175 offset:43008
	v_mfma_f32_16x16x32_bf16 v[116:119], v[216:219], v[192:195], v[116:119]
	ds_read_b128 v[232:235], v175 offset:45056
	v_mfma_f32_16x16x32_bf16 v[112:115], v[220:223], v[192:195], v[112:115]
	ds_read_b128 v[236:239], v175 offset:47104
	v_mfma_f32_16x16x32_bf16 v[92:95], v[208:211], v[196:199], v[92:95]
	v_mfma_f32_16x16x32_bf16 v[88:91], v[212:215], v[196:199], v[88:91]
	v_mfma_f32_16x16x32_bf16 v[84:87], v[216:219], v[196:199], v[84:87]
	v_mfma_f32_16x16x32_bf16 v[80:83], v[220:223], v[196:199], v[80:83]
	v_mfma_f32_16x16x32_bf16 v[60:63], v[208:211], v[200:203], v[60:63]
	v_mfma_f32_16x16x32_bf16 v[56:59], v[212:215], v[200:203], v[56:59]
	v_mfma_f32_16x16x32_bf16 v[52:55], v[216:219], v[200:203], v[52:55]
	v_mfma_f32_16x16x32_bf16 v[48:51], v[220:223], v[200:203], v[48:51]
	v_mfma_f32_16x16x32_bf16 v[28:31], v[208:211], v[204:207], v[28:31]
	v_mfma_f32_16x16x32_bf16 v[24:27], v[212:215], v[204:207], v[24:27]
	v_mfma_f32_16x16x32_bf16 v[20:23], v[216:219], v[204:207], v[20:23]
	v_mfma_f32_16x16x32_bf16 v[16:19], v[220:223], v[204:207], v[16:19]
	s_waitcnt lgkmcnt(0)
	s_barrier
	v_mfma_f32_16x16x32_bf16 v[108:111], v[224:227], v[192:195], v[108:111]
	v_mfma_f32_16x16x32_bf16 v[104:107], v[228:231], v[192:195], v[104:107]
	v_mfma_f32_16x16x32_bf16 v[100:103], v[232:235], v[192:195], v[100:103]
	v_mfma_f32_16x16x32_bf16 v[96:99], v[236:239], v[192:195], v[96:99]
	v_mfma_f32_16x16x32_bf16 v[76:79], v[224:227], v[196:199], v[76:79]
	v_mfma_f32_16x16x32_bf16 v[72:75], v[228:231], v[196:199], v[72:75]
	v_mfma_f32_16x16x32_bf16 v[68:71], v[232:235], v[196:199], v[68:71]
	v_mfma_f32_16x16x32_bf16 v[64:67], v[236:239], v[196:199], v[64:67]
	v_mfma_f32_16x16x32_bf16 v[44:47], v[224:227], v[200:203], v[44:47]
	v_mfma_f32_16x16x32_bf16 v[40:43], v[228:231], v[200:203], v[40:43]
	v_mfma_f32_16x16x32_bf16 v[36:39], v[232:235], v[200:203], v[36:39]
	v_mfma_f32_16x16x32_bf16 v[32:35], v[236:239], v[200:203], v[32:35]
	v_mfma_f32_16x16x32_bf16 v[12:15], v[224:227], v[204:207], v[12:15]
	v_mfma_f32_16x16x32_bf16 v[8:11], v[228:231], v[204:207], v[8:11]
	v_mfma_f32_16x16x32_bf16 v[4:7], v[232:235], v[204:207], v[4:7]
	v_mfma_f32_16x16x32_bf16 v[0:3], v[236:239], v[204:207], v[0:3]
	s_nop 7
	s_nop 3
	s_branch .LBB0_1093

.LBB0_1134:
	v_mov_b64_e32 v[0:1], v[132:133]
	v_mov_b64_e32 v[2:3], v[132:133]
	v_mov_b32_e32 v6, v154
	s_lshl_b32 s6, s88, 8
	s_mov_b64 s[4:5], 0x11a00000
	v_ashrrev_i32_e32 v9, 3, v6
	v_add_u32_e32 v4, s6, v9
	v_lshl_add_u64 v[0:1], v[0:1], 0, s[4:5]
	v_lshrrev_b32_e32 v8, 4, v6
	v_ashrrev_i32_e32 v5, 31, v4
	v_xor_b32_e32 v10, v8, v6
	v_lshlrev_b64 v[4:5], 11, v[4:5]
	v_lshl_add_u64 v[0:1], v[0:1], 0, v[4:5]
	v_lshlrev_b32_e32 v4, 4, v10
	s_lshl_b32 s7, s92, 8
	v_and_b32_e32 v134, 0x70, v4
	v_lshl_add_u64 v[128:129], v[0:1], 0, v[134:135]
	v_add_u32_e32 v0, s7, v9
	s_mov_b64 s[4:5], 0x8c0000
	v_ashrrev_i32_e32 v1, 31, v0
	v_lshl_add_u64 v[2:3], v[2:3], 0, s[4:5]
	v_lshlrev_b64 v[0:1], 11, v[0:1]
	v_ashrrev_i32_e32 v7, 6, v6
	v_lshl_add_u64 v[0:1], v[2:3], 0, v[0:1]
	v_lshl_add_u64 v[130:131], v[0:1], 0, v[134:135]
	v_ashrrev_i32_e32 v0, 1, v6
	v_and_b32_e32 v134, 0xffffffc0, v0
	v_lshlrev_b32_e32 v0, 7, v7
	v_and_b32_e32 v143, 0x80, v0
	v_lshlrev_b32_e32 v0, 10, v7
	v_add_u32_e32 v144, 0, v0
	v_add_u32_e32 v145, s79, v0
	v_readfirstlane_b32 s4, v144
	s_mov_b32 m0, s4
	v_readfirstlane_b32 s4, v145
	v_add_u32_e32 v146, 0x2000, v144
	global_load_lds_dwordx4 v[128:129], off
	s_mov_b32 m0, s4
	s_mov_b64 s[20:21], 0x20000
	v_readfirstlane_b32 s4, v146
	v_add_u32_e32 v147, 0x2000, v145
	global_load_lds_dwordx4 v[130:131], off
	v_lshl_add_u64 v[0:1], v[128:129], 0, s[20:21]
	s_mov_b32 m0, s4
	v_readfirstlane_b32 s4, v147
	v_add_u32_e32 v148, 0x4000, v144
	global_load_lds_dwordx4 v[0:1], off
	v_lshl_add_u64 v[0:1], v[130:131], 0, s[20:21]
	s_mov_b32 m0, s4
	s_mov_b64 s[20:21], 0x40000
	v_readfirstlane_b32 s4, v148
	v_add_u32_e32 v150, 0x4000, v145
	global_load_lds_dwordx4 v[0:1], off
	v_lshl_add_u64 v[0:1], v[128:129], 0, s[20:21]
	s_mov_b32 m0, s4
	v_readfirstlane_b32 s4, v150
	v_add_u32_e32 v151, 0x6000, v144
	global_load_lds_dwordx4 v[0:1], off
	v_lshl_add_u64 v[0:1], v[130:131], 0, s[20:21]
	s_mov_b32 m0, s4
	s_mov_b64 s[20:21], 0x60000
	v_readfirstlane_b32 s4, v151
	v_add_u32_e32 v152, 0x6000, v145
	global_load_lds_dwordx4 v[0:1], off
	v_lshl_add_u64 v[0:1], v[128:129], 0, s[20:21]
	s_mov_b32 m0, s4
	v_readfirstlane_b32 s4, v152
	global_load_lds_dwordx4 v[0:1], off
	v_lshl_add_u64 v[0:1], v[130:131], 0, s[20:21]
	s_mov_b32 m0, s4
	v_bfe_u32 v149, v6, 4, 2
	global_load_lds_dwordx4 v[0:1], off
	s_mov_b64 s[100:101], 0x80
	v_lshl_add_u64 v[240:241], v[128:129], 0, s[100:101]
	s_mov_b64 s[100:101], 0x20080
	v_lshl_add_u64 v[242:243], v[128:129], 0, s[100:101]
	s_mov_b64 s[100:101], 0x40080
	v_lshl_add_u64 v[244:245], v[128:129], 0, s[100:101]
	s_mov_b64 s[100:101], 0x60080
	v_lshl_add_u64 v[246:247], v[128:129], 0, s[100:101]
	s_mov_b64 s[100:101], 0x80
	v_lshl_add_u64 v[138:139], v[130:131], 0, s[100:101]
	s_mov_b64 s[100:101], 0x20080
	v_lshl_add_u64 v[140:141], v[130:131], 0, s[100:101]
	s_mov_b64 s[100:101], 0x40080
	v_lshl_add_u64 v[250:251], v[130:131], 0, s[100:101]
	s_mov_b64 s[100:101], 0x60080
	v_lshl_add_u64 v[252:253], v[130:131], 0, s[100:101]
	v_readfirstlane_b32 s100, v144
	v_readfirstlane_b32 s101, v145
	s_nop 3
	s_add_u32 m0, s100, 0x8000
	s_nop 0
	global_load_lds_dwordx4 v[240:241], off
	v_lshl_add_u64 v[240:241], v[240:241], 0, s[34:35]
	s_add_u32 m0, s100, 0xa000
	s_nop 0
	global_load_lds_dwordx4 v[242:243], off
	v_lshl_add_u64 v[242:243], v[242:243], 0, s[34:35]
	s_add_u32 m0, s100, 0xc000
	s_nop 0
	global_load_lds_dwordx4 v[244:245], off
	v_lshl_add_u64 v[244:245], v[244:245], 0, s[34:35]
	s_add_u32 m0, s100, 0xe000
	s_nop 0
	global_load_lds_dwordx4 v[246:247], off
	v_lshl_add_u64 v[246:247], v[246:247], 0, s[34:35]
	s_add_u32 m0, s101, 0x8000
	s_nop 0
	global_load_lds_dwordx4 v[138:139], off
	v_lshl_add_u64 v[138:139], v[138:139], 0, s[34:35]
	s_add_u32 m0, s101, 0xa000
	s_nop 0
	global_load_lds_dwordx4 v[140:141], off
	v_lshl_add_u64 v[140:141], v[140:141], 0, s[34:35]
	s_add_u32 m0, s101, 0xc000
	s_nop 0
	global_load_lds_dwordx4 v[250:251], off
	v_lshl_add_u64 v[250:251], v[250:251], 0, s[34:35]
	s_add_u32 m0, s101, 0xe000
	s_nop 0
	global_load_lds_dwordx4 v[252:253], off
	v_lshl_add_u64 v[252:253], v[252:253], 0, s[34:35]
	s_add_u32 m0, s100, 0x20000
	s_nop 0
	global_load_lds_dwordx4 v[240:241], off
	v_lshl_add_u64 v[240:241], v[240:241], 0, s[34:35]
	s_add_u32 m0, s100, 0x22000
	s_nop 0
	global_load_lds_dwordx4 v[242:243], off
	v_lshl_add_u64 v[242:243], v[242:243], 0, s[34:35]
	s_add_u32 m0, s100, 0x24000
	s_nop 0
	global_load_lds_dwordx4 v[244:245], off
	v_lshl_add_u64 v[244:245], v[244:245], 0, s[34:35]
	s_add_u32 m0, s100, 0x26000
	s_nop 0
	global_load_lds_dwordx4 v[246:247], off
	v_lshl_add_u64 v[246:247], v[246:247], 0, s[34:35]
	v_bfe_u32 v0, v6, 1, 3
	v_and_b32_e32 v142, 15, v6
	v_bitop3_b32 v1, v8, v0, 3 bitop3:0x6c
	v_bitop3_b32 v0, v149, v0, 4 bitop3:0x36
	v_or_b32_e32 v2, v134, v142
	v_or_b32_e32 v3, v143, v142
	v_lshlrev_b32_e32 v171, 4, v0
	v_lshl_add_u32 v153, v2, 7, 0
	v_lshl_add_u32 v169, v3, 7, s79
	v_lshlrev_b32_e32 v170, 4, v1
	s_mov_b64 s[4:5], 0
	s_waitcnt vmcnt(12) lgkmcnt(0)
	s_barrier
	s_branch .LBB0_1136
	s_nop 0
.LBB0_1136:
	v_add_u32_e32 v172, v153, v170
	v_add_u32_e32 v173, v153, v171
	v_add_u32_e32 v174, v169, v170
	v_add_u32_e32 v175, v169, v171
	v_add_u32_e32 v254, 0x20000, v172
	v_add_u32_e32 v255, 0x20000, v173
	s_nop 1
	s_nop 0
	ds_read_b128 v[176:179], v172 offset:0
	ds_read_b128 v[180:183], v172 offset:2048
	ds_read_b128 v[184:187], v172 offset:4096
	ds_read_b128 v[188:191], v172 offset:6144
	ds_read_b128 v[208:211], v174 offset:0
	ds_read_b128 v[212:215], v174 offset:2048
	ds_read_b128 v[216:219], v174 offset:4096
	ds_read_b128 v[220:223], v174 offset:6144
	s_waitcnt lgkmcnt(0)
	s_nop 0
	v_mfma_f32_16x16x32_bf16 v[124:127], v[208:211], v[176:179], 0
	ds_read_b128 v[224:227], v174 offset:8192
	v_mfma_f32_16x16x32_bf16 v[120:123], v[212:215], v[176:179], 0
	ds_read_b128 v[228:231], v174 offset:10240
	v_mfma_f32_16x16x32_bf16 v[116:119], v[216:219], v[176:179], 0
	ds_read_b128 v[232:235], v174 offset:12288
	v_mfma_f32_16x16x32_bf16 v[112:115], v[220:223], v[176:179], 0
	ds_read_b128 v[236:239], v174 offset:14336
	v_mfma_f32_16x16x32_bf16 v[92:95], v[208:211], v[180:183], 0
	v_mfma_f32_16x16x32_bf16 v[88:91], v[212:215], v[180:183], 0
	v_mfma_f32_16x16x32_bf16 v[84:87], v[216:219], v[180:183], 0
	v_mfma_f32_16x16x32_bf16 v[80:83], v[220:223], v[180:183], 0
	v_mfma_f32_16x16x32_bf16 v[60:63], v[208:211], v[184:187], 0
	v_mfma_f32_16x16x32_bf16 v[56:59], v[212:215], v[184:187], 0
	v_mfma_f32_16x16x32_bf16 v[52:55], v[216:219], v[184:187], 0
	v_mfma_f32_16x16x32_bf16 v[48:51], v[220:223], v[184:187], 0
	v_mfma_f32_16x16x32_bf16 v[28:31], v[208:211], v[188:191], 0
	v_mfma_f32_16x16x32_bf16 v[24:27], v[212:215], v[188:191], 0
	v_mfma_f32_16x16x32_bf16 v[20:23], v[216:219], v[188:191], 0
	v_mfma_f32_16x16x32_bf16 v[16:19], v[220:223], v[188:191], 0
	s_waitcnt lgkmcnt(0)
	s_nop 0
	v_mfma_f32_16x16x32_bf16 v[108:111], v[224:227], v[176:179], 0
	ds_read_b128 v[192:195], v173 offset:0
	v_mfma_f32_16x16x32_bf16 v[104:107], v[228:231], v[176:179], 0
	ds_read_b128 v[196:199], v173 offset:2048
	v_mfma_f32_16x16x32_bf16 v[100:103], v[232:235], v[176:179], 0
	ds_read_b128 v[200:203], v173 offset:4096
	v_mfma_f32_16x16x32_bf16 v[96:99], v[236:239], v[176:179], 0
	ds_read_b128 v[204:207], v173 offset:6144
	v_mfma_f32_16x16x32_bf16 v[76:79], v[224:227], v[180:183], 0
	ds_read_b128 v[208:211], v175 offset:0
	v_mfma_f32_16x16x32_bf16 v[72:75], v[228:231], v[180:183], 0
	ds_read_b128 v[212:215], v175 offset:2048
	v_mfma_f32_16x16x32_bf16 v[68:71], v[232:235], v[180:183], 0
	ds_read_b128 v[216:219], v175 offset:4096
	v_mfma_f32_16x16x32_bf16 v[64:67], v[236:239], v[180:183], 0
	ds_read_b128 v[220:223], v175 offset:6144
	v_mfma_f32_16x16x32_bf16 v[44:47], v[224:227], v[184:187], 0
	v_mfma_f32_16x16x32_bf16 v[40:43], v[228:231], v[184:187], 0
	v_mfma_f32_16x16x32_bf16 v[36:39], v[232:235], v[184:187], 0
	v_mfma_f32_16x16x32_bf16 v[32:35], v[236:239], v[184:187], 0
	v_mfma_f32_16x16x32_bf16 v[12:15], v[224:227], v[188:191], 0
	v_mfma_f32_16x16x32_bf16 v[8:11], v[228:231], v[188:191], 0
	v_mfma_f32_16x16x32_bf16 v[4:7], v[232:235], v[188:191], 0
	v_mfma_f32_16x16x32_bf16 v[0:3], v[236:239], v[188:191], 0
	s_waitcnt lgkmcnt(0)
	s_nop 0
	v_mfma_f32_16x16x32_bf16 v[124:127], v[208:211], v[192:195], v[124:127]
	ds_read_b128 v[224:227], v175 offset:8192
	v_mfma_f32_16x16x32_bf16 v[120:123], v[212:215], v[192:195], v[120:123]
	ds_read_b128 v[228:231], v175 offset:10240
	v_mfma_f32_16x16x32_bf16 v[116:119], v[216:219], v[192:195], v[116:119]
	ds_read_b128 v[232:235], v175 offset:12288
	v_mfma_f32_16x16x32_bf16 v[112:115], v[220:223], v[192:195], v[112:115]
	ds_read_b128 v[236:239], v175 offset:14336
	v_mfma_f32_16x16x32_bf16 v[92:95], v[208:211], v[196:199], v[92:95]
	v_mfma_f32_16x16x32_bf16 v[88:91], v[212:215], v[196:199], v[88:91]
	v_mfma_f32_16x16x32_bf16 v[84:87], v[216:219], v[196:199], v[84:87]
	v_mfma_f32_16x16x32_bf16 v[80:83], v[220:223], v[196:199], v[80:83]
	v_mfma_f32_16x16x32_bf16 v[60:63], v[208:211], v[200:203], v[60:63]
	v_mfma_f32_16x16x32_bf16 v[56:59], v[212:215], v[200:203], v[56:59]
	v_mfma_f32_16x16x32_bf16 v[52:55], v[216:219], v[200:203], v[52:55]
	v_mfma_f32_16x16x32_bf16 v[48:51], v[220:223], v[200:203], v[48:51]
	v_mfma_f32_16x16x32_bf16 v[28:31], v[208:211], v[204:207], v[28:31]
	v_mfma_f32_16x16x32_bf16 v[24:27], v[212:215], v[204:207], v[24:27]
	v_mfma_f32_16x16x32_bf16 v[20:23], v[216:219], v[204:207], v[20:23]
	v_mfma_f32_16x16x32_bf16 v[16:19], v[220:223], v[204:207], v[16:19]
	s_waitcnt lgkmcnt(0)
	s_waitcnt vmcnt(4)
	s_barrier
	s_mov_b32 s44, 2
.Lgemm_p9_loop:
	v_mfma_f32_16x16x32_bf16 v[108:111], v[224:227], v[192:195], v[108:111]
	ds_read_b128 v[176:179], v172 offset:32768
	s_mov_b32 m0, s101
	s_nop 0
	v_mfma_f32_16x16x32_bf16 v[104:107], v[228:231], v[192:195], v[104:107]
	ds_read_b128 v[180:183], v172 offset:34816
	global_load_lds_dwordx4 v[138:139], off
	v_lshl_add_u64 v[138:139], v[138:139], 0, s[34:35]
	v_mfma_f32_16x16x32_bf16 v[100:103], v[232:235], v[192:195], v[100:103]
	ds_read_b128 v[184:187], v172 offset:36864
	s_add_u32 m0, s101, 0x2000
	v_mfma_f32_16x16x32_bf16 v[96:99], v[236:239], v[192:195], v[96:99]
	ds_read_b128 v[188:191], v172 offset:38912
	global_load_lds_dwordx4 v[140:141], off
	v_lshl_add_u64 v[140:141], v[140:141], 0, s[34:35]
	v_mfma_f32_16x16x32_bf16 v[76:79], v[224:227], v[196:199], v[76:79]
	ds_read_b128 v[208:211], v174 offset:32768
	s_add_u32 m0, s101, 0x4000
	v_mfma_f32_16x16x32_bf16 v[72:75], v[228:231], v[196:199], v[72:75]
	ds_read_b128 v[212:215], v174 offset:34816
	global_load_lds_dwordx4 v[250:251], off
	v_lshl_add_u64 v[250:251], v[250:251], 0, s[34:35]
	v_mfma_f32_16x16x32_bf16 v[68:71], v[232:235], v[196:199], v[68:71]
	ds_read_b128 v[216:219], v174 offset:36864
	s_add_u32 m0, s101, 0x6000
	v_mfma_f32_16x16x32_bf16 v[64:67], v[236:239], v[196:199], v[64:67]
	ds_read_b128 v[220:223], v174 offset:38912
	global_load_lds_dwordx4 v[252:253], off
	v_lshl_add_u64 v[252:253], v[252:253], 0, s[34:35]
	v_mfma_f32_16x16x32_bf16 v[44:47], v[224:227], v[200:203], v[44:47]
	v_mfma_f32_16x16x32_bf16 v[40:43], v[228:231], v[200:203], v[40:43]
	v_mfma_f32_16x16x32_bf16 v[36:39], v[232:235], v[200:203], v[36:39]
	v_mfma_f32_16x16x32_bf16 v[32:35], v[236:239], v[200:203], v[32:35]
	v_mfma_f32_16x16x32_bf16 v[12:15], v[224:227], v[204:207], v[12:15]
	v_mfma_f32_16x16x32_bf16 v[8:11], v[228:231], v[204:207], v[8:11]
	v_mfma_f32_16x16x32_bf16 v[4:7], v[232:235], v[204:207], v[4:7]
	v_mfma_f32_16x16x32_bf16 v[0:3], v[236:239], v[204:207], v[0:3]
	s_waitcnt lgkmcnt(0)
	s_nop 0
	v_mfma_f32_16x16x32_bf16 v[124:127], v[208:211], v[176:179], v[124:127]
	ds_read_b128 v[224:227], v174 offset:40960
	v_mfma_f32_16x16x32_bf16 v[120:123], v[212:215], v[176:179], v[120:123]
	ds_read_b128 v[228:231], v174 offset:43008
	v_mfma_f32_16x16x32_bf16 v[116:119], v[216:219], v[176:179], v[116:119]
	ds_read_b128 v[232:235], v174 offset:45056
	v_mfma_f32_16x16x32_bf16 v[112:115], v[220:223], v[176:179], v[112:115]
	ds_read_b128 v[236:239], v174 offset:47104
	v_mfma_f32_16x16x32_bf16 v[92:95], v[208:211], v[180:183], v[92:95]
	s_mov_b32 m0, s100
	s_nop 0
	v_mfma_f32_16x16x32_bf16 v[88:91], v[212:215], v[180:183], v[88:91]
	global_load_lds_dwordx4 v[240:241], off
	v_lshl_add_u64 v[240:241], v[240:241], 0, s[34:35]
	v_mfma_f32_16x16x32_bf16 v[84:87], v[216:219], v[180:183], v[84:87]
	s_add_u32 m0, s100, 0x2000
	v_mfma_f32_16x16x32_bf16 v[80:83], v[220:223], v[180:183], v[80:83]
	global_load_lds_dwordx4 v[242:243], off
	v_lshl_add_u64 v[242:243], v[242:243], 0, s[34:35]
	v_mfma_f32_16x16x32_bf16 v[60:63], v[208:211], v[184:187], v[60:63]
	s_add_u32 m0, s100, 0x4000
	v_mfma_f32_16x16x32_bf16 v[56:59], v[212:215], v[184:187], v[56:59]
	global_load_lds_dwordx4 v[244:245], off
	v_lshl_add_u64 v[244:245], v[244:245], 0, s[34:35]
	v_mfma_f32_16x16x32_bf16 v[52:55], v[216:219], v[184:187], v[52:55]
	s_add_u32 m0, s100, 0x6000
	v_mfma_f32_16x16x32_bf16 v[48:51], v[220:223], v[184:187], v[48:51]
	global_load_lds_dwordx4 v[246:247], off
	v_lshl_add_u64 v[246:247], v[246:247], 0, s[34:35]
	v_mfma_f32_16x16x32_bf16 v[28:31], v[208:211], v[188:191], v[28:31]
	v_mfma_f32_16x16x32_bf16 v[24:27], v[212:215], v[188:191], v[24:27]
	v_mfma_f32_16x16x32_bf16 v[20:23], v[216:219], v[188:191], v[20:23]
	v_mfma_f32_16x16x32_bf16 v[16:19], v[220:223], v[188:191], v[16:19]
	s_waitcnt lgkmcnt(0)
	s_nop 0
	v_mfma_f32_16x16x32_bf16 v[108:111], v[224:227], v[176:179], v[108:111]
	ds_read_b128 v[192:195], v173 offset:32768
	v_mfma_f32_16x16x32_bf16 v[104:107], v[228:231], v[176:179], v[104:107]
	ds_read_b128 v[196:199], v173 offset:34816
	v_mfma_f32_16x16x32_bf16 v[100:103], v[232:235], v[176:179], v[100:103]
	ds_read_b128 v[200:203], v173 offset:36864
	v_mfma_f32_16x16x32_bf16 v[96:99], v[236:239], v[176:179], v[96:99]
	ds_read_b128 v[204:207], v173 offset:38912
	v_mfma_f32_16x16x32_bf16 v[76:79], v[224:227], v[180:183], v[76:79]
	ds_read_b128 v[208:211], v175 offset:32768
	v_mfma_f32_16x16x32_bf16 v[72:75], v[228:231], v[180:183], v[72:75]
	ds_read_b128 v[212:215], v175 offset:34816
	v_mfma_f32_16x16x32_bf16 v[68:71], v[232:235], v[180:183], v[68:71]
	ds_read_b128 v[216:219], v175 offset:36864
	v_mfma_f32_16x16x32_bf16 v[64:67], v[236:239], v[180:183], v[64:67]
	ds_read_b128 v[220:223], v175 offset:38912
	v_mfma_f32_16x16x32_bf16 v[44:47], v[224:227], v[184:187], v[44:47]
	v_mfma_f32_16x16x32_bf16 v[40:43], v[228:231], v[184:187], v[40:43]
	v_mfma_f32_16x16x32_bf16 v[36:39], v[232:235], v[184:187], v[36:39]
	v_mfma_f32_16x16x32_bf16 v[32:35], v[236:239], v[184:187], v[32:35]
	v_mfma_f32_16x16x32_bf16 v[12:15], v[224:227], v[188:191], v[12:15]
	v_mfma_f32_16x16x32_bf16 v[8:11], v[228:231], v[188:191], v[8:11]
	v_mfma_f32_16x16x32_bf16 v[4:7], v[232:235], v[188:191], v[4:7]
	v_mfma_f32_16x16x32_bf16 v[0:3], v[236:239], v[188:191], v[0:3]
	s_waitcnt lgkmcnt(0)
	s_nop 0
	v_mfma_f32_16x16x32_bf16 v[124:127], v[208:211], v[192:195], v[124:127]
	ds_read_b128 v[224:227], v175 offset:40960
	v_mfma_f32_16x16x32_bf16 v[120:123], v[212:215], v[192:195], v[120:123]
	ds_read_b128 v[228:231], v175 offset:43008
	v_mfma_f32_16x16x32_bf16 v[116:119], v[216:219], v[192:195], v[116:119]
	ds_read_b128 v[232:235], v175 offset:45056
	v_mfma_f32_16x16x32_bf16 v[112:115], v[220:223], v[192:195], v[112:115]
	ds_read_b128 v[236:239], v175 offset:47104
	v_mfma_f32_16x16x32_bf16 v[92:95], v[208:211], v[196:199], v[92:95]
	v_mfma_f32_16x16x32_bf16 v[88:91], v[212:215], v[196:199], v[88:91]
	v_mfma_f32_16x16x32_bf16 v[84:87], v[216:219], v[196:199], v[84:87]
	v_mfma_f32_16x16x32_bf16 v[80:83], v[220:223], v[196:199], v[80:83]
	v_mfma_f32_16x16x32_bf16 v[60:63], v[208:211], v[200:203], v[60:63]
	v_mfma_f32_16x16x32_bf16 v[56:59], v[212:215], v[200:203], v[56:59]
	v_mfma_f32_16x16x32_bf16 v[52:55], v[216:219], v[200:203], v[52:55]
	v_mfma_f32_16x16x32_bf16 v[48:51], v[220:223], v[200:203], v[48:51]
	v_mfma_f32_16x16x32_bf16 v[28:31], v[208:211], v[204:207], v[28:31]
	v_mfma_f32_16x16x32_bf16 v[24:27], v[212:215], v[204:207], v[24:27]
	v_mfma_f32_16x16x32_bf16 v[20:23], v[216:219], v[204:207], v[20:23]
	v_mfma_f32_16x16x32_bf16 v[16:19], v[220:223], v[204:207], v[16:19]
	s_waitcnt lgkmcnt(0)
	s_waitcnt vmcnt(4)
	s_barrier
	s_nop 0
	v_mfma_f32_16x16x32_bf16 v[108:111], v[224:227], v[192:195], v[108:111]
	ds_read_b128 v[176:179], v254 offset:0
	s_add_u32 m0, s101, 0x8000
	v_mfma_f32_16x16x32_bf16 v[104:107], v[228:231], v[192:195], v[104:107]
	ds_read_b128 v[180:183], v254 offset:2048
	global_load_lds_dwordx4 v[138:139], off
	v_lshl_add_u64 v[138:139], v[138:139], 0, s[34:35]
	v_mfma_f32_16x16x32_bf16 v[100:103], v[232:235], v[192:195], v[100:103]
	ds_read_b128 v[184:187], v254 offset:4096
	s_add_u32 m0, s101, 0xa000
	v_mfma_f32_16x16x32_bf16 v[96:99], v[236:239], v[192:195], v[96:99]
	ds_read_b128 v[188:191], v254 offset:6144
	global_load_lds_dwordx4 v[140:141], off
	v_lshl_add_u64 v[140:141], v[140:141], 0, s[34:35]
	v_mfma_f32_16x16x32_bf16 v[76:79], v[224:227], v[196:199], v[76:79]
	ds_read_b128 v[208:211], v174 offset:0
	s_add_u32 m0, s101, 0xc000
	v_mfma_f32_16x16x32_bf16 v[72:75], v[228:231], v[196:199], v[72:75]
	ds_read_b128 v[212:215], v174 offset:2048
	global_load_lds_dwordx4 v[250:251], off
	v_lshl_add_u64 v[250:251], v[250:251], 0, s[34:35]
	v_mfma_f32_16x16x32_bf16 v[68:71], v[232:235], v[196:199], v[68:71]
	ds_read_b128 v[216:219], v174 offset:4096
	s_add_u32 m0, s101, 0xe000
	v_mfma_f32_16x16x32_bf16 v[64:67], v[236:239], v[196:199], v[64:67]
	ds_read_b128 v[220:223], v174 offset:6144
	global_load_lds_dwordx4 v[252:253], off
	v_lshl_add_u64 v[252:253], v[252:253], 0, s[34:35]
	v_mfma_f32_16x16x32_bf16 v[44:47], v[224:227], v[200:203], v[44:47]
	v_mfma_f32_16x16x32_bf16 v[40:43], v[228:231], v[200:203], v[40:43]
	v_mfma_f32_16x16x32_bf16 v[36:39], v[232:235], v[200:203], v[36:39]
	v_mfma_f32_16x16x32_bf16 v[32:35], v[236:239], v[200:203], v[32:35]
	v_mfma_f32_16x16x32_bf16 v[12:15], v[224:227], v[204:207], v[12:15]
	v_mfma_f32_16x16x32_bf16 v[8:11], v[228:231], v[204:207], v[8:11]
	v_mfma_f32_16x16x32_bf16 v[4:7], v[232:235], v[204:207], v[4:7]
	v_mfma_f32_16x16x32_bf16 v[0:3], v[236:239], v[204:207], v[0:3]
	s_waitcnt lgkmcnt(0)
	s_nop 0
	v_mfma_f32_16x16x32_bf16 v[124:127], v[208:211], v[176:179], v[124:127]
	ds_read_b128 v[224:227], v174 offset:8192
	v_mfma_f32_16x16x32_bf16 v[120:123], v[212:215], v[176:179], v[120:123]
	ds_read_b128 v[228:231], v174 offset:10240
	v_mfma_f32_16x16x32_bf16 v[116:119], v[216:219], v[176:179], v[116:119]
	ds_read_b128 v[232:235], v174 offset:12288
	v_mfma_f32_16x16x32_bf16 v[112:115], v[220:223], v[176:179], v[112:115]
	ds_read_b128 v[236:239], v174 offset:14336
	v_mfma_f32_16x16x32_bf16 v[92:95], v[208:211], v[180:183], v[92:95]
	s_add_u32 m0, s100, 0x8000
	v_mfma_f32_16x16x32_bf16 v[88:91], v[212:215], v[180:183], v[88:91]
	global_load_lds_dwordx4 v[240:241], off
	v_lshl_add_u64 v[240:241], v[240:241], 0, s[34:35]
	v_mfma_f32_16x16x32_bf16 v[84:87], v[216:219], v[180:183], v[84:87]
	s_add_u32 m0, s100, 0xa000
	v_mfma_f32_16x16x32_bf16 v[80:83], v[220:223], v[180:183], v[80:83]
	global_load_lds_dwordx4 v[242:243], off
	v_lshl_add_u64 v[242:243], v[242:243], 0, s[34:35]
	v_mfma_f32_16x16x32_bf16 v[60:63], v[208:211], v[184:187], v[60:63]
	s_add_u32 m0, s100, 0xc000
	v_mfma_f32_16x16x32_bf16 v[56:59], v[212:215], v[184:187], v[56:59]
	global_load_lds_dwordx4 v[244:245], off
	v_lshl_add_u64 v[244:245], v[244:245], 0, s[34:35]
	v_mfma_f32_16x16x32_bf16 v[52:55], v[216:219], v[184:187], v[52:55]
	s_add_u32 m0, s100, 0xe000
	v_mfma_f32_16x16x32_bf16 v[48:51], v[220:223], v[184:187], v[48:51]
	global_load_lds_dwordx4 v[246:247], off
	v_lshl_add_u64 v[246:247], v[246:247], 0, s[34:35]
	v_mfma_f32_16x16x32_bf16 v[28:31], v[208:211], v[188:191], v[28:31]
	v_mfma_f32_16x16x32_bf16 v[24:27], v[212:215], v[188:191], v[24:27]
	v_mfma_f32_16x16x32_bf16 v[20:23], v[216:219], v[188:191], v[20:23]
	v_mfma_f32_16x16x32_bf16 v[16:19], v[220:223], v[188:191], v[16:19]
	s_waitcnt lgkmcnt(0)
	s_nop 0
	v_mfma_f32_16x16x32_bf16 v[108:111], v[224:227], v[176:179], v[108:111]
	ds_read_b128 v[192:195], v255 offset:0
	v_mfma_f32_16x16x32_bf16 v[104:107], v[228:231], v[176:179], v[104:107]
	ds_read_b128 v[196:199], v255 offset:2048
	v_mfma_f32_16x16x32_bf16 v[100:103], v[232:235], v[176:179], v[100:103]
	ds_read_b128 v[200:203], v255 offset:4096
	v_mfma_f32_16x16x32_bf16 v[96:99], v[236:239], v[176:179], v[96:99]
	ds_read_b128 v[204:207], v255 offset:6144
	v_mfma_f32_16x16x32_bf16 v[76:79], v[224:227], v[180:183], v[76:79]
	ds_read_b128 v[208:211], v175 offset:0
	v_mfma_f32_16x16x32_bf16 v[72:75], v[228:231], v[180:183], v[72:75]
	ds_read_b128 v[212:215], v175 offset:2048
	v_mfma_f32_16x16x32_bf16 v[68:71], v[232:235], v[180:183], v[68:71]
	ds_read_b128 v[216:219], v175 offset:4096
	v_mfma_f32_16x16x32_bf16 v[64:67], v[236:239], v[180:183], v[64:67]
	ds_read_b128 v[220:223], v175 offset:6144
	v_mfma_f32_16x16x32_bf16 v[44:47], v[224:227], v[184:187], v[44:47]
	v_mfma_f32_16x16x32_bf16 v[40:43], v[228:231], v[184:187], v[40:43]
	v_mfma_f32_16x16x32_bf16 v[36:39], v[232:235], v[184:187], v[36:39]
	v_mfma_f32_16x16x32_bf16 v[32:35], v[236:239], v[184:187], v[32:35]
	v_mfma_f32_16x16x32_bf16 v[12:15], v[224:227], v[188:191], v[12:15]
	v_mfma_f32_16x16x32_bf16 v[8:11], v[228:231], v[188:191], v[8:11]
	v_mfma_f32_16x16x32_bf16 v[4:7], v[232:235], v[188:191], v[4:7]
	v_mfma_f32_16x16x32_bf16 v[0:3], v[236:239], v[188:191], v[0:3]
	s_waitcnt lgkmcnt(0)
	s_nop 0
	v_mfma_f32_16x16x32_bf16 v[124:127], v[208:211], v[192:195], v[124:127]
	ds_read_b128 v[224:227], v175 offset:8192
	v_mfma_f32_16x16x32_bf16 v[120:123], v[212:215], v[192:195], v[120:123]
	ds_read_b128 v[228:231], v175 offset:10240
	v_mfma_f32_16x16x32_bf16 v[116:119], v[216:219], v[192:195], v[116:119]
	ds_read_b128 v[232:235], v175 offset:12288
	v_mfma_f32_16x16x32_bf16 v[112:115], v[220:223], v[192:195], v[112:115]
	ds_read_b128 v[236:239], v175 offset:14336
	v_mfma_f32_16x16x32_bf16 v[92:95], v[208:211], v[196:199], v[92:95]
	v_mfma_f32_16x16x32_bf16 v[88:91], v[212:215], v[196:199], v[88:91]
	v_mfma_f32_16x16x32_bf16 v[84:87], v[216:219], v[196:199], v[84:87]
	v_mfma_f32_16x16x32_bf16 v[80:83], v[220:223], v[196:199], v[80:83]
	v_mfma_f32_16x16x32_bf16 v[60:63], v[208:211], v[200:203], v[60:63]
	v_mfma_f32_16x16x32_bf16 v[56:59], v[212:215], v[200:203], v[56:59]
	v_mfma_f32_16x16x32_bf16 v[52:55], v[216:219], v[200:203], v[52:55]
	v_mfma_f32_16x16x32_bf16 v[48:51], v[220:223], v[200:203], v[48:51]
	v_mfma_f32_16x16x32_bf16 v[28:31], v[208:211], v[204:207], v[28:31]
	v_mfma_f32_16x16x32_bf16 v[24:27], v[212:215], v[204:207], v[24:27]
	v_mfma_f32_16x16x32_bf16 v[20:23], v[216:219], v[204:207], v[20:23]
	v_mfma_f32_16x16x32_bf16 v[16:19], v[220:223], v[204:207], v[16:19]
	s_waitcnt lgkmcnt(0)
	s_waitcnt vmcnt(4)
	s_barrier
	s_nop 0
	v_mfma_f32_16x16x32_bf16 v[108:111], v[224:227], v[192:195], v[108:111]
	ds_read_b128 v[176:179], v172 offset:0
	s_mov_b32 m0, s101
	s_nop 0
	v_mfma_f32_16x16x32_bf16 v[104:107], v[228:231], v[192:195], v[104:107]
	ds_read_b128 v[180:183], v172 offset:2048
	global_load_lds_dwordx4 v[138:139], off
	v_lshl_add_u64 v[138:139], v[138:139], 0, s[34:35]
	v_mfma_f32_16x16x32_bf16 v[100:103], v[232:235], v[192:195], v[100:103]
	ds_read_b128 v[184:187], v172 offset:4096
	s_add_u32 m0, s101, 0x2000
	v_mfma_f32_16x16x32_bf16 v[96:99], v[236:239], v[192:195], v[96:99]
	ds_read_b128 v[188:191], v172 offset:6144
	global_load_lds_dwordx4 v[140:141], off
	v_lshl_add_u64 v[140:141], v[140:141], 0, s[34:35]
	v_mfma_f32_16x16x32_bf16 v[76:79], v[224:227], v[196:199], v[76:79]
	ds_read_b128 v[208:211], v174 offset:32768
	s_add_u32 m0, s101, 0x4000
	v_mfma_f32_16x16x32_bf16 v[72:75], v[228:231], v[196:199], v[72:75]
	ds_read_b128 v[212:215], v174 offset:34816
	global_load_lds_dwordx4 v[250:251], off
	v_lshl_add_u64 v[250:251], v[250:251], 0, s[34:35]
	v_mfma_f32_16x16x32_bf16 v[68:71], v[232:235], v[196:199], v[68:71]
	ds_read_b128 v[216:219], v174 offset:36864
	s_add_u32 m0, s101, 0x6000
	v_mfma_f32_16x16x32_bf16 v[64:67], v[236:239], v[196:199], v[64:67]
	ds_read_b128 v[220:223], v174 offset:38912
	global_load_lds_dwordx4 v[252:253], off
	v_lshl_add_u64 v[252:253], v[252:253], 0, s[34:35]
	v_mfma_f32_16x16x32_bf16 v[44:47], v[224:227], v[200:203], v[44:47]
	v_mfma_f32_16x16x32_bf16 v[40:43], v[228:231], v[200:203], v[40:43]
	v_mfma_f32_16x16x32_bf16 v[36:39], v[232:235], v[200:203], v[36:39]
	v_mfma_f32_16x16x32_bf16 v[32:35], v[236:239], v[200:203], v[32:35]
	v_mfma_f32_16x16x32_bf16 v[12:15], v[224:227], v[204:207], v[12:15]
	v_mfma_f32_16x16x32_bf16 v[8:11], v[228:231], v[204:207], v[8:11]
	v_mfma_f32_16x16x32_bf16 v[4:7], v[232:235], v[204:207], v[4:7]
	v_mfma_f32_16x16x32_bf16 v[0:3], v[236:239], v[204:207], v[0:3]
	s_waitcnt lgkmcnt(0)
	s_nop 0
	v_mfma_f32_16x16x32_bf16 v[124:127], v[208:211], v[176:179], v[124:127]
	ds_read_b128 v[224:227], v174 offset:40960
	v_mfma_f32_16x16x32_bf16 v[120:123], v[212:215], v[176:179], v[120:123]
	ds_read_b128 v[228:231], v174 offset:43008
	v_mfma_f32_16x16x32_bf16 v[116:119], v[216:219], v[176:179], v[116:119]
	ds_read_b128 v[232:235], v174 offset:45056
	v_mfma_f32_16x16x32_bf16 v[112:115], v[220:223], v[176:179], v[112:115]
	ds_read_b128 v[236:239], v174 offset:47104
	v_mfma_f32_16x16x32_bf16 v[92:95], v[208:211], v[180:183], v[92:95]
	s_add_u32 m0, s100, 0x20000
	v_mfma_f32_16x16x32_bf16 v[88:91], v[212:215], v[180:183], v[88:91]
	global_load_lds_dwordx4 v[240:241], off
	v_lshl_add_u64 v[240:241], v[240:241], 0, s[34:35]
	v_mfma_f32_16x16x32_bf16 v[84:87], v[216:219], v[180:183], v[84:87]
	s_add_u32 m0, s100, 0x22000
	v_mfma_f32_16x16x32_bf16 v[80:83], v[220:223], v[180:183], v[80:83]
	global_load_lds_dwordx4 v[242:243], off
	v_lshl_add_u64 v[242:243], v[242:243], 0, s[34:35]
	v_mfma_f32_16x16x32_bf16 v[60:63], v[208:211], v[184:187], v[60:63]
	s_add_u32 m0, s100, 0x24000
	v_mfma_f32_16x16x32_bf16 v[56:59], v[212:215], v[184:187], v[56:59]
	global_load_lds_dwordx4 v[244:245], off
	v_lshl_add_u64 v[244:245], v[244:245], 0, s[34:35]
	v_mfma_f32_16x16x32_bf16 v[52:55], v[216:219], v[184:187], v[52:55]
	s_add_u32 m0, s100, 0x26000
	v_mfma_f32_16x16x32_bf16 v[48:51], v[220:223], v[184:187], v[48:51]
	global_load_lds_dwordx4 v[246:247], off
	v_lshl_add_u64 v[246:247], v[246:247], 0, s[34:35]
	v_mfma_f32_16x16x32_bf16 v[28:31], v[208:211], v[188:191], v[28:31]
	v_mfma_f32_16x16x32_bf16 v[24:27], v[212:215], v[188:191], v[24:27]
	v_mfma_f32_16x16x32_bf16 v[20:23], v[216:219], v[188:191], v[20:23]
	v_mfma_f32_16x16x32_bf16 v[16:19], v[220:223], v[188:191], v[16:19]
	s_waitcnt lgkmcnt(0)
	s_nop 0
	v_mfma_f32_16x16x32_bf16 v[108:111], v[224:227], v[176:179], v[108:111]
	ds_read_b128 v[192:195], v173 offset:0
	v_mfma_f32_16x16x32_bf16 v[104:107], v[228:231], v[176:179], v[104:107]
	ds_read_b128 v[196:199], v173 offset:2048
	v_mfma_f32_16x16x32_bf16 v[100:103], v[232:235], v[176:179], v[100:103]
	ds_read_b128 v[200:203], v173 offset:4096
	v_mfma_f32_16x16x32_bf16 v[96:99], v[236:239], v[176:179], v[96:99]
	ds_read_b128 v[204:207], v173 offset:6144
	v_mfma_f32_16x16x32_bf16 v[76:79], v[224:227], v[180:183], v[76:79]
	ds_read_b128 v[208:211], v175 offset:32768
	v_mfma_f32_16x16x32_bf16 v[72:75], v[228:231], v[180:183], v[72:75]
	ds_read_b128 v[212:215], v175 offset:34816
	v_mfma_f32_16x16x32_bf16 v[68:71], v[232:235], v[180:183], v[68:71]
	ds_read_b128 v[216:219], v175 offset:36864
	v_mfma_f32_16x16x32_bf16 v[64:67], v[236:239], v[180:183], v[64:67]
	ds_read_b128 v[220:223], v175 offset:38912
	v_mfma_f32_16x16x32_bf16 v[44:47], v[224:227], v[184:187], v[44:47]
	v_mfma_f32_16x16x32_bf16 v[40:43], v[228:231], v[184:187], v[40:43]
	v_mfma_f32_16x16x32_bf16 v[36:39], v[232:235], v[184:187], v[36:39]
	v_mfma_f32_16x16x32_bf16 v[32:35], v[236:239], v[184:187], v[32:35]
	v_mfma_f32_16x16x32_bf16 v[12:15], v[224:227], v[188:191], v[12:15]
	v_mfma_f32_16x16x32_bf16 v[8:11], v[228:231], v[188:191], v[8:11]
	v_mfma_f32_16x16x32_bf16 v[4:7], v[232:235], v[188:191], v[4:7]
	v_mfma_f32_16x16x32_bf16 v[0:3], v[236:239], v[188:191], v[0:3]
	s_waitcnt lgkmcnt(0)
	s_nop 0
	v_mfma_f32_16x16x32_bf16 v[124:127], v[208:211], v[192:195], v[124:127]
	ds_read_b128 v[224:227], v175 offset:40960
	v_mfma_f32_16x16x32_bf16 v[120:123], v[212:215], v[192:195], v[120:123]
	ds_read_b128 v[228:231], v175 offset:43008
	v_mfma_f32_16x16x32_bf16 v[116:119], v[216:219], v[192:195], v[116:119]
	ds_read_b128 v[232:235], v175 offset:45056
	v_mfma_f32_16x16x32_bf16 v[112:115], v[220:223], v[192:195], v[112:115]
	ds_read_b128 v[236:239], v175 offset:47104
	v_mfma_f32_16x16x32_bf16 v[92:95], v[208:211], v[196:199], v[92:95]
	v_mfma_f32_16x16x32_bf16 v[88:91], v[212:215], v[196:199], v[88:91]
	v_mfma_f32_16x16x32_bf16 v[84:87], v[216:219], v[196:199], v[84:87]
	v_mfma_f32_16x16x32_bf16 v[80:83], v[220:223], v[196:199], v[80:83]
	v_mfma_f32_16x16x32_bf16 v[60:63], v[208:211], v[200:203], v[60:63]
	v_mfma_f32_16x16x32_bf16 v[56:59], v[212:215], v[200:203], v[56:59]
	v_mfma_f32_16x16x32_bf16 v[52:55], v[216:219], v[200:203], v[52:55]
	v_mfma_f32_16x16x32_bf16 v[48:51], v[220:223], v[200:203], v[48:51]
	v_mfma_f32_16x16x32_bf16 v[28:31], v[208:211], v[204:207], v[28:31]
	v_mfma_f32_16x16x32_bf16 v[24:27], v[212:215], v[204:207], v[24:27]
	v_mfma_f32_16x16x32_bf16 v[20:23], v[216:219], v[204:207], v[20:23]
	v_mfma_f32_16x16x32_bf16 v[16:19], v[220:223], v[204:207], v[16:19]
	s_waitcnt lgkmcnt(0)
	s_waitcnt vmcnt(4)
	s_barrier
	s_nop 0
	v_mfma_f32_16x16x32_bf16 v[108:111], v[224:227], v[192:195], v[108:111]
	ds_read_b128 v[176:179], v172 offset:32768
	s_add_u32 m0, s101, 0x8000
	v_mfma_f32_16x16x32_bf16 v[104:107], v[228:231], v[192:195], v[104:107]
	ds_read_b128 v[180:183], v172 offset:34816
	global_load_lds_dwordx4 v[138:139], off
	v_lshl_add_u64 v[138:139], v[138:139], 0, s[34:35]
	v_mfma_f32_16x16x32_bf16 v[100:103], v[232:235], v[192:195], v[100:103]
	ds_read_b128 v[184:187], v172 offset:36864
	s_add_u32 m0, s101, 0xa000
	v_mfma_f32_16x16x32_bf16 v[96:99], v[236:239], v[192:195], v[96:99]
	ds_read_b128 v[188:191], v172 offset:38912
	global_load_lds_dwordx4 v[140:141], off
	v_lshl_add_u64 v[140:141], v[140:141], 0, s[34:35]
	v_mfma_f32_16x16x32_bf16 v[76:79], v[224:227], v[196:199], v[76:79]
	ds_read_b128 v[208:211], v174 offset:0
	s_add_u32 m0, s101, 0xc000
	v_mfma_f32_16x16x32_bf16 v[72:75], v[228:231], v[196:199], v[72:75]
	ds_read_b128 v[212:215], v174 offset:2048
	global_load_lds_dwordx4 v[250:251], off
	v_lshl_add_u64 v[250:251], v[250:251], 0, s[34:35]
	v_mfma_f32_16x16x32_bf16 v[68:71], v[232:235], v[196:199], v[68:71]
	ds_read_b128 v[216:219], v174 offset:4096
	s_add_u32 m0, s101, 0xe000
	v_mfma_f32_16x16x32_bf16 v[64:67], v[236:239], v[196:199], v[64:67]
	ds_read_b128 v[220:223], v174 offset:6144
	global_load_lds_dwordx4 v[252:253], off
	v_lshl_add_u64 v[252:253], v[252:253], 0, s[34:35]
	v_mfma_f32_16x16x32_bf16 v[44:47], v[224:227], v[200:203], v[44:47]
	v_mfma_f32_16x16x32_bf16 v[40:43], v[228:231], v[200:203], v[40:43]
	v_mfma_f32_16x16x32_bf16 v[36:39], v[232:235], v[200:203], v[36:39]
	v_mfma_f32_16x16x32_bf16 v[32:35], v[236:239], v[200:203], v[32:35]
	v_mfma_f32_16x16x32_bf16 v[12:15], v[224:227], v[204:207], v[12:15]
	v_mfma_f32_16x16x32_bf16 v[8:11], v[228:231], v[204:207], v[8:11]
	v_mfma_f32_16x16x32_bf16 v[4:7], v[232:235], v[204:207], v[4:7]
	v_mfma_f32_16x16x32_bf16 v[0:3], v[236:239], v[204:207], v[0:3]
	s_waitcnt lgkmcnt(0)
	s_nop 0
	v_mfma_f32_16x16x32_bf16 v[124:127], v[208:211], v[176:179], v[124:127]
	ds_read_b128 v[224:227], v174 offset:8192
	v_mfma_f32_16x16x32_bf16 v[120:123], v[212:215], v[176:179], v[120:123]
	ds_read_b128 v[228:231], v174 offset:10240
	v_mfma_f32_16x16x32_bf16 v[116:119], v[216:219], v[176:179], v[116:119]
	ds_read_b128 v[232:235], v174 offset:12288
	v_mfma_f32_16x16x32_bf16 v[112:115], v[220:223], v[176:179], v[112:115]
	ds_read_b128 v[236:239], v174 offset:14336
	v_mfma_f32_16x16x32_bf16 v[92:95], v[208:211], v[180:183], v[92:95]
	s_mov_b32 m0, s100
	s_nop 0
	v_mfma_f32_16x16x32_bf16 v[88:91], v[212:215], v[180:183], v[88:91]
	global_load_lds_dwordx4 v[240:241], off
	v_lshl_add_u64 v[240:241], v[240:241], 0, s[34:35]
	v_mfma_f32_16x16x32_bf16 v[84:87], v[216:219], v[180:183], v[84:87]
	s_add_u32 m0, s100, 0x2000
	v_mfma_f32_16x16x32_bf16 v[80:83], v[220:223], v[180:183], v[80:83]
	global_load_lds_dwordx4 v[242:243], off
	v_lshl_add_u64 v[242:243], v[242:243], 0, s[34:35]
	v_mfma_f32_16x16x32_bf16 v[60:63], v[208:211], v[184:187], v[60:63]
	s_add_u32 m0, s100, 0x4000
	v_mfma_f32_16x16x32_bf16 v[56:59], v[212:215], v[184:187], v[56:59]
	global_load_lds_dwordx4 v[244:245], off
	v_lshl_add_u64 v[244:245], v[244:245], 0, s[34:35]
	v_mfma_f32_16x16x32_bf16 v[52:55], v[216:219], v[184:187], v[52:55]
	s_add_u32 m0, s100, 0x6000
	v_mfma_f32_16x16x32_bf16 v[48:51], v[220:223], v[184:187], v[48:51]
	global_load_lds_dwordx4 v[246:247], off
	v_lshl_add_u64 v[246:247], v[246:247], 0, s[34:35]
	v_mfma_f32_16x16x32_bf16 v[28:31], v[208:211], v[188:191], v[28:31]
	v_mfma_f32_16x16x32_bf16 v[24:27], v[212:215], v[188:191], v[24:27]
	v_mfma_f32_16x16x32_bf16 v[20:23], v[216:219], v[188:191], v[20:23]
	v_mfma_f32_16x16x32_bf16 v[16:19], v[220:223], v[188:191], v[16:19]
	s_waitcnt lgkmcnt(0)
	s_nop 0
	v_mfma_f32_16x16x32_bf16 v[108:111], v[224:227], v[176:179], v[108:111]
	ds_read_b128 v[192:195], v173 offset:32768
	v_mfma_f32_16x16x32_bf16 v[104:107], v[228:231], v[176:179], v[104:107]
	ds_read_b128 v[196:199], v173 offset:34816
	v_mfma_f32_16x16x32_bf16 v[100:103], v[232:235], v[176:179], v[100:103]
	ds_read_b128 v[200:203], v173 offset:36864
	v_mfma_f32_16x16x32_bf16 v[96:99], v[236:239], v[176:179], v[96:99]
	ds_read_b128 v[204:207], v173 offset:38912
	v_mfma_f32_16x16x32_bf16 v[76:79], v[224:227], v[180:183], v[76:79]
	ds_read_b128 v[208:211], v175 offset:0
	v_mfma_f32_16x16x32_bf16 v[72:75], v[228:231], v[180:183], v[72:75]
	ds_read_b128 v[212:215], v175 offset:2048
	v_mfma_f32_16x16x32_bf16 v[68:71], v[232:235], v[180:183], v[68:71]
	ds_read_b128 v[216:219], v175 offset:4096
	v_mfma_f32_16x16x32_bf16 v[64:67], v[236:239], v[180:183], v[64:67]
	ds_read_b128 v[220:223], v175 offset:6144
	v_mfma_f32_16x16x32_bf16 v[44:47], v[224:227], v[184:187], v[44:47]
	v_mfma_f32_16x16x32_bf16 v[40:43], v[228:231], v[184:187], v[40:43]
	v_mfma_f32_16x16x32_bf16 v[36:39], v[232:235], v[184:187], v[36:39]
	v_mfma_f32_16x16x32_bf16 v[32:35], v[236:239], v[184:187], v[32:35]
	v_mfma_f32_16x16x32_bf16 v[12:15], v[224:227], v[188:191], v[12:15]
	v_mfma_f32_16x16x32_bf16 v[8:11], v[228:231], v[188:191], v[8:11]
	v_mfma_f32_16x16x32_bf16 v[4:7], v[232:235], v[188:191], v[4:7]
	v_mfma_f32_16x16x32_bf16 v[0:3], v[236:239], v[188:191], v[0:3]
	s_waitcnt lgkmcnt(0)
	s_nop 0
	v_mfma_f32_16x16x32_bf16 v[124:127], v[208:211], v[192:195], v[124:127]
	ds_read_b128 v[224:227], v175 offset:8192
	v_mfma_f32_16x16x32_bf16 v[120:123], v[212:215], v[192:195], v[120:123]
	ds_read_b128 v[228:231], v175 offset:10240
	v_mfma_f32_16x16x32_bf16 v[116:119], v[216:219], v[192:195], v[116:119]
	ds_read_b128 v[232:235], v175 offset:12288
	v_mfma_f32_16x16x32_bf16 v[112:115], v[220:223], v[192:195], v[112:115]
	ds_read_b128 v[236:239], v175 offset:14336
	v_mfma_f32_16x16x32_bf16 v[92:95], v[208:211], v[196:199], v[92:95]
	v_mfma_f32_16x16x32_bf16 v[88:91], v[212:215], v[196:199], v[88:91]
	v_mfma_f32_16x16x32_bf16 v[84:87], v[216:219], v[196:199], v[84:87]
	v_mfma_f32_16x16x32_bf16 v[80:83], v[220:223], v[196:199], v[80:83]
	v_mfma_f32_16x16x32_bf16 v[60:63], v[208:211], v[200:203], v[60:63]
	v_mfma_f32_16x16x32_bf16 v[56:59], v[212:215], v[200:203], v[56:59]
	v_mfma_f32_16x16x32_bf16 v[52:55], v[216:219], v[200:203], v[52:55]
	v_mfma_f32_16x16x32_bf16 v[48:51], v[220:223], v[200:203], v[48:51]
	v_mfma_f32_16x16x32_bf16 v[28:31], v[208:211], v[204:207], v[28:31]
	v_mfma_f32_16x16x32_bf16 v[24:27], v[212:215], v[204:207], v[24:27]
	v_mfma_f32_16x16x32_bf16 v[20:23], v[216:219], v[204:207], v[20:23]
	v_mfma_f32_16x16x32_bf16 v[16:19], v[220:223], v[204:207], v[16:19]
	s_waitcnt lgkmcnt(0)
	s_waitcnt vmcnt(4)
	s_barrier
	s_nop 0
	v_mfma_f32_16x16x32_bf16 v[108:111], v[224:227], v[192:195], v[108:111]
	ds_read_b128 v[176:179], v254 offset:0
	s_mov_b32 m0, s101
	s_nop 0
	v_mfma_f32_16x16x32_bf16 v[104:107], v[228:231], v[192:195], v[104:107]
	ds_read_b128 v[180:183], v254 offset:2048
	global_load_lds_dwordx4 v[138:139], off
	v_lshl_add_u64 v[138:139], v[138:139], 0, s[34:35]
	v_mfma_f32_16x16x32_bf16 v[100:103], v[232:235], v[192:195], v[100:103]
	ds_read_b128 v[184:187], v254 offset:4096
	s_add_u32 m0, s101, 0x2000
	v_mfma_f32_16x16x32_bf16 v[96:99], v[236:239], v[192:195], v[96:99]
	ds_read_b128 v[188:191], v254 offset:6144
	global_load_lds_dwordx4 v[140:141], off
	v_lshl_add_u64 v[140:141], v[140:141], 0, s[34:35]
	v_mfma_f32_16x16x32_bf16 v[76:79], v[224:227], v[196:199], v[76:79]
	ds_read_b128 v[208:211], v174 offset:32768
	s_add_u32 m0, s101, 0x4000
	v_mfma_f32_16x16x32_bf16 v[72:75], v[228:231], v[196:199], v[72:75]
	ds_read_b128 v[212:215], v174 offset:34816
	global_load_lds_dwordx4 v[250:251], off
	v_lshl_add_u64 v[250:251], v[250:251], 0, s[34:35]
	v_mfma_f32_16x16x32_bf16 v[68:71], v[232:235], v[196:199], v[68:71]
	ds_read_b128 v[216:219], v174 offset:36864
	s_add_u32 m0, s101, 0x6000
	v_mfma_f32_16x16x32_bf16 v[64:67], v[236:239], v[196:199], v[64:67]
	ds_read_b128 v[220:223], v174 offset:38912
	global_load_lds_dwordx4 v[252:253], off
	v_lshl_add_u64 v[252:253], v[252:253], 0, s[34:35]
	v_mfma_f32_16x16x32_bf16 v[44:47], v[224:227], v[200:203], v[44:47]
	v_mfma_f32_16x16x32_bf16 v[40:43], v[228:231], v[200:203], v[40:43]
	v_mfma_f32_16x16x32_bf16 v[36:39], v[232:235], v[200:203], v[36:39]
	v_mfma_f32_16x16x32_bf16 v[32:35], v[236:239], v[200:203], v[32:35]
	v_mfma_f32_16x16x32_bf16 v[12:15], v[224:227], v[204:207], v[12:15]
	v_mfma_f32_16x16x32_bf16 v[8:11], v[228:231], v[204:207], v[8:11]
	v_mfma_f32_16x16x32_bf16 v[4:7], v[232:235], v[204:207], v[4:7]
	v_mfma_f32_16x16x32_bf16 v[0:3], v[236:239], v[204:207], v[0:3]
	s_waitcnt lgkmcnt(0)
	s_nop 0
	v_mfma_f32_16x16x32_bf16 v[124:127], v[208:211], v[176:179], v[124:127]
	ds_read_b128 v[224:227], v174 offset:40960
	v_mfma_f32_16x16x32_bf16 v[120:123], v[212:215], v[176:179], v[120:123]
	ds_read_b128 v[228:231], v174 offset:43008
	v_mfma_f32_16x16x32_bf16 v[116:119], v[216:219], v[176:179], v[116:119]
	ds_read_b128 v[232:235], v174 offset:45056
	v_mfma_f32_16x16x32_bf16 v[112:115], v[220:223], v[176:179], v[112:115]
	ds_read_b128 v[236:239], v174 offset:47104
	v_mfma_f32_16x16x32_bf16 v[92:95], v[208:211], v[180:183], v[92:95]
	s_add_u32 m0, s100, 0x8000
	v_mfma_f32_16x16x32_bf16 v[88:91], v[212:215], v[180:183], v[88:91]
	global_load_lds_dwordx4 v[240:241], off
	v_lshl_add_u64 v[240:241], v[240:241], 0, s[34:35]
	v_mfma_f32_16x16x32_bf16 v[84:87], v[216:219], v[180:183], v[84:87]
	s_add_u32 m0, s100, 0xa000
	v_mfma_f32_16x16x32_bf16 v[80:83], v[220:223], v[180:183], v[80:83]
	global_load_lds_dwordx4 v[242:243], off
	v_lshl_add_u64 v[242:243], v[242:243], 0, s[34:35]
	v_mfma_f32_16x16x32_bf16 v[60:63], v[208:211], v[184:187], v[60:63]
	s_add_u32 m0, s100, 0xc000
	v_mfma_f32_16x16x32_bf16 v[56:59], v[212:215], v[184:187], v[56:59]
	global_load_lds_dwordx4 v[244:245], off
	v_lshl_add_u64 v[244:245], v[244:245], 0, s[34:35]
	v_mfma_f32_16x16x32_bf16 v[52:55], v[216:219], v[184:187], v[52:55]
	s_add_u32 m0, s100, 0xe000
	v_mfma_f32_16x16x32_bf16 v[48:51], v[220:223], v[184:187], v[48:51]
	global_load_lds_dwordx4 v[246:247], off
	v_lshl_add_u64 v[246:247], v[246:247], 0, s[34:35]
	v_mfma_f32_16x16x32_bf16 v[28:31], v[208:211], v[188:191], v[28:31]
	v_mfma_f32_16x16x32_bf16 v[24:27], v[212:215], v[188:191], v[24:27]
	v_mfma_f32_16x16x32_bf16 v[20:23], v[216:219], v[188:191], v[20:23]
	v_mfma_f32_16x16x32_bf16 v[16:19], v[220:223], v[188:191], v[16:19]
	s_waitcnt lgkmcnt(0)
	s_nop 0
	v_mfma_f32_16x16x32_bf16 v[108:111], v[224:227], v[176:179], v[108:111]
	ds_read_b128 v[192:195], v255 offset:0
	v_mfma_f32_16x16x32_bf16 v[104:107], v[228:231], v[176:179], v[104:107]
	ds_read_b128 v[196:199], v255 offset:2048
	v_mfma_f32_16x16x32_bf16 v[100:103], v[232:235], v[176:179], v[100:103]
	ds_read_b128 v[200:203], v255 offset:4096
	v_mfma_f32_16x16x32_bf16 v[96:99], v[236:239], v[176:179], v[96:99]
	ds_read_b128 v[204:207], v255 offset:6144
	v_mfma_f32_16x16x32_bf16 v[76:79], v[224:227], v[180:183], v[76:79]
	ds_read_b128 v[208:211], v175 offset:32768
	v_mfma_f32_16x16x32_bf16 v[72:75], v[228:231], v[180:183], v[72:75]
	ds_read_b128 v[212:215], v175 offset:34816
	v_mfma_f32_16x16x32_bf16 v[68:71], v[232:235], v[180:183], v[68:71]
	ds_read_b128 v[216:219], v175 offset:36864
	v_mfma_f32_16x16x32_bf16 v[64:67], v[236:239], v[180:183], v[64:67]
	ds_read_b128 v[220:223], v175 offset:38912
	v_mfma_f32_16x16x32_bf16 v[44:47], v[224:227], v[184:187], v[44:47]
	v_mfma_f32_16x16x32_bf16 v[40:43], v[228:231], v[184:187], v[40:43]
	v_mfma_f32_16x16x32_bf16 v[36:39], v[232:235], v[184:187], v[36:39]
	v_mfma_f32_16x16x32_bf16 v[32:35], v[236:239], v[184:187], v[32:35]
	v_mfma_f32_16x16x32_bf16 v[12:15], v[224:227], v[188:191], v[12:15]
	v_mfma_f32_16x16x32_bf16 v[8:11], v[228:231], v[188:191], v[8:11]
	v_mfma_f32_16x16x32_bf16 v[4:7], v[232:235], v[188:191], v[4:7]
	v_mfma_f32_16x16x32_bf16 v[0:3], v[236:239], v[188:191], v[0:3]
	s_waitcnt lgkmcnt(0)
	s_nop 0
	v_mfma_f32_16x16x32_bf16 v[124:127], v[208:211], v[192:195], v[124:127]
	ds_read_b128 v[224:227], v175 offset:40960
	v_mfma_f32_16x16x32_bf16 v[120:123], v[212:215], v[192:195], v[120:123]
	ds_read_b128 v[228:231], v175 offset:43008
	v_mfma_f32_16x16x32_bf16 v[116:119], v[216:219], v[192:195], v[116:119]
	ds_read_b128 v[232:235], v175 offset:45056
	v_mfma_f32_16x16x32_bf16 v[112:115], v[220:223], v[192:195], v[112:115]
	ds_read_b128 v[236:239], v175 offset:47104
	v_mfma_f32_16x16x32_bf16 v[92:95], v[208:211], v[196:199], v[92:95]
	v_mfma_f32_16x16x32_bf16 v[88:91], v[212:215], v[196:199], v[88:91]
	v_mfma_f32_16x16x32_bf16 v[84:87], v[216:219], v[196:199], v[84:87]
	v_mfma_f32_16x16x32_bf16 v[80:83], v[220:223], v[196:199], v[80:83]
	v_mfma_f32_16x16x32_bf16 v[60:63], v[208:211], v[200:203], v[60:63]
	v_mfma_f32_16x16x32_bf16 v[56:59], v[212:215], v[200:203], v[56:59]
	v_mfma_f32_16x16x32_bf16 v[52:55], v[216:219], v[200:203], v[52:55]
	v_mfma_f32_16x16x32_bf16 v[48:51], v[220:223], v[200:203], v[48:51]
	v_mfma_f32_16x16x32_bf16 v[28:31], v[208:211], v[204:207], v[28:31]
	v_mfma_f32_16x16x32_bf16 v[24:27], v[212:215], v[204:207], v[24:27]
	v_mfma_f32_16x16x32_bf16 v[20:23], v[216:219], v[204:207], v[20:23]
	v_mfma_f32_16x16x32_bf16 v[16:19], v[220:223], v[204:207], v[16:19]
	s_waitcnt lgkmcnt(0)
	s_waitcnt vmcnt(4)
	s_barrier
	s_nop 0
	v_mfma_f32_16x16x32_bf16 v[108:111], v[224:227], v[192:195], v[108:111]
	ds_read_b128 v[176:179], v172 offset:0
	s_add_u32 m0, s101, 0x8000
	v_mfma_f32_16x16x32_bf16 v[104:107], v[228:231], v[192:195], v[104:107]
	ds_read_b128 v[180:183], v172 offset:2048
	global_load_lds_dwordx4 v[138:139], off
	v_lshl_add_u64 v[138:139], v[138:139], 0, s[34:35]
	v_mfma_f32_16x16x32_bf16 v[100:103], v[232:235], v[192:195], v[100:103]
	ds_read_b128 v[184:187], v172 offset:4096
	s_add_u32 m0, s101, 0xa000
	v_mfma_f32_16x16x32_bf16 v[96:99], v[236:239], v[192:195], v[96:99]
	ds_read_b128 v[188:191], v172 offset:6144
	global_load_lds_dwordx4 v[140:141], off
	v_lshl_add_u64 v[140:141], v[140:141], 0, s[34:35]
	v_mfma_f32_16x16x32_bf16 v[76:79], v[224:227], v[196:199], v[76:79]
	ds_read_b128 v[208:211], v174 offset:0
	s_add_u32 m0, s101, 0xc000
	v_mfma_f32_16x16x32_bf16 v[72:75], v[228:231], v[196:199], v[72:75]
	ds_read_b128 v[212:215], v174 offset:2048
	global_load_lds_dwordx4 v[250:251], off
	v_lshl_add_u64 v[250:251], v[250:251], 0, s[34:35]
	v_mfma_f32_16x16x32_bf16 v[68:71], v[232:235], v[196:199], v[68:71]
	ds_read_b128 v[216:219], v174 offset:4096
	s_add_u32 m0, s101, 0xe000
	v_mfma_f32_16x16x32_bf16 v[64:67], v[236:239], v[196:199], v[64:67]
	ds_read_b128 v[220:223], v174 offset:6144
	global_load_lds_dwordx4 v[252:253], off
	v_lshl_add_u64 v[252:253], v[252:253], 0, s[34:35]
	v_mfma_f32_16x16x32_bf16 v[44:47], v[224:227], v[200:203], v[44:47]
	v_mfma_f32_16x16x32_bf16 v[40:43], v[228:231], v[200:203], v[40:43]
	v_mfma_f32_16x16x32_bf16 v[36:39], v[232:235], v[200:203], v[36:39]
	v_mfma_f32_16x16x32_bf16 v[32:35], v[236:239], v[200:203], v[32:35]
	v_mfma_f32_16x16x32_bf16 v[12:15], v[224:227], v[204:207], v[12:15]
	v_mfma_f32_16x16x32_bf16 v[8:11], v[228:231], v[204:207], v[8:11]
	v_mfma_f32_16x16x32_bf16 v[4:7], v[232:235], v[204:207], v[4:7]
	v_mfma_f32_16x16x32_bf16 v[0:3], v[236:239], v[204:207], v[0:3]
	s_waitcnt lgkmcnt(0)
	s_nop 0
	v_mfma_f32_16x16x32_bf16 v[124:127], v[208:211], v[176:179], v[124:127]
	ds_read_b128 v[224:227], v174 offset:8192
	v_mfma_f32_16x16x32_bf16 v[120:123], v[212:215], v[176:179], v[120:123]
	ds_read_b128 v[228:231], v174 offset:10240
	v_mfma_f32_16x16x32_bf16 v[116:119], v[216:219], v[176:179], v[116:119]
	ds_read_b128 v[232:235], v174 offset:12288
	v_mfma_f32_16x16x32_bf16 v[112:115], v[220:223], v[176:179], v[112:115]
	ds_read_b128 v[236:239], v174 offset:14336
	v_mfma_f32_16x16x32_bf16 v[92:95], v[208:211], v[180:183], v[92:95]
	s_add_u32 m0, s100, 0x20000
	v_mfma_f32_16x16x32_bf16 v[88:91], v[212:215], v[180:183], v[88:91]
	global_load_lds_dwordx4 v[240:241], off
	v_lshl_add_u64 v[240:241], v[240:241], 0, s[34:35]
	v_mfma_f32_16x16x32_bf16 v[84:87], v[216:219], v[180:183], v[84:87]
	s_add_u32 m0, s100, 0x22000
	v_mfma_f32_16x16x32_bf16 v[80:83], v[220:223], v[180:183], v[80:83]
	global_load_lds_dwordx4 v[242:243], off
	v_lshl_add_u64 v[242:243], v[242:243], 0, s[34:35]
	v_mfma_f32_16x16x32_bf16 v[60:63], v[208:211], v[184:187], v[60:63]
	s_add_u32 m0, s100, 0x24000
	v_mfma_f32_16x16x32_bf16 v[56:59], v[212:215], v[184:187], v[56:59]
	global_load_lds_dwordx4 v[244:245], off
	v_lshl_add_u64 v[244:245], v[244:245], 0, s[34:35]
	v_mfma_f32_16x16x32_bf16 v[52:55], v[216:219], v[184:187], v[52:55]
	s_add_u32 m0, s100, 0x26000
	v_mfma_f32_16x16x32_bf16 v[48:51], v[220:223], v[184:187], v[48:51]
	global_load_lds_dwordx4 v[246:247], off
	v_lshl_add_u64 v[246:247], v[246:247], 0, s[34:35]
	v_mfma_f32_16x16x32_bf16 v[28:31], v[208:211], v[188:191], v[28:31]
	v_mfma_f32_16x16x32_bf16 v[24:27], v[212:215], v[188:191], v[24:27]
	v_mfma_f32_16x16x32_bf16 v[20:23], v[216:219], v[188:191], v[20:23]
	v_mfma_f32_16x16x32_bf16 v[16:19], v[220:223], v[188:191], v[16:19]
	s_waitcnt lgkmcnt(0)
	s_nop 0
	v_mfma_f32_16x16x32_bf16 v[108:111], v[224:227], v[176:179], v[108:111]
	ds_read_b128 v[192:195], v173 offset:0
	v_mfma_f32_16x16x32_bf16 v[104:107], v[228:231], v[176:179], v[104:107]
	ds_read_b128 v[196:199], v173 offset:2048
	v_mfma_f32_16x16x32_bf16 v[100:103], v[232:235], v[176:179], v[100:103]
	ds_read_b128 v[200:203], v173 offset:4096
	v_mfma_f32_16x16x32_bf16 v[96:99], v[236:239], v[176:179], v[96:99]
	ds_read_b128 v[204:207], v173 offset:6144
	v_mfma_f32_16x16x32_bf16 v[76:79], v[224:227], v[180:183], v[76:79]
	ds_read_b128 v[208:211], v175 offset:0
	v_mfma_f32_16x16x32_bf16 v[72:75], v[228:231], v[180:183], v[72:75]
	ds_read_b128 v[212:215], v175 offset:2048
	v_mfma_f32_16x16x32_bf16 v[68:71], v[232:235], v[180:183], v[68:71]
	ds_read_b128 v[216:219], v175 offset:4096
	v_mfma_f32_16x16x32_bf16 v[64:67], v[236:239], v[180:183], v[64:67]
	ds_read_b128 v[220:223], v175 offset:6144
	v_mfma_f32_16x16x32_bf16 v[44:47], v[224:227], v[184:187], v[44:47]
	v_mfma_f32_16x16x32_bf16 v[40:43], v[228:231], v[184:187], v[40:43]
	v_mfma_f32_16x16x32_bf16 v[36:39], v[232:235], v[184:187], v[36:39]
	v_mfma_f32_16x16x32_bf16 v[32:35], v[236:239], v[184:187], v[32:35]
	v_mfma_f32_16x16x32_bf16 v[12:15], v[224:227], v[188:191], v[12:15]
	v_mfma_f32_16x16x32_bf16 v[8:11], v[228:231], v[188:191], v[8:11]
	v_mfma_f32_16x16x32_bf16 v[4:7], v[232:235], v[188:191], v[4:7]
	v_mfma_f32_16x16x32_bf16 v[0:3], v[236:239], v[188:191], v[0:3]
	s_waitcnt lgkmcnt(0)
	s_nop 0
	v_mfma_f32_16x16x32_bf16 v[124:127], v[208:211], v[192:195], v[124:127]
	ds_read_b128 v[224:227], v175 offset:8192
	v_mfma_f32_16x16x32_bf16 v[120:123], v[212:215], v[192:195], v[120:123]
	ds_read_b128 v[228:231], v175 offset:10240
	v_mfma_f32_16x16x32_bf16 v[116:119], v[216:219], v[192:195], v[116:119]
	ds_read_b128 v[232:235], v175 offset:12288
	v_mfma_f32_16x16x32_bf16 v[112:115], v[220:223], v[192:195], v[112:115]
	ds_read_b128 v[236:239], v175 offset:14336
	v_mfma_f32_16x16x32_bf16 v[92:95], v[208:211], v[196:199], v[92:95]
	v_mfma_f32_16x16x32_bf16 v[88:91], v[212:215], v[196:199], v[88:91]
	v_mfma_f32_16x16x32_bf16 v[84:87], v[216:219], v[196:199], v[84:87]
	v_mfma_f32_16x16x32_bf16 v[80:83], v[220:223], v[196:199], v[80:83]
	v_mfma_f32_16x16x32_bf16 v[60:63], v[208:211], v[200:203], v[60:63]
	v_mfma_f32_16x16x32_bf16 v[56:59], v[212:215], v[200:203], v[56:59]
	v_mfma_f32_16x16x32_bf16 v[52:55], v[216:219], v[200:203], v[52:55]
	v_mfma_f32_16x16x32_bf16 v[48:51], v[220:223], v[200:203], v[48:51]
	v_mfma_f32_16x16x32_bf16 v[28:31], v[208:211], v[204:207], v[28:31]
	v_mfma_f32_16x16x32_bf16 v[24:27], v[212:215], v[204:207], v[24:27]
	v_mfma_f32_16x16x32_bf16 v[20:23], v[216:219], v[204:207], v[20:23]
	v_mfma_f32_16x16x32_bf16 v[16:19], v[220:223], v[204:207], v[16:19]
	s_waitcnt lgkmcnt(0)
	s_waitcnt vmcnt(4)
	s_barrier
	s_add_i32 s44, s44, -1
	s_cmp_lg_u32 s44, 0
	s_cbranch_scc1 .Lgemm_p9_loop
	v_mfma_f32_16x16x32_bf16 v[108:111], v[224:227], v[192:195], v[108:111]
	ds_read_b128 v[176:179], v172 offset:32768
	s_mov_b32 m0, s101
	s_nop 0
	v_mfma_f32_16x16x32_bf16 v[104:107], v[228:231], v[192:195], v[104:107]
	ds_read_b128 v[180:183], v172 offset:34816
	global_load_lds_dwordx4 v[138:139], off
	v_lshl_add_u64 v[138:139], v[138:139], 0, s[34:35]
	v_mfma_f32_16x16x32_bf16 v[100:103], v[232:235], v[192:195], v[100:103]
	ds_read_b128 v[184:187], v172 offset:36864
	s_add_u32 m0, s101, 0x2000
	v_mfma_f32_16x16x32_bf16 v[96:99], v[236:239], v[192:195], v[96:99]
	ds_read_b128 v[188:191], v172 offset:38912
	global_load_lds_dwordx4 v[140:141], off
	v_lshl_add_u64 v[140:141], v[140:141], 0, s[34:35]
	v_mfma_f32_16x16x32_bf16 v[76:79], v[224:227], v[196:199], v[76:79]
	ds_read_b128 v[208:211], v174 offset:32768
	s_add_u32 m0, s101, 0x4000
	v_mfma_f32_16x16x32_bf16 v[72:75], v[228:231], v[196:199], v[72:75]
	ds_read_b128 v[212:215], v174 offset:34816
	global_load_lds_dwordx4 v[250:251], off
	v_lshl_add_u64 v[250:251], v[250:251], 0, s[34:35]
	v_mfma_f32_16x16x32_bf16 v[68:71], v[232:235], v[196:199], v[68:71]
	ds_read_b128 v[216:219], v174 offset:36864
	s_add_u32 m0, s101, 0x6000
	v_mfma_f32_16x16x32_bf16 v[64:67], v[236:239], v[196:199], v[64:67]
	ds_read_b128 v[220:223], v174 offset:38912
	global_load_lds_dwordx4 v[252:253], off
	v_lshl_add_u64 v[252:253], v[252:253], 0, s[34:35]
	v_mfma_f32_16x16x32_bf16 v[44:47], v[224:227], v[200:203], v[44:47]
	v_mfma_f32_16x16x32_bf16 v[40:43], v[228:231], v[200:203], v[40:43]
	v_mfma_f32_16x16x32_bf16 v[36:39], v[232:235], v[200:203], v[36:39]
	v_mfma_f32_16x16x32_bf16 v[32:35], v[236:239], v[200:203], v[32:35]
	v_mfma_f32_16x16x32_bf16 v[12:15], v[224:227], v[204:207], v[12:15]
	v_mfma_f32_16x16x32_bf16 v[8:11], v[228:231], v[204:207], v[8:11]
	v_mfma_f32_16x16x32_bf16 v[4:7], v[232:235], v[204:207], v[4:7]
	v_mfma_f32_16x16x32_bf16 v[0:3], v[236:239], v[204:207], v[0:3]
	s_waitcnt lgkmcnt(0)
	s_nop 0
	v_mfma_f32_16x16x32_bf16 v[124:127], v[208:211], v[176:179], v[124:127]
	ds_read_b128 v[224:227], v174 offset:40960
	v_mfma_f32_16x16x32_bf16 v[120:123], v[212:215], v[176:179], v[120:123]
	ds_read_b128 v[228:231], v174 offset:43008
	v_mfma_f32_16x16x32_bf16 v[116:119], v[216:219], v[176:179], v[116:119]
	ds_read_b128 v[232:235], v174 offset:45056
	v_mfma_f32_16x16x32_bf16 v[112:115], v[220:223], v[176:179], v[112:115]
	ds_read_b128 v[236:239], v174 offset:47104
	v_mfma_f32_16x16x32_bf16 v[92:95], v[208:211], v[180:183], v[92:95]
	s_mov_b32 m0, s100
	s_nop 0
	v_mfma_f32_16x16x32_bf16 v[88:91], v[212:215], v[180:183], v[88:91]
	global_load_lds_dwordx4 v[240:241], off
	v_lshl_add_u64 v[240:241], v[240:241], 0, s[34:35]
	v_mfma_f32_16x16x32_bf16 v[84:87], v[216:219], v[180:183], v[84:87]
	s_add_u32 m0, s100, 0x2000
	v_mfma_f32_16x16x32_bf16 v[80:83], v[220:223], v[180:183], v[80:83]
	global_load_lds_dwordx4 v[242:243], off
	v_lshl_add_u64 v[242:243], v[242:243], 0, s[34:35]
	v_mfma_f32_16x16x32_bf16 v[60:63], v[208:211], v[184:187], v[60:63]
	s_add_u32 m0, s100, 0x4000
	v_mfma_f32_16x16x32_bf16 v[56:59], v[212:215], v[184:187], v[56:59]
	global_load_lds_dwordx4 v[244:245], off
	v_lshl_add_u64 v[244:245], v[244:245], 0, s[34:35]
	v_mfma_f32_16x16x32_bf16 v[52:55], v[216:219], v[184:187], v[52:55]
	s_add_u32 m0, s100, 0x6000
	v_mfma_f32_16x16x32_bf16 v[48:51], v[220:223], v[184:187], v[48:51]
	global_load_lds_dwordx4 v[246:247], off
	v_lshl_add_u64 v[246:247], v[246:247], 0, s[34:35]
	v_mfma_f32_16x16x32_bf16 v[28:31], v[208:211], v[188:191], v[28:31]
	v_mfma_f32_16x16x32_bf16 v[24:27], v[212:215], v[188:191], v[24:27]
	v_mfma_f32_16x16x32_bf16 v[20:23], v[216:219], v[188:191], v[20:23]
	v_mfma_f32_16x16x32_bf16 v[16:19], v[220:223], v[188:191], v[16:19]
	s_waitcnt lgkmcnt(0)
	s_nop 0
	v_mfma_f32_16x16x32_bf16 v[108:111], v[224:227], v[176:179], v[108:111]
	ds_read_b128 v[192:195], v173 offset:32768
	v_mfma_f32_16x16x32_bf16 v[104:107], v[228:231], v[176:179], v[104:107]
	ds_read_b128 v[196:199], v173 offset:34816
	v_mfma_f32_16x16x32_bf16 v[100:103], v[232:235], v[176:179], v[100:103]
	ds_read_b128 v[200:203], v173 offset:36864
	v_mfma_f32_16x16x32_bf16 v[96:99], v[236:239], v[176:179], v[96:99]
	ds_read_b128 v[204:207], v173 offset:38912
	v_mfma_f32_16x16x32_bf16 v[76:79], v[224:227], v[180:183], v[76:79]
	ds_read_b128 v[208:211], v175 offset:32768
	v_mfma_f32_16x16x32_bf16 v[72:75], v[228:231], v[180:183], v[72:75]
	ds_read_b128 v[212:215], v175 offset:34816
	v_mfma_f32_16x16x32_bf16 v[68:71], v[232:235], v[180:183], v[68:71]
	ds_read_b128 v[216:219], v175 offset:36864
	v_mfma_f32_16x16x32_bf16 v[64:67], v[236:239], v[180:183], v[64:67]
	ds_read_b128 v[220:223], v175 offset:38912
	v_mfma_f32_16x16x32_bf16 v[44:47], v[224:227], v[184:187], v[44:47]
	v_mfma_f32_16x16x32_bf16 v[40:43], v[228:231], v[184:187], v[40:43]
	v_mfma_f32_16x16x32_bf16 v[36:39], v[232:235], v[184:187], v[36:39]
	v_mfma_f32_16x16x32_bf16 v[32:35], v[236:239], v[184:187], v[32:35]
	v_mfma_f32_16x16x32_bf16 v[12:15], v[224:227], v[188:191], v[12:15]
	v_mfma_f32_16x16x32_bf16 v[8:11], v[228:231], v[188:191], v[8:11]
	v_mfma_f32_16x16x32_bf16 v[4:7], v[232:235], v[188:191], v[4:7]
	v_mfma_f32_16x16x32_bf16 v[0:3], v[236:239], v[188:191], v[0:3]
	s_waitcnt lgkmcnt(0)
	s_nop 0
	v_mfma_f32_16x16x32_bf16 v[124:127], v[208:211], v[192:195], v[124:127]
	ds_read_b128 v[224:227], v175 offset:40960
	v_mfma_f32_16x16x32_bf16 v[120:123], v[212:215], v[192:195], v[120:123]
	ds_read_b128 v[228:231], v175 offset:43008
	v_mfma_f32_16x16x32_bf16 v[116:119], v[216:219], v[192:195], v[116:119]
	ds_read_b128 v[232:235], v175 offset:45056
	v_mfma_f32_16x16x32_bf16 v[112:115], v[220:223], v[192:195], v[112:115]
	ds_read_b128 v[236:239], v175 offset:47104
	v_mfma_f32_16x16x32_bf16 v[92:95], v[208:211], v[196:199], v[92:95]
	v_mfma_f32_16x16x32_bf16 v[88:91], v[212:215], v[196:199], v[88:91]
	v_mfma_f32_16x16x32_bf16 v[84:87], v[216:219], v[196:199], v[84:87]
	v_mfma_f32_16x16x32_bf16 v[80:83], v[220:223], v[196:199], v[80:83]
	v_mfma_f32_16x16x32_bf16 v[60:63], v[208:211], v[200:203], v[60:63]
	v_mfma_f32_16x16x32_bf16 v[56:59], v[212:215], v[200:203], v[56:59]
	v_mfma_f32_16x16x32_bf16 v[52:55], v[216:219], v[200:203], v[52:55]
	v_mfma_f32_16x16x32_bf16 v[48:51], v[220:223], v[200:203], v[48:51]
	v_mfma_f32_16x16x32_bf16 v[28:31], v[208:211], v[204:207], v[28:31]
	v_mfma_f32_16x16x32_bf16 v[24:27], v[212:215], v[204:207], v[24:27]
	v_mfma_f32_16x16x32_bf16 v[20:23], v[216:219], v[204:207], v[20:23]
	v_mfma_f32_16x16x32_bf16 v[16:19], v[220:223], v[204:207], v[16:19]
	s_waitcnt lgkmcnt(0)
	s_waitcnt vmcnt(4)
	s_barrier
	s_nop 0
	v_mfma_f32_16x16x32_bf16 v[108:111], v[224:227], v[192:195], v[108:111]
	ds_read_b128 v[176:179], v254 offset:0
	s_add_u32 m0, s101, 0x8000
	v_mfma_f32_16x16x32_bf16 v[104:107], v[228:231], v[192:195], v[104:107]
	ds_read_b128 v[180:183], v254 offset:2048
	global_load_lds_dwordx4 v[138:139], off
	v_lshl_add_u64 v[138:139], v[138:139], 0, s[34:35]
	v_mfma_f32_16x16x32_bf16 v[100:103], v[232:235], v[192:195], v[100:103]
	ds_read_b128 v[184:187], v254 offset:4096
	s_add_u32 m0, s101, 0xa000
	v_mfma_f32_16x16x32_bf16 v[96:99], v[236:239], v[192:195], v[96:99]
	ds_read_b128 v[188:191], v254 offset:6144
	global_load_lds_dwordx4 v[140:141], off
	v_lshl_add_u64 v[140:141], v[140:141], 0, s[34:35]
	v_mfma_f32_16x16x32_bf16 v[76:79], v[224:227], v[196:199], v[76:79]
	ds_read_b128 v[208:211], v174 offset:0
	s_add_u32 m0, s101, 0xc000
	v_mfma_f32_16x16x32_bf16 v[72:75], v[228:231], v[196:199], v[72:75]
	ds_read_b128 v[212:215], v174 offset:2048
	global_load_lds_dwordx4 v[250:251], off
	v_lshl_add_u64 v[250:251], v[250:251], 0, s[34:35]
	v_mfma_f32_16x16x32_bf16 v[68:71], v[232:235], v[196:199], v[68:71]
	ds_read_b128 v[216:219], v174 offset:4096
	s_add_u32 m0, s101, 0xe000
	v_mfma_f32_16x16x32_bf16 v[64:67], v[236:239], v[196:199], v[64:67]
	ds_read_b128 v[220:223], v174 offset:6144
	global_load_lds_dwordx4 v[252:253], off
	v_lshl_add_u64 v[252:253], v[252:253], 0, s[34:35]
	v_mfma_f32_16x16x32_bf16 v[44:47], v[224:227], v[200:203], v[44:47]
	v_mfma_f32_16x16x32_bf16 v[40:43], v[228:231], v[200:203], v[40:43]
	v_mfma_f32_16x16x32_bf16 v[36:39], v[232:235], v[200:203], v[36:39]
	v_mfma_f32_16x16x32_bf16 v[32:35], v[236:239], v[200:203], v[32:35]
	v_mfma_f32_16x16x32_bf16 v[12:15], v[224:227], v[204:207], v[12:15]
	v_mfma_f32_16x16x32_bf16 v[8:11], v[228:231], v[204:207], v[8:11]
	v_mfma_f32_16x16x32_bf16 v[4:7], v[232:235], v[204:207], v[4:7]
	v_mfma_f32_16x16x32_bf16 v[0:3], v[236:239], v[204:207], v[0:3]
	s_waitcnt lgkmcnt(0)
	s_nop 0
	v_mfma_f32_16x16x32_bf16 v[124:127], v[208:211], v[176:179], v[124:127]
	ds_read_b128 v[224:227], v174 offset:8192
	v_mfma_f32_16x16x32_bf16 v[120:123], v[212:215], v[176:179], v[120:123]
	ds_read_b128 v[228:231], v174 offset:10240
	v_mfma_f32_16x16x32_bf16 v[116:119], v[216:219], v[176:179], v[116:119]
	ds_read_b128 v[232:235], v174 offset:12288
	v_mfma_f32_16x16x32_bf16 v[112:115], v[220:223], v[176:179], v[112:115]
	ds_read_b128 v[236:239], v174 offset:14336
	v_mfma_f32_16x16x32_bf16 v[92:95], v[208:211], v[180:183], v[92:95]
	v_mfma_f32_16x16x32_bf16 v[88:91], v[212:215], v[180:183], v[88:91]
	v_mfma_f32_16x16x32_bf16 v[84:87], v[216:219], v[180:183], v[84:87]
	v_mfma_f32_16x16x32_bf16 v[80:83], v[220:223], v[180:183], v[80:83]
	v_mfma_f32_16x16x32_bf16 v[60:63], v[208:211], v[184:187], v[60:63]
	v_mfma_f32_16x16x32_bf16 v[56:59], v[212:215], v[184:187], v[56:59]
	v_mfma_f32_16x16x32_bf16 v[52:55], v[216:219], v[184:187], v[52:55]
	v_mfma_f32_16x16x32_bf16 v[48:51], v[220:223], v[184:187], v[48:51]
	v_mfma_f32_16x16x32_bf16 v[28:31], v[208:211], v[188:191], v[28:31]
	v_mfma_f32_16x16x32_bf16 v[24:27], v[212:215], v[188:191], v[24:27]
	v_mfma_f32_16x16x32_bf16 v[20:23], v[216:219], v[188:191], v[20:23]
	v_mfma_f32_16x16x32_bf16 v[16:19], v[220:223], v[188:191], v[16:19]
	s_waitcnt lgkmcnt(0)
	s_nop 0
	v_mfma_f32_16x16x32_bf16 v[108:111], v[224:227], v[176:179], v[108:111]
	ds_read_b128 v[192:195], v255 offset:0
	v_mfma_f32_16x16x32_bf16 v[104:107], v[228:231], v[176:179], v[104:107]
	ds_read_b128 v[196:199], v255 offset:2048
	v_mfma_f32_16x16x32_bf16 v[100:103], v[232:235], v[176:179], v[100:103]
	ds_read_b128 v[200:203], v255 offset:4096
	v_mfma_f32_16x16x32_bf16 v[96:99], v[236:239], v[176:179], v[96:99]
	ds_read_b128 v[204:207], v255 offset:6144
	v_mfma_f32_16x16x32_bf16 v[76:79], v[224:227], v[180:183], v[76:79]
	ds_read_b128 v[208:211], v175 offset:0
	v_mfma_f32_16x16x32_bf16 v[72:75], v[228:231], v[180:183], v[72:75]
	ds_read_b128 v[212:215], v175 offset:2048
	v_mfma_f32_16x16x32_bf16 v[68:71], v[232:235], v[180:183], v[68:71]
	ds_read_b128 v[216:219], v175 offset:4096
	v_mfma_f32_16x16x32_bf16 v[64:67], v[236:239], v[180:183], v[64:67]
	ds_read_b128 v[220:223], v175 offset:6144
	v_mfma_f32_16x16x32_bf16 v[44:47], v[224:227], v[184:187], v[44:47]
	v_mfma_f32_16x16x32_bf16 v[40:43], v[228:231], v[184:187], v[40:43]
	v_mfma_f32_16x16x32_bf16 v[36:39], v[232:235], v[184:187], v[36:39]
	v_mfma_f32_16x16x32_bf16 v[32:35], v[236:239], v[184:187], v[32:35]
	v_mfma_f32_16x16x32_bf16 v[12:15], v[224:227], v[188:191], v[12:15]
	v_mfma_f32_16x16x32_bf16 v[8:11], v[228:231], v[188:191], v[8:11]
	v_mfma_f32_16x16x32_bf16 v[4:7], v[232:235], v[188:191], v[4:7]
	v_mfma_f32_16x16x32_bf16 v[0:3], v[236:239], v[188:191], v[0:3]
	s_waitcnt lgkmcnt(0)
	s_nop 0
	v_mfma_f32_16x16x32_bf16 v[124:127], v[208:211], v[192:195], v[124:127]
	ds_read_b128 v[224:227], v175 offset:8192
	v_mfma_f32_16x16x32_bf16 v[120:123], v[212:215], v[192:195], v[120:123]
	ds_read_b128 v[228:231], v175 offset:10240
	v_mfma_f32_16x16x32_bf16 v[116:119], v[216:219], v[192:195], v[116:119]
	ds_read_b128 v[232:235], v175 offset:12288
	v_mfma_f32_16x16x32_bf16 v[112:115], v[220:223], v[192:195], v[112:115]
	ds_read_b128 v[236:239], v175 offset:14336
	v_mfma_f32_16x16x32_bf16 v[92:95], v[208:211], v[196:199], v[92:95]
	v_mfma_f32_16x16x32_bf16 v[88:91], v[212:215], v[196:199], v[88:91]
	v_mfma_f32_16x16x32_bf16 v[84:87], v[216:219], v[196:199], v[84:87]
	v_mfma_f32_16x16x32_bf16 v[80:83], v[220:223], v[196:199], v[80:83]
	v_mfma_f32_16x16x32_bf16 v[60:63], v[208:211], v[200:203], v[60:63]
	v_mfma_f32_16x16x32_bf16 v[56:59], v[212:215], v[200:203], v[56:59]
	v_mfma_f32_16x16x32_bf16 v[52:55], v[216:219], v[200:203], v[52:55]
	v_mfma_f32_16x16x32_bf16 v[48:51], v[220:223], v[200:203], v[48:51]
	v_mfma_f32_16x16x32_bf16 v[28:31], v[208:211], v[204:207], v[28:31]
	v_mfma_f32_16x16x32_bf16 v[24:27], v[212:215], v[204:207], v[24:27]
	v_mfma_f32_16x16x32_bf16 v[20:23], v[216:219], v[204:207], v[20:23]
	v_mfma_f32_16x16x32_bf16 v[16:19], v[220:223], v[204:207], v[16:19]
	s_waitcnt lgkmcnt(0)
	s_waitcnt vmcnt(0)
	s_barrier
	s_nop 0
	v_mfma_f32_16x16x32_bf16 v[108:111], v[224:227], v[192:195], v[108:111]
	ds_read_b128 v[176:179], v172 offset:0
	v_mfma_f32_16x16x32_bf16 v[104:107], v[228:231], v[192:195], v[104:107]
	ds_read_b128 v[180:183], v172 offset:2048
	v_mfma_f32_16x16x32_bf16 v[100:103], v[232:235], v[192:195], v[100:103]
	ds_read_b128 v[184:187], v172 offset:4096
	v_mfma_f32_16x16x32_bf16 v[96:99], v[236:239], v[192:195], v[96:99]
	ds_read_b128 v[188:191], v172 offset:6144
	v_mfma_f32_16x16x32_bf16 v[76:79], v[224:227], v[196:199], v[76:79]
	ds_read_b128 v[208:211], v174 offset:32768
	v_mfma_f32_16x16x32_bf16 v[72:75], v[228:231], v[196:199], v[72:75]
	ds_read_b128 v[212:215], v174 offset:34816
	v_mfma_f32_16x16x32_bf16 v[68:71], v[232:235], v[196:199], v[68:71]
	ds_read_b128 v[216:219], v174 offset:36864
	v_mfma_f32_16x16x32_bf16 v[64:67], v[236:239], v[196:199], v[64:67]
	ds_read_b128 v[220:223], v174 offset:38912
	v_mfma_f32_16x16x32_bf16 v[44:47], v[224:227], v[200:203], v[44:47]
	v_mfma_f32_16x16x32_bf16 v[40:43], v[228:231], v[200:203], v[40:43]
	v_mfma_f32_16x16x32_bf16 v[36:39], v[232:235], v[200:203], v[36:39]
	v_mfma_f32_16x16x32_bf16 v[32:35], v[236:239], v[200:203], v[32:35]
	v_mfma_f32_16x16x32_bf16 v[12:15], v[224:227], v[204:207], v[12:15]
	v_mfma_f32_16x16x32_bf16 v[8:11], v[228:231], v[204:207], v[8:11]
	v_mfma_f32_16x16x32_bf16 v[4:7], v[232:235], v[204:207], v[4:7]
	v_mfma_f32_16x16x32_bf16 v[0:3], v[236:239], v[204:207], v[0:3]
	s_waitcnt lgkmcnt(0)
	s_nop 0
	v_mfma_f32_16x16x32_bf16 v[124:127], v[208:211], v[176:179], v[124:127]
	ds_read_b128 v[224:227], v174 offset:40960
	v_mfma_f32_16x16x32_bf16 v[120:123], v[212:215], v[176:179], v[120:123]
	ds_read_b128 v[228:231], v174 offset:43008
	v_mfma_f32_16x16x32_bf16 v[116:119], v[216:219], v[176:179], v[116:119]
	ds_read_b128 v[232:235], v174 offset:45056
	v_mfma_f32_16x16x32_bf16 v[112:115], v[220:223], v[176:179], v[112:115]
	ds_read_b128 v[236:239], v174 offset:47104
	v_mfma_f32_16x16x32_bf16 v[92:95], v[208:211], v[180:183], v[92:95]
	v_mfma_f32_16x16x32_bf16 v[88:91], v[212:215], v[180:183], v[88:91]
	v_mfma_f32_16x16x32_bf16 v[84:87], v[216:219], v[180:183], v[84:87]
	v_mfma_f32_16x16x32_bf16 v[80:83], v[220:223], v[180:183], v[80:83]
	v_mfma_f32_16x16x32_bf16 v[60:63], v[208:211], v[184:187], v[60:63]
	v_mfma_f32_16x16x32_bf16 v[56:59], v[212:215], v[184:187], v[56:59]
	v_mfma_f32_16x16x32_bf16 v[52:55], v[216:219], v[184:187], v[52:55]
	v_mfma_f32_16x16x32_bf16 v[48:51], v[220:223], v[184:187], v[48:51]
	v_mfma_f32_16x16x32_bf16 v[28:31], v[208:211], v[188:191], v[28:31]
	v_mfma_f32_16x16x32_bf16 v[24:27], v[212:215], v[188:191], v[24:27]
	v_mfma_f32_16x16x32_bf16 v[20:23], v[216:219], v[188:191], v[20:23]
	v_mfma_f32_16x16x32_bf16 v[16:19], v[220:223], v[188:191], v[16:19]
	s_waitcnt lgkmcnt(0)
	s_nop 0
	v_mfma_f32_16x16x32_bf16 v[108:111], v[224:227], v[176:179], v[108:111]
	ds_read_b128 v[192:195], v173 offset:0
	v_mfma_f32_16x16x32_bf16 v[104:107], v[228:231], v[176:179], v[104:107]
	ds_read_b128 v[196:199], v173 offset:2048
	v_mfma_f32_16x16x32_bf16 v[100:103], v[232:235], v[176:179], v[100:103]
	ds_read_b128 v[200:203], v173 offset:4096
	v_mfma_f32_16x16x32_bf16 v[96:99], v[236:239], v[176:179], v[96:99]
	ds_read_b128 v[204:207], v173 offset:6144
	v_mfma_f32_16x16x32_bf16 v[76:79], v[224:227], v[180:183], v[76:79]
	ds_read_b128 v[208:211], v175 offset:32768
	v_mfma_f32_16x16x32_bf16 v[72:75], v[228:231], v[180:183], v[72:75]
	ds_read_b128 v[212:215], v175 offset:34816
	v_mfma_f32_16x16x32_bf16 v[68:71], v[232:235], v[180:183], v[68:71]
	ds_read_b128 v[216:219], v175 offset:36864
	v_mfma_f32_16x16x32_bf16 v[64:67], v[236:239], v[180:183], v[64:67]
	ds_read_b128 v[220:223], v175 offset:38912
	v_mfma_f32_16x16x32_bf16 v[44:47], v[224:227], v[184:187], v[44:47]
	v_mfma_f32_16x16x32_bf16 v[40:43], v[228:231], v[184:187], v[40:43]
	v_mfma_f32_16x16x32_bf16 v[36:39], v[232:235], v[184:187], v[36:39]
	v_mfma_f32_16x16x32_bf16 v[32:35], v[236:239], v[184:187], v[32:35]
	v_mfma_f32_16x16x32_bf16 v[12:15], v[224:227], v[188:191], v[12:15]
	v_mfma_f32_16x16x32_bf16 v[8:11], v[228:231], v[188:191], v[8:11]
	v_mfma_f32_16x16x32_bf16 v[4:7], v[232:235], v[188:191], v[4:7]
	v_mfma_f32_16x16x32_bf16 v[0:3], v[236:239], v[188:191], v[0:3]
	s_waitcnt lgkmcnt(0)
	s_nop 0
	v_mfma_f32_16x16x32_bf16 v[124:127], v[208:211], v[192:195], v[124:127]
	ds_read_b128 v[224:227], v175 offset:40960
	v_mfma_f32_16x16x32_bf16 v[120:123], v[212:215], v[192:195], v[120:123]
	ds_read_b128 v[228:231], v175 offset:43008
	v_mfma_f32_16x16x32_bf16 v[116:119], v[216:219], v[192:195], v[116:119]
	ds_read_b128 v[232:235], v175 offset:45056
	v_mfma_f32_16x16x32_bf16 v[112:115], v[220:223], v[192:195], v[112:115]
	ds_read_b128 v[236:239], v175 offset:47104
	v_mfma_f32_16x16x32_bf16 v[92:95], v[208:211], v[196:199], v[92:95]
	v_mfma_f32_16x16x32_bf16 v[88:91], v[212:215], v[196:199], v[88:91]
	v_mfma_f32_16x16x32_bf16 v[84:87], v[216:219], v[196:199], v[84:87]
	v_mfma_f32_16x16x32_bf16 v[80:83], v[220:223], v[196:199], v[80:83]
	v_mfma_f32_16x16x32_bf16 v[60:63], v[208:211], v[200:203], v[60:63]
	v_mfma_f32_16x16x32_bf16 v[56:59], v[212:215], v[200:203], v[56:59]
	v_mfma_f32_16x16x32_bf16 v[52:55], v[216:219], v[200:203], v[52:55]
	v_mfma_f32_16x16x32_bf16 v[48:51], v[220:223], v[200:203], v[48:51]
	v_mfma_f32_16x16x32_bf16 v[28:31], v[208:211], v[204:207], v[28:31]
	v_mfma_f32_16x16x32_bf16 v[24:27], v[212:215], v[204:207], v[24:27]
	v_mfma_f32_16x16x32_bf16 v[20:23], v[216:219], v[204:207], v[20:23]
	v_mfma_f32_16x16x32_bf16 v[16:19], v[220:223], v[204:207], v[16:19]
	s_waitcnt lgkmcnt(0)
	s_barrier
	v_mfma_f32_16x16x32_bf16 v[108:111], v[224:227], v[192:195], v[108:111]
	v_mfma_f32_16x16x32_bf16 v[104:107], v[228:231], v[192:195], v[104:107]
	v_mfma_f32_16x16x32_bf16 v[100:103], v[232:235], v[192:195], v[100:103]
	v_mfma_f32_16x16x32_bf16 v[96:99], v[236:239], v[192:195], v[96:99]
	v_mfma_f32_16x16x32_bf16 v[76:79], v[224:227], v[196:199], v[76:79]
	v_mfma_f32_16x16x32_bf16 v[72:75], v[228:231], v[196:199], v[72:75]
	v_mfma_f32_16x16x32_bf16 v[68:71], v[232:235], v[196:199], v[68:71]
	v_mfma_f32_16x16x32_bf16 v[64:67], v[236:239], v[196:199], v[64:67]
	v_mfma_f32_16x16x32_bf16 v[44:47], v[224:227], v[200:203], v[44:47]
	v_mfma_f32_16x16x32_bf16 v[40:43], v[228:231], v[200:203], v[40:43]
	v_mfma_f32_16x16x32_bf16 v[36:39], v[232:235], v[200:203], v[36:39]
	v_mfma_f32_16x16x32_bf16 v[32:35], v[236:239], v[200:203], v[32:35]
	v_mfma_f32_16x16x32_bf16 v[12:15], v[224:227], v[204:207], v[12:15]
	v_mfma_f32_16x16x32_bf16 v[8:11], v[228:231], v[204:207], v[8:11]
	v_mfma_f32_16x16x32_bf16 v[4:7], v[232:235], v[204:207], v[4:7]
	v_mfma_f32_16x16x32_bf16 v[0:3], v[236:239], v[204:207], v[0:3]
	s_nop 7
	s_nop 3
	s_branch .LBB0_1124

.LBB0_1157:
	v_add_u32_e32 v172, v153, v170
	v_add_u32_e32 v173, v153, v171
	v_add_u32_e32 v174, v169, v170
	v_add_u32_e32 v175, v169, v171
	v_add_u32_e32 v254, 0x20000, v172
	v_add_u32_e32 v255, 0x20000, v173
	s_nop 1
	s_nop 0
	ds_read_b128 v[176:179], v172 offset:0
	ds_read_b128 v[180:183], v172 offset:2048
	ds_read_b128 v[184:187], v172 offset:4096
	ds_read_b128 v[188:191], v172 offset:6144
	ds_read_b128 v[208:211], v174 offset:0
	ds_read_b128 v[212:215], v174 offset:2048
	ds_read_b128 v[216:219], v174 offset:4096
	ds_read_b128 v[220:223], v174 offset:6144
	s_waitcnt lgkmcnt(0)
	s_nop 0
	v_mfma_f32_16x16x32_bf16 v[124:127], v[208:211], v[176:179], 0
	ds_read_b128 v[224:227], v174 offset:8192
	v_mfma_f32_16x16x32_bf16 v[120:123], v[212:215], v[176:179], 0
	ds_read_b128 v[228:231], v174 offset:10240
	v_mfma_f32_16x16x32_bf16 v[116:119], v[216:219], v[176:179], 0
	ds_read_b128 v[232:235], v174 offset:12288
	v_mfma_f32_16x16x32_bf16 v[112:115], v[220:223], v[176:179], 0
	ds_read_b128 v[236:239], v174 offset:14336
	v_mfma_f32_16x16x32_bf16 v[92:95], v[208:211], v[180:183], 0
	v_mfma_f32_16x16x32_bf16 v[88:91], v[212:215], v[180:183], 0
	v_mfma_f32_16x16x32_bf16 v[84:87], v[216:219], v[180:183], 0
	v_mfma_f32_16x16x32_bf16 v[80:83], v[220:223], v[180:183], 0
	v_mfma_f32_16x16x32_bf16 v[60:63], v[208:211], v[184:187], 0
	v_mfma_f32_16x16x32_bf16 v[56:59], v[212:215], v[184:187], 0
	v_mfma_f32_16x16x32_bf16 v[52:55], v[216:219], v[184:187], 0
	v_mfma_f32_16x16x32_bf16 v[48:51], v[220:223], v[184:187], 0
	v_mfma_f32_16x16x32_bf16 v[28:31], v[208:211], v[188:191], 0
	v_mfma_f32_16x16x32_bf16 v[24:27], v[212:215], v[188:191], 0
	v_mfma_f32_16x16x32_bf16 v[20:23], v[216:219], v[188:191], 0
	v_mfma_f32_16x16x32_bf16 v[16:19], v[220:223], v[188:191], 0
	s_waitcnt lgkmcnt(0)
	s_nop 0
	v_mfma_f32_16x16x32_bf16 v[108:111], v[224:227], v[176:179], 0
	ds_read_b128 v[192:195], v173 offset:0
	v_mfma_f32_16x16x32_bf16 v[104:107], v[228:231], v[176:179], 0
	ds_read_b128 v[196:199], v173 offset:2048
	v_mfma_f32_16x16x32_bf16 v[100:103], v[232:235], v[176:179], 0
	ds_read_b128 v[200:203], v173 offset:4096
	v_mfma_f32_16x16x32_bf16 v[96:99], v[236:239], v[176:179], 0
	ds_read_b128 v[204:207], v173 offset:6144
	v_mfma_f32_16x16x32_bf16 v[76:79], v[224:227], v[180:183], 0
	ds_read_b128 v[208:211], v175 offset:0
	v_mfma_f32_16x16x32_bf16 v[72:75], v[228:231], v[180:183], 0
	ds_read_b128 v[212:215], v175 offset:2048
	v_mfma_f32_16x16x32_bf16 v[68:71], v[232:235], v[180:183], 0
	ds_read_b128 v[216:219], v175 offset:4096
	v_mfma_f32_16x16x32_bf16 v[64:67], v[236:239], v[180:183], 0
	ds_read_b128 v[220:223], v175 offset:6144
	v_mfma_f32_16x16x32_bf16 v[44:47], v[224:227], v[184:187], 0
	v_mfma_f32_16x16x32_bf16 v[40:43], v[228:231], v[184:187], 0
	v_mfma_f32_16x16x32_bf16 v[36:39], v[232:235], v[184:187], 0
	v_mfma_f32_16x16x32_bf16 v[32:35], v[236:239], v[184:187], 0
	v_mfma_f32_16x16x32_bf16 v[12:15], v[224:227], v[188:191], 0
	v_mfma_f32_16x16x32_bf16 v[8:11], v[228:231], v[188:191], 0
	v_mfma_f32_16x16x32_bf16 v[4:7], v[232:235], v[188:191], 0
	v_mfma_f32_16x16x32_bf16 v[0:3], v[236:239], v[188:191], 0
	s_waitcnt lgkmcnt(0)
	s_nop 0
	v_mfma_f32_16x16x32_bf16 v[124:127], v[208:211], v[192:195], v[124:127]
	ds_read_b128 v[224:227], v175 offset:8192
	v_mfma_f32_16x16x32_bf16 v[120:123], v[212:215], v[192:195], v[120:123]
	ds_read_b128 v[228:231], v175 offset:10240
	v_mfma_f32_16x16x32_bf16 v[116:119], v[216:219], v[192:195], v[116:119]
	ds_read_b128 v[232:235], v175 offset:12288
	v_mfma_f32_16x16x32_bf16 v[112:115], v[220:223], v[192:195], v[112:115]
	ds_read_b128 v[236:239], v175 offset:14336
	v_mfma_f32_16x16x32_bf16 v[92:95], v[208:211], v[196:199], v[92:95]
	v_mfma_f32_16x16x32_bf16 v[88:91], v[212:215], v[196:199], v[88:91]
	v_mfma_f32_16x16x32_bf16 v[84:87], v[216:219], v[196:199], v[84:87]
	v_mfma_f32_16x16x32_bf16 v[80:83], v[220:223], v[196:199], v[80:83]
	v_mfma_f32_16x16x32_bf16 v[60:63], v[208:211], v[200:203], v[60:63]
	v_mfma_f32_16x16x32_bf16 v[56:59], v[212:215], v[200:203], v[56:59]
	v_mfma_f32_16x16x32_bf16 v[52:55], v[216:219], v[200:203], v[52:55]
	v_mfma_f32_16x16x32_bf16 v[48:51], v[220:223], v[200:203], v[48:51]
	v_mfma_f32_16x16x32_bf16 v[28:31], v[208:211], v[204:207], v[28:31]
	v_mfma_f32_16x16x32_bf16 v[24:27], v[212:215], v[204:207], v[24:27]
	v_mfma_f32_16x16x32_bf16 v[20:23], v[216:219], v[204:207], v[20:23]
	v_mfma_f32_16x16x32_bf16 v[16:19], v[220:223], v[204:207], v[16:19]
	s_waitcnt lgkmcnt(0)
	s_waitcnt vmcnt(4)
	s_barrier
	s_mov_b32 s44, 10
